# removed the s_setprio 1/0 pairs around the MFMA bursts in all 7 GEMM K loops and in the hyena Toeplitz blocks (v12 + no priority toggling)
# baseline (speedup 1.0000x reference)
; #define PG8_STAGE(bufoff, gbase, voff) do { _Pragma("unroll") for (int _i = 0; _i < 2; ++_i) \
;         __builtin_amdgcn_global_load_lds((const unsigned*)((const char*)(gbase) + (voff)[_i]), (PG8_LAS unsigned*)(lds + (bufoff) + ldsw + _i * 8192), 16, 0, 0); } while (0)
; #define PG8_LDA(dst, b, h) do { _Pragma("unroll") for (int m = 0; m < 4; ++m) _Pragma("unroll") for (int k = 0; k < 2; ++k) dst[m][k] = *(const PG8_LAS bf16x8*)(lds + PG8_SA(b, h) + aoff + m * 2048 + k * 1024); } while (0)
; #define PG8_LDB(dst, b, h) do { _Pragma("unroll") for (int n = 0; n < 2; ++n) _Pragma("unroll") for (int k = 0; k < 2; ++k) dst[n][k] = *(const PG8_LAS bf16x8*)(lds + PG8_SB(b, h) + boff + n * 2048 + k * 1024); } while (0)
; #define PG8_MMA(ai, bj, At, Bt) do { __builtin_amdgcn_s_setprio(1); _Pragma("unroll") for (int m = 0; m < 4; ++m) _Pragma("unroll") for (int n = 0; n < 2; ++n) _Pragma("unroll") for (int k = 0; k < 2; ++k) \
;         acc[ai][bj][m][n] = __builtin_amdgcn_mfma_f32_16x16x32_bf16(Bt[n][k], At[m][k], acc[ai][bj][m][n], 0, 0, 0); __builtin_amdgcn_s_setprio(0); } while (0)
; #define PG8_WAIT_V(n) asm volatile("s_waitcnt vmcnt(" #n ")" ::: "memory")
; #define PG8_WAIT_L(n) asm volatile("s_waitcnt lgkmcnt(" #n ")" ::: "memory")
; template <class Epi, class Sched, bool ALIGN_EPI = false, bool SP2 = false>
; __device__ __forceinline__ void gemm_phase(PG8_LAS unsigned char* lds, const Gemm g, const Sched& S, const Epi& E) {
;     ...
;             const bool last = (t == nt - 2);
;             const char* a1 = cA + (size_t)(t + 1) * kstep;
;             const char* a2 = last ? nA : cA + (size_t)(t + 2) * kstep; const char* b2 = last ? nB : cB + (size_t)(t + 2) * kstep;
;             const char* a3 = a2 + kstep; const char* b3 = b2 + kstep;
;             if (last && has_next) S.a_ready(nxt);
;             if constexpr (SP2) {
;             PG8_LDB(B0, 0, 0); PG8_LDB(B1, 0, 1); PG8_SCHED; PG8_LDA(At, 0, 0); PG8_STAGE(PG8_SA(1, 1), a1 + hstep, voffA);
;             PG8_WAIT_V(8); PG8_WAIT_L(0); PG8_BAR; PG8_MMA(0, 0, At, B0); PG8_MMA(0, 1, At, B1); PG8_BAR; PG8_SCHED;
;             PG8_LDA(At, 0, 1); PG8_STAGE(PG8_SB(0, 0), b2, voffB); PG8_STAGE(PG8_SB(0, 1), b2 + hstep, voffB); PG8_STAGE(PG8_SA(0, 0), a2, voffA);
;             PG8_WAIT_V(8); PG8_WAIT_L(0); PG8_BAR; PG8_MMA(1, 0, At, B0); PG8_MMA(1, 1, At, B1); PG8_BAR; PG8_SCHED;
.LBB0_208:
	s_add_i32 s59, s33, 2
	s_add_u32 s6, s30, 0x80
	s_addc_u32 s7, s31, 0
	s_add_i32 s67, 0, 0x10000
	s_cmp_eq_u32 s60, s33
	s_cselect_b32 s35, s11, s7
	s_cselect_b32 s34, s10, s6
	v_add_u32_e32 v150, s67, v158
	s_cselect_b32 s7, s29, s54
	s_cselect_b32 s6, s28, s2
	s_add_i32 s33, 0, 0x14000
	ds_read_b128 v[146:149], v150
	ds_read_b128 v[162:165], v150 offset:1024
	ds_read_b128 v[166:169], v150 offset:2048
	ds_read_b128 v[170:173], v150 offset:3072
	v_add_u32_e32 v150, s33, v158
	ds_read_b128 v[174:177], v150
	ds_read_b128 v[182:185], v150 offset:1024
	ds_read_b128 v[186:189], v150 offset:2048
	ds_read_b128 v[190:193], v150 offset:3072
	s_add_i32 m0, s47, 0xc000
	ds_read_b128 v[194:197], v160
	ds_read_b128 v[198:201], v160 offset:1024
	ds_read_b128 v[202:205], v160 offset:2048
	ds_read_b128 v[206:209], v160 offset:3072
	ds_read_b128 v[210:213], v160 offset:4096
	ds_read_b128 v[214:217], v160 offset:5120
	ds_read_b128 v[218:221], v160 offset:6144
	ds_read_b128 v[222:225], v160 offset:7168
	global_load_lds_dwordx4 v140, s[30:31]
	s_add_i32 m0, s47, 0xe000
	s_nop 0
	global_load_lds_dwordx4 v142, s[30:31]
	s_waitcnt vmcnt(8)
	s_waitcnt lgkmcnt(0)
	s_barrier
	s_waitcnt lgkmcnt(0)
	v_mfma_f32_16x16x32_bf16 v[122:125], v[146:149], v[194:197], v[122:125]
	v_mfma_f32_16x16x32_bf16 v[126:129], v[166:169], v[194:197], v[126:129]
	v_mfma_f32_16x16x32_bf16 v[110:113], v[146:149], v[202:205], v[110:113]
	v_mfma_f32_16x16x32_bf16 v[106:109], v[166:169], v[202:205], v[106:109]
	v_mfma_f32_16x16x32_bf16 v[94:97], v[146:149], v[210:213], v[94:97]
	v_mfma_f32_16x16x32_bf16 v[90:93], v[166:169], v[210:213], v[90:93]
	v_mfma_f32_16x16x32_bf16 v[78:81], v[146:149], v[218:221], v[78:81]
	v_mfma_f32_16x16x32_bf16 v[74:77], v[166:169], v[218:221], v[74:77]
	v_mfma_f32_16x16x32_bf16 v[122:125], v[162:165], v[198:201], v[122:125]
	v_mfma_f32_16x16x32_bf16 v[126:129], v[170:173], v[198:201], v[126:129]
	v_mfma_f32_16x16x32_bf16 v[110:113], v[162:165], v[206:209], v[110:113]
	v_mfma_f32_16x16x32_bf16 v[106:109], v[170:173], v[206:209], v[106:109]
	v_mfma_f32_16x16x32_bf16 v[94:97], v[162:165], v[214:217], v[94:97]
	v_mfma_f32_16x16x32_bf16 v[90:93], v[170:173], v[214:217], v[90:93]
	v_mfma_f32_16x16x32_bf16 v[78:81], v[162:165], v[222:225], v[78:81]
	v_mfma_f32_16x16x32_bf16 v[74:77], v[170:173], v[222:225], v[74:77]
	v_mfma_f32_16x16x32_bf16 v[118:121], v[174:177], v[194:197], v[118:121]
	v_mfma_f32_16x16x32_bf16 v[114:117], v[186:189], v[194:197], v[114:117]
	v_mfma_f32_16x16x32_bf16 v[102:105], v[174:177], v[202:205], v[102:105]
	v_mfma_f32_16x16x32_bf16 v[98:101], v[186:189], v[202:205], v[98:101]
	v_mfma_f32_16x16x32_bf16 v[86:89], v[174:177], v[210:213], v[86:89]
	v_mfma_f32_16x16x32_bf16 v[82:85], v[186:189], v[210:213], v[82:85]
	v_mfma_f32_16x16x32_bf16 v[70:73], v[174:177], v[218:221], v[70:73]
	v_mfma_f32_16x16x32_bf16 v[66:69], v[186:189], v[218:221], v[66:69]
	v_mfma_f32_16x16x32_bf16 v[118:121], v[182:185], v[198:201], v[118:121]
	v_mfma_f32_16x16x32_bf16 v[114:117], v[190:193], v[198:201], v[114:117]
	v_mfma_f32_16x16x32_bf16 v[102:105], v[182:185], v[206:209], v[102:105]
	v_mfma_f32_16x16x32_bf16 v[98:101], v[190:193], v[206:209], v[98:101]
	v_mfma_f32_16x16x32_bf16 v[86:89], v[182:185], v[214:217], v[86:89]
	v_mfma_f32_16x16x32_bf16 v[82:85], v[190:193], v[214:217], v[82:85]
	v_mfma_f32_16x16x32_bf16 v[70:73], v[182:185], v[222:225], v[70:73]
	v_mfma_f32_16x16x32_bf16 v[66:69], v[190:193], v[222:225], v[66:69]
	s_barrier
	s_add_i32 s67, s67, s41
	s_mov_b32 m0, s67
	ds_read_b128 v[194:197], v160 offset:16384
	ds_read_b128 v[198:201], v160 offset:17408
	ds_read_b128 v[202:205], v160 offset:18432
	ds_read_b128 v[206:209], v160 offset:19456
	ds_read_b128 v[210:213], v160 offset:20480
	ds_read_b128 v[214:217], v160 offset:21504
	ds_read_b128 v[218:221], v160 offset:22528
	ds_read_b128 v[222:225], v160 offset:23552
	global_load_lds_dwordx4 v134, s[6:7]
	s_add_i32 m0, s67, 0x2000
	s_add_u32 s100, s6, 0x80
	s_addc_u32 s101, s7, 0
	global_load_lds_dwordx4 v130, s[6:7]
	s_add_u32 s6, s6, s14
	s_addc_u32 s7, s7, s15
	s_add_i32 s33, s33, s41
	s_mov_b32 m0, s33
	s_nop 0
	global_load_lds_dwordx4 v134, s[6:7]
	s_add_i32 m0, s33, 0x2000
	s_nop 0
	global_load_lds_dwordx4 v130, s[6:7]
	s_mov_b32 m0, s47
	s_nop 0
	global_load_lds_dwordx4 v136, s[34:35]
	s_mov_b32 m0, s48
	s_nop 0
	global_load_lds_dwordx4 v132, s[34:35]
	s_waitcnt vmcnt(8)
	s_waitcnt lgkmcnt(0)
	s_barrier
	s_waitcnt lgkmcnt(0)
	v_mfma_f32_16x16x32_bf16 v[62:65], v[146:149], v[194:197], v[62:65]
	v_mfma_f32_16x16x32_bf16 v[58:61], v[166:169], v[194:197], v[58:61]
	v_mfma_f32_16x16x32_bf16 v[46:49], v[146:149], v[202:205], v[46:49]
	v_mfma_f32_16x16x32_bf16 v[42:45], v[166:169], v[202:205], v[42:45]
	v_mfma_f32_16x16x32_bf16 v[30:33], v[146:149], v[210:213], v[30:33]
	v_mfma_f32_16x16x32_bf16 v[26:29], v[166:169], v[210:213], v[26:29]
	v_mfma_f32_16x16x32_bf16 v[14:17], v[146:149], v[218:221], v[14:17]
	v_mfma_f32_16x16x32_bf16 v[10:13], v[166:169], v[218:221], v[10:13]
	v_mfma_f32_16x16x32_bf16 v[62:65], v[162:165], v[198:201], v[62:65]
	v_mfma_f32_16x16x32_bf16 v[58:61], v[170:173], v[198:201], v[58:61]
	v_mfma_f32_16x16x32_bf16 v[46:49], v[162:165], v[206:209], v[46:49]
	v_mfma_f32_16x16x32_bf16 v[42:45], v[170:173], v[206:209], v[42:45]
	v_mfma_f32_16x16x32_bf16 v[30:33], v[162:165], v[214:217], v[30:33]
	v_mfma_f32_16x16x32_bf16 v[26:29], v[170:173], v[214:217], v[26:29]
	v_mfma_f32_16x16x32_bf16 v[14:17], v[162:165], v[222:225], v[14:17]
	v_mfma_f32_16x16x32_bf16 v[10:13], v[170:173], v[222:225], v[10:13]
	v_mfma_f32_16x16x32_bf16 v[54:57], v[174:177], v[194:197], v[54:57]
	v_mfma_f32_16x16x32_bf16 v[50:53], v[186:189], v[194:197], v[50:53]
	v_mfma_f32_16x16x32_bf16 v[38:41], v[174:177], v[202:205], v[38:41]
	v_mfma_f32_16x16x32_bf16 v[34:37], v[186:189], v[202:205], v[34:37]
	v_mfma_f32_16x16x32_bf16 v[22:25], v[174:177], v[210:213], v[22:25]
	v_mfma_f32_16x16x32_bf16 v[18:21], v[186:189], v[210:213], v[18:21]
	v_mfma_f32_16x16x32_bf16 v[6:9], v[174:177], v[218:221], v[6:9]
	v_mfma_f32_16x16x32_bf16 v[2:5], v[186:189], v[218:221], v[2:5]
	v_mfma_f32_16x16x32_bf16 v[54:57], v[182:185], v[198:201], v[54:57]
	v_mfma_f32_16x16x32_bf16 v[50:53], v[190:193], v[198:201], v[50:53]
	v_mfma_f32_16x16x32_bf16 v[38:41], v[182:185], v[206:209], v[38:41]
	v_mfma_f32_16x16x32_bf16 v[34:37], v[190:193], v[206:209], v[34:37]
	v_mfma_f32_16x16x32_bf16 v[22:25], v[182:185], v[214:217], v[22:25]
	v_mfma_f32_16x16x32_bf16 v[18:21], v[190:193], v[214:217], v[18:21]
	v_mfma_f32_16x16x32_bf16 v[6:9], v[182:185], v[222:225], v[6:9]
	v_mfma_f32_16x16x32_bf16 v[2:5], v[190:193], v[222:225], v[2:5]
	s_barrier
; #define PG8_STAGE(bufoff, gbase, voff) do { _Pragma("unroll") for (int _i = 0; _i < 2; ++_i) \
;         __builtin_amdgcn_global_load_lds((const unsigned*)((const char*)(gbase) + (voff)[_i]), (PG8_LAS unsigned*)(lds + (bufoff) + ldsw + _i * 8192), 16, 0, 0); } while (0)
; #define PG8_LDA(dst, b, h) do { _Pragma("unroll") for (int m = 0; m < 4; ++m) _Pragma("unroll") for (int k = 0; k < 2; ++k) dst[m][k] = *(const PG8_LAS bf16x8*)(lds + PG8_SA(b, h) + aoff + m * 2048 + k * 1024); } while (0)
; #define PG8_LDB(dst, b, h) do { _Pragma("unroll") for (int n = 0; n < 2; ++n) _Pragma("unroll") for (int k = 0; k < 2; ++k) dst[n][k] = *(const PG8_LAS bf16x8*)(lds + PG8_SB(b, h) + boff + n * 2048 + k * 1024); } while (0)
; #define PG8_MMA(ai, bj, At, Bt) do { __builtin_amdgcn_s_setprio(1); _Pragma("unroll") for (int m = 0; m < 4; ++m) _Pragma("unroll") for (int n = 0; n < 2; ++n) _Pragma("unroll") for (int k = 0; k < 2; ++k) \
;         acc[ai][bj][m][n] = __builtin_amdgcn_mfma_f32_16x16x32_bf16(Bt[n][k], At[m][k], acc[ai][bj][m][n], 0, 0, 0); __builtin_amdgcn_s_setprio(0); } while (0)
; #define PG8_WAIT_V(n) asm volatile("s_waitcnt vmcnt(" #n ")" ::: "memory")
; #define PG8_WAIT_L(n) asm volatile("s_waitcnt lgkmcnt(" #n ")" ::: "memory")
; #define PG8_BAR __builtin_amdgcn_s_barrier()
; #define PG8_SCHED __builtin_amdgcn_sched_barrier(0)
; template <class Epi, class Sched, bool ALIGN_EPI = false, bool SP2 = false>
; __device__ __forceinline__ void gemm_phase(PG8_LAS unsigned char* lds, const Gemm g, const Sched& S, const Epi& E) {
;     ...
;             PG8_LDB(B0, 1, 0); PG8_LDB(B1, 1, 1); PG8_SCHED; PG8_LDA(At, 1, 0); PG8_STAGE(PG8_SA(0, 1), a2 + hstep, voffA);
;             PG8_WAIT_V(8); PG8_WAIT_L(0); PG8_BAR; PG8_MMA(0, 0, At, B0); PG8_MMA(0, 1, At, B1); PG8_BAR; PG8_SCHED;
;             PG8_LDA(At, 1, 1); PG8_STAGE(PG8_SB(1, 0), b3, voffB); PG8_STAGE(PG8_SB(1, 1), b3 + hstep, voffB); PG8_STAGE(PG8_SA(1, 0), a3, voffA);
;             PG8_WAIT_V(8); PG8_WAIT_L(0); PG8_BAR; PG8_MMA(1, 0, At, B0); PG8_MMA(1, 1, At, B1); PG8_BAR; PG8_SCHED;
	s_add_i32 s33, 0, 0x18000
	v_add_u32_e32 v161, s33, v158
	s_add_i32 s67, 0, 0x1c000
	ds_read_b128 v[146:149], v161
	ds_read_b128 v[162:165], v161 offset:1024
	ds_read_b128 v[166:169], v161 offset:2048
	ds_read_b128 v[170:173], v161 offset:3072
	v_add_u32_e32 v161, s67, v158
	ds_read_b128 v[174:177], v161
	ds_read_b128 v[182:185], v161 offset:1024
	ds_read_b128 v[186:189], v161 offset:2048
	ds_read_b128 v[190:193], v161 offset:3072
	s_add_u32 s6, s34, s14
	s_addc_u32 s7, s35, s15
	s_mov_b32 m0, s49
	ds_read_b128 v[194:197], v160 offset:32768
	ds_read_b128 v[198:201], v160 offset:33792
	ds_read_b128 v[202:205], v160 offset:34816
	ds_read_b128 v[206:209], v160 offset:35840
	ds_read_b128 v[210:213], v160 offset:36864
	ds_read_b128 v[214:217], v160 offset:37888
	ds_read_b128 v[218:221], v160 offset:38912
	ds_read_b128 v[222:225], v160 offset:39936
	global_load_lds_dwordx4 v136, s[6:7]
	s_mov_b32 m0, s50
	s_nop 0
	global_load_lds_dwordx4 v132, s[6:7]
	s_waitcnt vmcnt(8)
	s_waitcnt lgkmcnt(0)
	s_barrier
	s_waitcnt lgkmcnt(0)
	v_mfma_f32_16x16x32_bf16 v[122:125], v[146:149], v[194:197], v[122:125]
	v_mfma_f32_16x16x32_bf16 v[126:129], v[166:169], v[194:197], v[126:129]
	v_mfma_f32_16x16x32_bf16 v[110:113], v[146:149], v[202:205], v[110:113]
	v_mfma_f32_16x16x32_bf16 v[106:109], v[166:169], v[202:205], v[106:109]
	v_mfma_f32_16x16x32_bf16 v[94:97], v[146:149], v[210:213], v[94:97]
	v_mfma_f32_16x16x32_bf16 v[90:93], v[166:169], v[210:213], v[90:93]
	v_mfma_f32_16x16x32_bf16 v[78:81], v[146:149], v[218:221], v[78:81]
	v_mfma_f32_16x16x32_bf16 v[74:77], v[166:169], v[218:221], v[74:77]
	v_mfma_f32_16x16x32_bf16 v[122:125], v[162:165], v[198:201], v[122:125]
	v_mfma_f32_16x16x32_bf16 v[126:129], v[170:173], v[198:201], v[126:129]
	v_mfma_f32_16x16x32_bf16 v[110:113], v[162:165], v[206:209], v[110:113]
	v_mfma_f32_16x16x32_bf16 v[106:109], v[170:173], v[206:209], v[106:109]
	v_mfma_f32_16x16x32_bf16 v[94:97], v[162:165], v[214:217], v[94:97]
	v_mfma_f32_16x16x32_bf16 v[90:93], v[170:173], v[214:217], v[90:93]
	v_mfma_f32_16x16x32_bf16 v[78:81], v[162:165], v[222:225], v[78:81]
	v_mfma_f32_16x16x32_bf16 v[74:77], v[170:173], v[222:225], v[74:77]
	v_mfma_f32_16x16x32_bf16 v[118:121], v[174:177], v[194:197], v[118:121]
	v_mfma_f32_16x16x32_bf16 v[114:117], v[186:189], v[194:197], v[114:117]
	v_mfma_f32_16x16x32_bf16 v[102:105], v[174:177], v[202:205], v[102:105]
	v_mfma_f32_16x16x32_bf16 v[98:101], v[186:189], v[202:205], v[98:101]
	v_mfma_f32_16x16x32_bf16 v[86:89], v[174:177], v[210:213], v[86:89]
	v_mfma_f32_16x16x32_bf16 v[82:85], v[186:189], v[210:213], v[82:85]
	v_mfma_f32_16x16x32_bf16 v[70:73], v[174:177], v[218:221], v[70:73]
	v_mfma_f32_16x16x32_bf16 v[66:69], v[186:189], v[218:221], v[66:69]
	v_mfma_f32_16x16x32_bf16 v[118:121], v[182:185], v[198:201], v[118:121]
	v_mfma_f32_16x16x32_bf16 v[114:117], v[190:193], v[198:201], v[114:117]
	v_mfma_f32_16x16x32_bf16 v[102:105], v[182:185], v[206:209], v[102:105]
	v_mfma_f32_16x16x32_bf16 v[98:101], v[190:193], v[206:209], v[98:101]
	v_mfma_f32_16x16x32_bf16 v[86:89], v[182:185], v[214:217], v[86:89]
	v_mfma_f32_16x16x32_bf16 v[82:85], v[190:193], v[214:217], v[82:85]
	v_mfma_f32_16x16x32_bf16 v[70:73], v[182:185], v[222:225], v[70:73]
	v_mfma_f32_16x16x32_bf16 v[66:69], v[190:193], v[222:225], v[66:69]
	s_barrier
	s_add_i32 s6, s33, s41
	s_mov_b32 m0, s6
	ds_read_b128 v[194:197], v160 offset:49152
	ds_read_b128 v[198:201], v160 offset:50176
	ds_read_b128 v[202:205], v160 offset:51200
	ds_read_b128 v[206:209], v160 offset:52224
	ds_read_b128 v[210:213], v160 offset:53248
	ds_read_b128 v[214:217], v160 offset:54272
	ds_read_b128 v[218:221], v160 offset:55296
	ds_read_b128 v[222:225], v160 offset:56320
	global_load_lds_dwordx4 v134, s[100:101]
	s_add_i32 m0, s6, 0x2000
	s_add_i32 s6, s67, s41
	global_load_lds_dwordx4 v130, s[100:101]
	s_add_u32 s100, s100, s14
	s_addc_u32 s101, s101, s15
	s_mov_b32 m0, s6
	s_nop 0
	global_load_lds_dwordx4 v134, s[100:101]
	s_add_i32 m0, s6, 0x2000
	s_nop 0
	global_load_lds_dwordx4 v130, s[100:101]
	s_add_u32 s100, s34, 0x80
	s_addc_u32 s101, s35, 0
	s_mov_b32 m0, s56
	s_nop 0
	global_load_lds_dwordx4 v136, s[100:101]
	s_mov_b32 m0, s57
	s_nop 0
	global_load_lds_dwordx4 v132, s[100:101]
	s_waitcnt vmcnt(8)
	s_waitcnt lgkmcnt(0)
	s_barrier
	s_waitcnt lgkmcnt(0)
	v_mfma_f32_16x16x32_bf16 v[62:65], v[146:149], v[194:197], v[62:65]
	v_mfma_f32_16x16x32_bf16 v[58:61], v[166:169], v[194:197], v[58:61]
	v_mfma_f32_16x16x32_bf16 v[46:49], v[146:149], v[202:205], v[46:49]
	v_mfma_f32_16x16x32_bf16 v[42:45], v[166:169], v[202:205], v[42:45]
	v_mfma_f32_16x16x32_bf16 v[30:33], v[146:149], v[210:213], v[30:33]
	v_mfma_f32_16x16x32_bf16 v[26:29], v[166:169], v[210:213], v[26:29]
	v_mfma_f32_16x16x32_bf16 v[14:17], v[146:149], v[218:221], v[14:17]
	v_mfma_f32_16x16x32_bf16 v[10:13], v[166:169], v[218:221], v[10:13]
	v_mfma_f32_16x16x32_bf16 v[62:65], v[162:165], v[198:201], v[62:65]
	v_mfma_f32_16x16x32_bf16 v[58:61], v[170:173], v[198:201], v[58:61]
	v_mfma_f32_16x16x32_bf16 v[46:49], v[162:165], v[206:209], v[46:49]
	v_mfma_f32_16x16x32_bf16 v[42:45], v[170:173], v[206:209], v[42:45]
	v_mfma_f32_16x16x32_bf16 v[30:33], v[162:165], v[214:217], v[30:33]
	v_mfma_f32_16x16x32_bf16 v[26:29], v[170:173], v[214:217], v[26:29]
	v_mfma_f32_16x16x32_bf16 v[14:17], v[162:165], v[222:225], v[14:17]
	v_mfma_f32_16x16x32_bf16 v[10:13], v[170:173], v[222:225], v[10:13]
	v_mfma_f32_16x16x32_bf16 v[54:57], v[174:177], v[194:197], v[54:57]
	v_mfma_f32_16x16x32_bf16 v[50:53], v[186:189], v[194:197], v[50:53]
	v_mfma_f32_16x16x32_bf16 v[38:41], v[174:177], v[202:205], v[38:41]
	v_mfma_f32_16x16x32_bf16 v[34:37], v[186:189], v[202:205], v[34:37]
	v_mfma_f32_16x16x32_bf16 v[22:25], v[174:177], v[210:213], v[22:25]
	v_mfma_f32_16x16x32_bf16 v[18:21], v[186:189], v[210:213], v[18:21]
	v_mfma_f32_16x16x32_bf16 v[6:9], v[174:177], v[218:221], v[6:9]
	v_mfma_f32_16x16x32_bf16 v[2:5], v[186:189], v[218:221], v[2:5]
	v_mfma_f32_16x16x32_bf16 v[54:57], v[182:185], v[198:201], v[54:57]
	v_mfma_f32_16x16x32_bf16 v[50:53], v[190:193], v[198:201], v[50:53]
	v_mfma_f32_16x16x32_bf16 v[38:41], v[182:185], v[206:209], v[38:41]
	v_mfma_f32_16x16x32_bf16 v[34:37], v[190:193], v[206:209], v[34:37]
	v_mfma_f32_16x16x32_bf16 v[22:25], v[182:185], v[214:217], v[22:25]
	v_mfma_f32_16x16x32_bf16 v[18:21], v[190:193], v[214:217], v[18:21]
	v_mfma_f32_16x16x32_bf16 v[6:9], v[182:185], v[222:225], v[6:9]
	v_mfma_f32_16x16x32_bf16 v[2:5], v[190:193], v[222:225], v[2:5]
	s_barrier
	s_add_u32 s30, s30, 0x100
	s_addc_u32 s31, s31, 0
	s_add_u32 s2, s2, 0x100
	s_addc_u32 s54, s54, 0
	s_cmp_ge_i32 s59, s51
	s_mov_b32 s33, s59
	s_cbranch_scc0 .LBB0_208

; #define PG8_STAGE(bufoff, gbase, voff) do { _Pragma("unroll") for (int _i = 0; _i < 2; ++_i) \
;         __builtin_amdgcn_global_load_lds((const unsigned*)((const char*)(gbase) + (voff)[_i]), (PG8_LAS unsigned*)(lds + (bufoff) + ldsw + _i * 8192), 16, 0, 0); } while (0)
; #define PG8_LDA(dst, b, h) do { _Pragma("unroll") for (int m = 0; m < 4; ++m) _Pragma("unroll") for (int k = 0; k < 2; ++k) dst[m][k] = *(const PG8_LAS bf16x8*)(lds + PG8_SA(b, h) + aoff + m * 2048 + k * 1024); } while (0)
; #define PG8_LDB(dst, b, h) do { _Pragma("unroll") for (int n = 0; n < 2; ++n) _Pragma("unroll") for (int k = 0; k < 2; ++k) dst[n][k] = *(const PG8_LAS bf16x8*)(lds + PG8_SB(b, h) + boff + n * 2048 + k * 1024); } while (0)
; #define PG8_MMA(ai, bj, At, Bt) do { __builtin_amdgcn_s_setprio(1); _Pragma("unroll") for (int m = 0; m < 4; ++m) _Pragma("unroll") for (int n = 0; n < 2; ++n) _Pragma("unroll") for (int k = 0; k < 2; ++k) \
;         acc[ai][bj][m][n] = __builtin_amdgcn_mfma_f32_16x16x32_bf16(Bt[n][k], At[m][k], acc[ai][bj][m][n], 0, 0, 0); __builtin_amdgcn_s_setprio(0); } while (0)
; #define PG8_WAIT_V(n) asm volatile("s_waitcnt vmcnt(" #n ")" ::: "memory")
; #define PG8_WAIT_L(n) asm volatile("s_waitcnt lgkmcnt(" #n ")" ::: "memory")
; template <class Epi, class Sched, bool ALIGN_EPI = false, bool SP2 = false>
; __device__ __forceinline__ void gemm_phase(PG8_LAS unsigned char* lds, const Gemm g, const Sched& S, const Epi& E) {
;     ...
;             const bool last = (t == nt - 2);
;             const char* a1 = cA + (size_t)(t + 1) * kstep;
;             const char* a2 = last ? nA : cA + (size_t)(t + 2) * kstep; const char* b2 = last ? nB : cB + (size_t)(t + 2) * kstep;
;             const char* a3 = a2 + kstep; const char* b3 = b2 + kstep;
;             if (last && has_next) S.a_ready(nxt);
;             if constexpr (SP2) {
;             PG8_LDB(B0, 0, 0); PG8_LDB(B1, 0, 1); PG8_SCHED; PG8_LDA(At, 0, 0); PG8_STAGE(PG8_SA(1, 1), a1 + hstep, voffA);
;             PG8_WAIT_V(8); PG8_WAIT_L(0); PG8_BAR; PG8_MMA(0, 0, At, B0); PG8_MMA(0, 1, At, B1); PG8_BAR; PG8_SCHED;
;             PG8_LDA(At, 0, 1); PG8_STAGE(PG8_SB(0, 0), b2, voffB); PG8_STAGE(PG8_SB(0, 1), b2 + hstep, voffB); PG8_STAGE(PG8_SA(0, 0), a2, voffA);
;             PG8_WAIT_V(8); PG8_WAIT_L(0); PG8_BAR; PG8_MMA(1, 0, At, B0); PG8_MMA(1, 1, At, B1); PG8_BAR; PG8_SCHED;
.LBB0_300:
	s_add_i32 s59, s33, 2
	s_add_u32 s6, s38, 0x80
	s_addc_u32 s7, s39, 0
	s_add_i32 s72, 0, 0x10000
	s_cmp_eq_u32 s54, s33
	s_cselect_b32 s41, s13, s7
	s_cselect_b32 s40, s12, s6
	s_cselect_b32 s7, s37, s80
	s_cselect_b32 s6, s36, s79
	s_add_i32 s33, 0, 0x14000
	v_add_u32_e32 v166, s72, v148
	v_add_u32_e32 v178, s33, v148
	ds_read_b128 v[144:147], v166
	ds_read_b128 v[158:161], v166 offset:1024
	ds_read_b128 v[162:165], v166 offset:2048
	ds_read_b128 v[166:169], v166 offset:3072
	ds_read_b128 v[170:173], v178
	ds_read_b128 v[174:177], v178 offset:1024
	ds_read_b128 v[182:185], v178 offset:2048
	ds_read_b128 v[186:189], v178 offset:3072
	s_add_i32 m0, s45, 0xc000
	ds_read_b128 v[190:193], v151
	ds_read_b128 v[194:197], v151 offset:1024
	ds_read_b128 v[198:201], v151 offset:2048
	ds_read_b128 v[202:205], v151 offset:3072
	ds_read_b128 v[206:209], v151 offset:4096
	ds_read_b128 v[210:213], v151 offset:5120
	ds_read_b128 v[214:217], v151 offset:6144
	ds_read_b128 v[218:221], v151 offset:7168
	global_load_lds_dwordx4 v140, s[38:39]
	s_add_i32 m0, s45, 0xe000
	s_nop 0
	global_load_lds_dwordx4 v142, s[38:39]
	s_waitcnt vmcnt(8)
	s_waitcnt lgkmcnt(0)
	s_barrier
	s_waitcnt lgkmcnt(0)
	v_mfma_f32_16x16x32_bf16 v[126:129], v[144:147], v[190:193], v[126:129]
	v_mfma_f32_16x16x32_bf16 v[122:125], v[162:165], v[190:193], v[122:125]
	v_mfma_f32_16x16x32_bf16 v[110:113], v[144:147], v[198:201], v[110:113]
	v_mfma_f32_16x16x32_bf16 v[106:109], v[162:165], v[198:201], v[106:109]
	v_mfma_f32_16x16x32_bf16 v[94:97], v[144:147], v[206:209], v[94:97]
	v_mfma_f32_16x16x32_bf16 v[90:93], v[162:165], v[206:209], v[90:93]
	v_mfma_f32_16x16x32_bf16 v[78:81], v[144:147], v[214:217], v[78:81]
	v_mfma_f32_16x16x32_bf16 v[74:77], v[162:165], v[214:217], v[74:77]
	v_mfma_f32_16x16x32_bf16 v[126:129], v[158:161], v[194:197], v[126:129]
	v_mfma_f32_16x16x32_bf16 v[122:125], v[166:169], v[194:197], v[122:125]
	v_mfma_f32_16x16x32_bf16 v[110:113], v[158:161], v[202:205], v[110:113]
	v_mfma_f32_16x16x32_bf16 v[106:109], v[166:169], v[202:205], v[106:109]
	v_mfma_f32_16x16x32_bf16 v[94:97], v[158:161], v[210:213], v[94:97]
	v_mfma_f32_16x16x32_bf16 v[90:93], v[166:169], v[210:213], v[90:93]
	v_mfma_f32_16x16x32_bf16 v[78:81], v[158:161], v[218:221], v[78:81]
	v_mfma_f32_16x16x32_bf16 v[74:77], v[166:169], v[218:221], v[74:77]
	v_mfma_f32_16x16x32_bf16 v[118:121], v[170:173], v[190:193], v[118:121]
	v_mfma_f32_16x16x32_bf16 v[114:117], v[182:185], v[190:193], v[114:117]
	v_mfma_f32_16x16x32_bf16 v[102:105], v[170:173], v[198:201], v[102:105]
	v_mfma_f32_16x16x32_bf16 v[98:101], v[182:185], v[198:201], v[98:101]
	v_mfma_f32_16x16x32_bf16 v[86:89], v[170:173], v[206:209], v[86:89]
	v_mfma_f32_16x16x32_bf16 v[82:85], v[182:185], v[206:209], v[82:85]
	v_mfma_f32_16x16x32_bf16 v[70:73], v[170:173], v[214:217], v[70:73]
	v_mfma_f32_16x16x32_bf16 v[66:69], v[182:185], v[214:217], v[66:69]
	v_mfma_f32_16x16x32_bf16 v[118:121], v[174:177], v[194:197], v[118:121]
	v_mfma_f32_16x16x32_bf16 v[114:117], v[186:189], v[194:197], v[114:117]
	v_mfma_f32_16x16x32_bf16 v[102:105], v[174:177], v[202:205], v[102:105]
	v_mfma_f32_16x16x32_bf16 v[98:101], v[186:189], v[202:205], v[98:101]
	v_mfma_f32_16x16x32_bf16 v[86:89], v[174:177], v[210:213], v[86:89]
	v_mfma_f32_16x16x32_bf16 v[82:85], v[186:189], v[210:213], v[82:85]
	v_mfma_f32_16x16x32_bf16 v[70:73], v[174:177], v[218:221], v[70:73]
	v_mfma_f32_16x16x32_bf16 v[66:69], v[186:189], v[218:221], v[66:69]
	s_barrier
	s_add_i32 s72, s72, s44
	s_mov_b32 m0, s72
	ds_read_b128 v[190:193], v151 offset:16384
	ds_read_b128 v[194:197], v151 offset:17408
	ds_read_b128 v[198:201], v151 offset:18432
	ds_read_b128 v[202:205], v151 offset:19456
	ds_read_b128 v[206:209], v151 offset:20480
	ds_read_b128 v[210:213], v151 offset:21504
	ds_read_b128 v[214:217], v151 offset:22528
	ds_read_b128 v[218:221], v151 offset:23552
	global_load_lds_dwordx4 v132, s[6:7]
	s_add_i32 m0, s72, 0x2000
	s_add_u32 s100, s6, 0x80
	s_addc_u32 s101, s7, 0
	global_load_lds_dwordx4 v136, s[6:7]
	s_add_u32 s6, s6, s20
	s_addc_u32 s7, s7, s21
	s_add_i32 s33, s33, s44
	s_mov_b32 m0, s33
	s_nop 0
	global_load_lds_dwordx4 v132, s[6:7]
	s_add_i32 m0, s33, 0x2000
	s_nop 0
	global_load_lds_dwordx4 v136, s[6:7]
	s_mov_b32 m0, s45
	s_nop 0
	global_load_lds_dwordx4 v130, s[40:41]
	s_mov_b32 m0, s46
	s_nop 0
	global_load_lds_dwordx4 v134, s[40:41]
	s_waitcnt vmcnt(8)
	s_waitcnt lgkmcnt(0)
	s_barrier
	s_waitcnt lgkmcnt(0)
	v_mfma_f32_16x16x32_bf16 v[62:65], v[144:147], v[190:193], v[62:65]
	v_mfma_f32_16x16x32_bf16 v[58:61], v[162:165], v[190:193], v[58:61]
	v_mfma_f32_16x16x32_bf16 v[46:49], v[144:147], v[198:201], v[46:49]
	v_mfma_f32_16x16x32_bf16 v[42:45], v[162:165], v[198:201], v[42:45]
	v_mfma_f32_16x16x32_bf16 v[30:33], v[144:147], v[206:209], v[30:33]
	v_mfma_f32_16x16x32_bf16 v[26:29], v[162:165], v[206:209], v[26:29]
	v_mfma_f32_16x16x32_bf16 v[14:17], v[144:147], v[214:217], v[14:17]
	v_mfma_f32_16x16x32_bf16 v[10:13], v[162:165], v[214:217], v[10:13]
	v_mfma_f32_16x16x32_bf16 v[62:65], v[158:161], v[194:197], v[62:65]
	v_mfma_f32_16x16x32_bf16 v[58:61], v[166:169], v[194:197], v[58:61]
	v_mfma_f32_16x16x32_bf16 v[46:49], v[158:161], v[202:205], v[46:49]
	v_mfma_f32_16x16x32_bf16 v[42:45], v[166:169], v[202:205], v[42:45]
	v_mfma_f32_16x16x32_bf16 v[30:33], v[158:161], v[210:213], v[30:33]
	v_mfma_f32_16x16x32_bf16 v[26:29], v[166:169], v[210:213], v[26:29]
	v_mfma_f32_16x16x32_bf16 v[14:17], v[158:161], v[218:221], v[14:17]
	v_mfma_f32_16x16x32_bf16 v[10:13], v[166:169], v[218:221], v[10:13]
	v_mfma_f32_16x16x32_bf16 v[54:57], v[170:173], v[190:193], v[54:57]
	v_mfma_f32_16x16x32_bf16 v[50:53], v[182:185], v[190:193], v[50:53]
	v_mfma_f32_16x16x32_bf16 v[38:41], v[170:173], v[198:201], v[38:41]
	v_mfma_f32_16x16x32_bf16 v[34:37], v[182:185], v[198:201], v[34:37]
	v_mfma_f32_16x16x32_bf16 v[22:25], v[170:173], v[206:209], v[22:25]
	v_mfma_f32_16x16x32_bf16 v[18:21], v[182:185], v[206:209], v[18:21]
	v_mfma_f32_16x16x32_bf16 v[6:9], v[170:173], v[214:217], v[6:9]
	v_mfma_f32_16x16x32_bf16 v[2:5], v[182:185], v[214:217], v[2:5]
	v_mfma_f32_16x16x32_bf16 v[54:57], v[174:177], v[194:197], v[54:57]
	v_mfma_f32_16x16x32_bf16 v[50:53], v[186:189], v[194:197], v[50:53]
	v_mfma_f32_16x16x32_bf16 v[38:41], v[174:177], v[202:205], v[38:41]
	v_mfma_f32_16x16x32_bf16 v[34:37], v[186:189], v[202:205], v[34:37]
	v_mfma_f32_16x16x32_bf16 v[22:25], v[174:177], v[210:213], v[22:25]
	v_mfma_f32_16x16x32_bf16 v[18:21], v[186:189], v[210:213], v[18:21]
	v_mfma_f32_16x16x32_bf16 v[6:9], v[174:177], v[218:221], v[6:9]
	v_mfma_f32_16x16x32_bf16 v[2:5], v[186:189], v[218:221], v[2:5]
	s_barrier
; #define PG8_STAGE(bufoff, gbase, voff) do { _Pragma("unroll") for (int _i = 0; _i < 2; ++_i) \
;         __builtin_amdgcn_global_load_lds((const unsigned*)((const char*)(gbase) + (voff)[_i]), (PG8_LAS unsigned*)(lds + (bufoff) + ldsw + _i * 8192), 16, 0, 0); } while (0)
; #define PG8_LDA(dst, b, h) do { _Pragma("unroll") for (int m = 0; m < 4; ++m) _Pragma("unroll") for (int k = 0; k < 2; ++k) dst[m][k] = *(const PG8_LAS bf16x8*)(lds + PG8_SA(b, h) + aoff + m * 2048 + k * 1024); } while (0)
; #define PG8_LDB(dst, b, h) do { _Pragma("unroll") for (int n = 0; n < 2; ++n) _Pragma("unroll") for (int k = 0; k < 2; ++k) dst[n][k] = *(const PG8_LAS bf16x8*)(lds + PG8_SB(b, h) + boff + n * 2048 + k * 1024); } while (0)
; #define PG8_MMA(ai, bj, At, Bt) do { __builtin_amdgcn_s_setprio(1); _Pragma("unroll") for (int m = 0; m < 4; ++m) _Pragma("unroll") for (int n = 0; n < 2; ++n) _Pragma("unroll") for (int k = 0; k < 2; ++k) \
;         acc[ai][bj][m][n] = __builtin_amdgcn_mfma_f32_16x16x32_bf16(Bt[n][k], At[m][k], acc[ai][bj][m][n], 0, 0, 0); __builtin_amdgcn_s_setprio(0); } while (0)
; #define PG8_WAIT_V(n) asm volatile("s_waitcnt vmcnt(" #n ")" ::: "memory")
; #define PG8_WAIT_L(n) asm volatile("s_waitcnt lgkmcnt(" #n ")" ::: "memory")
; #define PG8_BAR __builtin_amdgcn_s_barrier()
; #define PG8_SCHED __builtin_amdgcn_sched_barrier(0)
; template <class Epi, class Sched, bool ALIGN_EPI = false, bool SP2 = false>
; __device__ __forceinline__ void gemm_phase(PG8_LAS unsigned char* lds, const Gemm g, const Sched& S, const Epi& E) {
;     ...
;             PG8_LDB(B0, 1, 0); PG8_LDB(B1, 1, 1); PG8_SCHED; PG8_LDA(At, 1, 0); PG8_STAGE(PG8_SA(0, 1), a2 + hstep, voffA);
;             PG8_WAIT_V(8); PG8_WAIT_L(0); PG8_BAR; PG8_MMA(0, 0, At, B0); PG8_MMA(0, 1, At, B1); PG8_BAR; PG8_SCHED;
;             PG8_LDA(At, 1, 1); PG8_STAGE(PG8_SB(1, 0), b3, voffB); PG8_STAGE(PG8_SB(1, 1), b3 + hstep, voffB); PG8_STAGE(PG8_SA(1, 0), a3, voffA);
;             PG8_WAIT_V(8); PG8_WAIT_L(0); PG8_BAR; PG8_MMA(1, 0, At, B0); PG8_MMA(1, 1, At, B1); PG8_BAR; PG8_SCHED;
	s_add_i32 s33, 0, 0x18000
	s_add_i32 s72, 0, 0x1c000
	v_add_u32_e32 v166, s33, v148
	v_add_u32_e32 v181, s72, v148
	ds_read_b128 v[144:147], v166
	ds_read_b128 v[158:161], v166 offset:1024
	ds_read_b128 v[162:165], v166 offset:2048
	ds_read_b128 v[166:169], v166 offset:3072
	ds_read_b128 v[170:173], v181
	ds_read_b128 v[174:177], v181 offset:1024
	ds_read_b128 v[182:185], v181 offset:2048
	ds_read_b128 v[186:189], v181 offset:3072
	s_add_u32 s6, s40, s20
	s_addc_u32 s7, s41, s21
	s_mov_b32 m0, s47
	ds_read_b128 v[190:193], v151 offset:32768
	ds_read_b128 v[194:197], v151 offset:33792
	ds_read_b128 v[198:201], v151 offset:34816
	ds_read_b128 v[202:205], v151 offset:35840
	ds_read_b128 v[206:209], v151 offset:36864
	ds_read_b128 v[210:213], v151 offset:37888
	ds_read_b128 v[214:217], v151 offset:38912
	ds_read_b128 v[218:221], v151 offset:39936
	global_load_lds_dwordx4 v130, s[6:7]
	s_mov_b32 m0, s48
	s_nop 0
	global_load_lds_dwordx4 v134, s[6:7]
	s_waitcnt vmcnt(8)
	s_waitcnt lgkmcnt(0)
	s_barrier
	s_waitcnt lgkmcnt(0)
	v_mfma_f32_16x16x32_bf16 v[126:129], v[144:147], v[190:193], v[126:129]
	v_mfma_f32_16x16x32_bf16 v[122:125], v[162:165], v[190:193], v[122:125]
	v_mfma_f32_16x16x32_bf16 v[110:113], v[144:147], v[198:201], v[110:113]
	v_mfma_f32_16x16x32_bf16 v[106:109], v[162:165], v[198:201], v[106:109]
	v_mfma_f32_16x16x32_bf16 v[94:97], v[144:147], v[206:209], v[94:97]
	v_mfma_f32_16x16x32_bf16 v[90:93], v[162:165], v[206:209], v[90:93]
	v_mfma_f32_16x16x32_bf16 v[78:81], v[144:147], v[214:217], v[78:81]
	v_mfma_f32_16x16x32_bf16 v[74:77], v[162:165], v[214:217], v[74:77]
	v_mfma_f32_16x16x32_bf16 v[126:129], v[158:161], v[194:197], v[126:129]
	v_mfma_f32_16x16x32_bf16 v[122:125], v[166:169], v[194:197], v[122:125]
	v_mfma_f32_16x16x32_bf16 v[110:113], v[158:161], v[202:205], v[110:113]
	v_mfma_f32_16x16x32_bf16 v[106:109], v[166:169], v[202:205], v[106:109]
	v_mfma_f32_16x16x32_bf16 v[94:97], v[158:161], v[210:213], v[94:97]
	v_mfma_f32_16x16x32_bf16 v[90:93], v[166:169], v[210:213], v[90:93]
	v_mfma_f32_16x16x32_bf16 v[78:81], v[158:161], v[218:221], v[78:81]
	v_mfma_f32_16x16x32_bf16 v[74:77], v[166:169], v[218:221], v[74:77]
	v_mfma_f32_16x16x32_bf16 v[118:121], v[170:173], v[190:193], v[118:121]
	v_mfma_f32_16x16x32_bf16 v[114:117], v[182:185], v[190:193], v[114:117]
	v_mfma_f32_16x16x32_bf16 v[102:105], v[170:173], v[198:201], v[102:105]
	v_mfma_f32_16x16x32_bf16 v[98:101], v[182:185], v[198:201], v[98:101]
	v_mfma_f32_16x16x32_bf16 v[86:89], v[170:173], v[206:209], v[86:89]
	v_mfma_f32_16x16x32_bf16 v[82:85], v[182:185], v[206:209], v[82:85]
	v_mfma_f32_16x16x32_bf16 v[70:73], v[170:173], v[214:217], v[70:73]
	v_mfma_f32_16x16x32_bf16 v[66:69], v[182:185], v[214:217], v[66:69]
	v_mfma_f32_16x16x32_bf16 v[118:121], v[174:177], v[194:197], v[118:121]
	v_mfma_f32_16x16x32_bf16 v[114:117], v[186:189], v[194:197], v[114:117]
	v_mfma_f32_16x16x32_bf16 v[102:105], v[174:177], v[202:205], v[102:105]
	v_mfma_f32_16x16x32_bf16 v[98:101], v[186:189], v[202:205], v[98:101]
	v_mfma_f32_16x16x32_bf16 v[86:89], v[174:177], v[210:213], v[86:89]
	v_mfma_f32_16x16x32_bf16 v[82:85], v[186:189], v[210:213], v[82:85]
	v_mfma_f32_16x16x32_bf16 v[70:73], v[174:177], v[218:221], v[70:73]
	v_mfma_f32_16x16x32_bf16 v[66:69], v[186:189], v[218:221], v[66:69]
	s_barrier
	s_add_i32 s6, s33, s44
	s_mov_b32 m0, s6
	ds_read_b128 v[190:193], v151 offset:49152
	ds_read_b128 v[194:197], v151 offset:50176
	ds_read_b128 v[198:201], v151 offset:51200
	ds_read_b128 v[202:205], v151 offset:52224
	ds_read_b128 v[206:209], v151 offset:53248
	ds_read_b128 v[210:213], v151 offset:54272
	ds_read_b128 v[214:217], v151 offset:55296
	ds_read_b128 v[218:221], v151 offset:56320
	global_load_lds_dwordx4 v132, s[100:101]
	s_add_i32 m0, s6, 0x2000
	s_add_i32 s6, s72, s44
	global_load_lds_dwordx4 v136, s[100:101]
	s_add_u32 s100, s100, s20
	s_addc_u32 s101, s101, s21
	s_mov_b32 m0, s6
	s_nop 0
	global_load_lds_dwordx4 v132, s[100:101]
	s_add_i32 m0, s6, 0x2000
	s_nop 0
	global_load_lds_dwordx4 v136, s[100:101]
	s_add_u32 s100, s40, 0x80
	s_addc_u32 s101, s41, 0
	s_mov_b32 m0, s50
	s_nop 0
	global_load_lds_dwordx4 v130, s[100:101]
	s_mov_b32 m0, s51
	s_nop 0
	global_load_lds_dwordx4 v134, s[100:101]
	s_waitcnt vmcnt(8)
	s_waitcnt lgkmcnt(0)
	s_barrier
	s_waitcnt lgkmcnt(0)
	v_mfma_f32_16x16x32_bf16 v[62:65], v[144:147], v[190:193], v[62:65]
	v_mfma_f32_16x16x32_bf16 v[58:61], v[162:165], v[190:193], v[58:61]
	v_mfma_f32_16x16x32_bf16 v[46:49], v[144:147], v[198:201], v[46:49]
	v_mfma_f32_16x16x32_bf16 v[42:45], v[162:165], v[198:201], v[42:45]
	v_mfma_f32_16x16x32_bf16 v[30:33], v[144:147], v[206:209], v[30:33]
	v_mfma_f32_16x16x32_bf16 v[26:29], v[162:165], v[206:209], v[26:29]
	v_mfma_f32_16x16x32_bf16 v[14:17], v[144:147], v[214:217], v[14:17]
	v_mfma_f32_16x16x32_bf16 v[10:13], v[162:165], v[214:217], v[10:13]
	v_mfma_f32_16x16x32_bf16 v[62:65], v[158:161], v[194:197], v[62:65]
	v_mfma_f32_16x16x32_bf16 v[58:61], v[166:169], v[194:197], v[58:61]
	v_mfma_f32_16x16x32_bf16 v[46:49], v[158:161], v[202:205], v[46:49]
	v_mfma_f32_16x16x32_bf16 v[42:45], v[166:169], v[202:205], v[42:45]
	v_mfma_f32_16x16x32_bf16 v[30:33], v[158:161], v[210:213], v[30:33]
	v_mfma_f32_16x16x32_bf16 v[26:29], v[166:169], v[210:213], v[26:29]
	v_mfma_f32_16x16x32_bf16 v[14:17], v[158:161], v[218:221], v[14:17]
	v_mfma_f32_16x16x32_bf16 v[10:13], v[166:169], v[218:221], v[10:13]
	v_mfma_f32_16x16x32_bf16 v[54:57], v[170:173], v[190:193], v[54:57]
	v_mfma_f32_16x16x32_bf16 v[50:53], v[182:185], v[190:193], v[50:53]
	v_mfma_f32_16x16x32_bf16 v[38:41], v[170:173], v[198:201], v[38:41]
	v_mfma_f32_16x16x32_bf16 v[34:37], v[182:185], v[198:201], v[34:37]
	v_mfma_f32_16x16x32_bf16 v[22:25], v[170:173], v[206:209], v[22:25]
	v_mfma_f32_16x16x32_bf16 v[18:21], v[182:185], v[206:209], v[18:21]
	v_mfma_f32_16x16x32_bf16 v[6:9], v[170:173], v[214:217], v[6:9]
	v_mfma_f32_16x16x32_bf16 v[2:5], v[182:185], v[214:217], v[2:5]
	v_mfma_f32_16x16x32_bf16 v[54:57], v[174:177], v[194:197], v[54:57]
	v_mfma_f32_16x16x32_bf16 v[50:53], v[186:189], v[194:197], v[50:53]
	v_mfma_f32_16x16x32_bf16 v[38:41], v[174:177], v[202:205], v[38:41]
	v_mfma_f32_16x16x32_bf16 v[34:37], v[186:189], v[202:205], v[34:37]
	v_mfma_f32_16x16x32_bf16 v[22:25], v[174:177], v[210:213], v[22:25]
	v_mfma_f32_16x16x32_bf16 v[18:21], v[186:189], v[210:213], v[18:21]
	v_mfma_f32_16x16x32_bf16 v[6:9], v[174:177], v[218:221], v[6:9]
	v_mfma_f32_16x16x32_bf16 v[2:5], v[186:189], v[218:221], v[2:5]
	s_barrier
	s_add_u32 s38, s38, 0x100
	s_addc_u32 s39, s39, 0
	s_add_u32 s79, s79, 0x100
	s_addc_u32 s80, s80, 0
	s_cmp_ge_i32 s59, s49
	s_mov_b32 s33, s59
	s_cbranch_scc0 .LBB0_300

; #define PG8_STAGE(bufoff, gbase, voff) do { _Pragma("unroll") for (int _i = 0; _i < 2; ++_i) \
;         __builtin_amdgcn_global_load_lds((const unsigned*)((const char*)(gbase) + (voff)[_i]), (PG8_LAS unsigned*)(lds + (bufoff) + ldsw + _i * 8192), 16, 0, 0); } while (0)
; #define PG8_LDA(dst, b, h) do { _Pragma("unroll") for (int m = 0; m < 4; ++m) _Pragma("unroll") for (int k = 0; k < 2; ++k) dst[m][k] = *(const PG8_LAS bf16x8*)(lds + PG8_SA(b, h) + aoff + m * 2048 + k * 1024); } while (0)
; #define PG8_LDB(dst, b, h) do { _Pragma("unroll") for (int n = 0; n < 2; ++n) _Pragma("unroll") for (int k = 0; k < 2; ++k) dst[n][k] = *(const PG8_LAS bf16x8*)(lds + PG8_SB(b, h) + boff + n * 2048 + k * 1024); } while (0)
; #define PG8_MMA(ai, bj, At, Bt) do { __builtin_amdgcn_s_setprio(1); _Pragma("unroll") for (int m = 0; m < 4; ++m) _Pragma("unroll") for (int n = 0; n < 2; ++n) _Pragma("unroll") for (int k = 0; k < 2; ++k) \
;         acc[ai][bj][m][n] = __builtin_amdgcn_mfma_f32_16x16x32_bf16(Bt[n][k], At[m][k], acc[ai][bj][m][n], 0, 0, 0); __builtin_amdgcn_s_setprio(0); } while (0)
; #define PG8_WAIT_V(n) asm volatile("s_waitcnt vmcnt(" #n ")" ::: "memory")
; #define PG8_WAIT_L(n) asm volatile("s_waitcnt lgkmcnt(" #n ")" ::: "memory")
; template <class Epi, class Sched, bool ALIGN_EPI = false, bool SP2 = false>
; __device__ __forceinline__ void gemm_phase(PG8_LAS unsigned char* lds, const Gemm g, const Sched& S, const Epi& E) {
;     ...
;             const bool last = (t == nt - 2);
;             const char* a1 = cA + (size_t)(t + 1) * kstep;
;             const char* a2 = last ? nA : cA + (size_t)(t + 2) * kstep; const char* b2 = last ? nB : cB + (size_t)(t + 2) * kstep;
;             const char* a3 = a2 + kstep; const char* b3 = b2 + kstep;
;             if (last && has_next) S.a_ready(nxt);
;             if constexpr (SP2) {
;             PG8_LDB(B0, 0, 0); PG8_LDB(B1, 0, 1); PG8_SCHED; PG8_LDA(At, 0, 0); PG8_STAGE(PG8_SA(1, 1), a1 + hstep, voffA);
;             PG8_WAIT_V(8); PG8_WAIT_L(0); PG8_BAR; PG8_MMA(0, 0, At, B0); PG8_MMA(0, 1, At, B1); PG8_BAR; PG8_SCHED;
;             PG8_LDA(At, 0, 1); PG8_STAGE(PG8_SB(0, 0), b2, voffB); PG8_STAGE(PG8_SB(0, 1), b2 + hstep, voffB); PG8_STAGE(PG8_SA(0, 0), a2, voffA);
;             PG8_WAIT_V(8); PG8_WAIT_L(0); PG8_BAR; PG8_MMA(1, 0, At, B0); PG8_MMA(1, 1, At, B1); PG8_BAR; PG8_SCHED;
.LBB0_406:
	s_add_i32 s59, s33, 2
	s_add_u32 s6, s34, 0x80
	s_addc_u32 s7, s35, 0
	s_add_i32 s72, 0, 0x10000
	s_cmp_eq_u32 s56, s33
	s_cselect_b32 s37, s11, s7
	s_cselect_b32 s36, s10, s6
	v_add_u32_e32 v148, s72, v150
	s_cselect_b32 s7, s31, s79
	s_cselect_b32 s6, s30, s67
	s_add_i32 s33, 0, 0x14000
	ds_read_b128 v[144:147], v148
	ds_read_b128 v[160:163], v148 offset:1024
	ds_read_b128 v[164:167], v148 offset:2048
	ds_read_b128 v[168:171], v148 offset:3072
	v_add_u32_e32 v148, s33, v150
	ds_read_b128 v[172:175], v148
	ds_read_b128 v[176:179], v148 offset:1024
	ds_read_b128 v[182:185], v148 offset:2048
	ds_read_b128 v[186:189], v148 offset:3072
	s_add_i32 m0, s46, 0xc000
	ds_read_b128 v[190:193], v158
	ds_read_b128 v[194:197], v158 offset:1024
	ds_read_b128 v[198:201], v158 offset:2048
	ds_read_b128 v[202:205], v158 offset:3072
	ds_read_b128 v[206:209], v158 offset:4096
	ds_read_b128 v[210:213], v158 offset:5120
	ds_read_b128 v[214:217], v158 offset:6144
	ds_read_b128 v[218:221], v158 offset:7168
	global_load_lds_dwordx4 v140, s[34:35]
	s_add_i32 m0, s46, 0xe000
	s_nop 0
	global_load_lds_dwordx4 v142, s[34:35]
	s_waitcnt vmcnt(8)
	s_waitcnt lgkmcnt(0)
	s_barrier
	s_waitcnt lgkmcnt(0)
	v_mfma_f32_16x16x32_bf16 v[122:125], v[144:147], v[190:193], v[122:125]
	v_mfma_f32_16x16x32_bf16 v[126:129], v[164:167], v[190:193], v[126:129]
	v_mfma_f32_16x16x32_bf16 v[110:113], v[144:147], v[198:201], v[110:113]
	v_mfma_f32_16x16x32_bf16 v[106:109], v[164:167], v[198:201], v[106:109]
	v_mfma_f32_16x16x32_bf16 v[94:97], v[144:147], v[206:209], v[94:97]
	v_mfma_f32_16x16x32_bf16 v[90:93], v[164:167], v[206:209], v[90:93]
	v_mfma_f32_16x16x32_bf16 v[78:81], v[144:147], v[214:217], v[78:81]
	v_mfma_f32_16x16x32_bf16 v[74:77], v[164:167], v[214:217], v[74:77]
	v_mfma_f32_16x16x32_bf16 v[122:125], v[160:163], v[194:197], v[122:125]
	v_mfma_f32_16x16x32_bf16 v[126:129], v[168:171], v[194:197], v[126:129]
	v_mfma_f32_16x16x32_bf16 v[110:113], v[160:163], v[202:205], v[110:113]
	v_mfma_f32_16x16x32_bf16 v[106:109], v[168:171], v[202:205], v[106:109]
	v_mfma_f32_16x16x32_bf16 v[94:97], v[160:163], v[210:213], v[94:97]
	v_mfma_f32_16x16x32_bf16 v[90:93], v[168:171], v[210:213], v[90:93]
	v_mfma_f32_16x16x32_bf16 v[78:81], v[160:163], v[218:221], v[78:81]
	v_mfma_f32_16x16x32_bf16 v[74:77], v[168:171], v[218:221], v[74:77]
	v_mfma_f32_16x16x32_bf16 v[118:121], v[172:175], v[190:193], v[118:121]
	v_mfma_f32_16x16x32_bf16 v[114:117], v[182:185], v[190:193], v[114:117]
	v_mfma_f32_16x16x32_bf16 v[102:105], v[172:175], v[198:201], v[102:105]
	v_mfma_f32_16x16x32_bf16 v[98:101], v[182:185], v[198:201], v[98:101]
	v_mfma_f32_16x16x32_bf16 v[86:89], v[172:175], v[206:209], v[86:89]
	v_mfma_f32_16x16x32_bf16 v[82:85], v[182:185], v[206:209], v[82:85]
	v_mfma_f32_16x16x32_bf16 v[70:73], v[172:175], v[214:217], v[70:73]
	v_mfma_f32_16x16x32_bf16 v[66:69], v[182:185], v[214:217], v[66:69]
	v_mfma_f32_16x16x32_bf16 v[118:121], v[176:179], v[194:197], v[118:121]
	v_mfma_f32_16x16x32_bf16 v[114:117], v[186:189], v[194:197], v[114:117]
	v_mfma_f32_16x16x32_bf16 v[102:105], v[176:179], v[202:205], v[102:105]
	v_mfma_f32_16x16x32_bf16 v[98:101], v[186:189], v[202:205], v[98:101]
	v_mfma_f32_16x16x32_bf16 v[86:89], v[176:179], v[210:213], v[86:89]
	v_mfma_f32_16x16x32_bf16 v[82:85], v[186:189], v[210:213], v[82:85]
	v_mfma_f32_16x16x32_bf16 v[70:73], v[176:179], v[218:221], v[70:73]
	v_mfma_f32_16x16x32_bf16 v[66:69], v[186:189], v[218:221], v[66:69]
	s_barrier
	s_add_i32 s72, s72, s40
	s_mov_b32 m0, s72
	ds_read_b128 v[190:193], v158 offset:16384
	ds_read_b128 v[194:197], v158 offset:17408
	ds_read_b128 v[198:201], v158 offset:18432
	ds_read_b128 v[202:205], v158 offset:19456
	ds_read_b128 v[206:209], v158 offset:20480
	ds_read_b128 v[210:213], v158 offset:21504
	ds_read_b128 v[214:217], v158 offset:22528
	ds_read_b128 v[218:221], v158 offset:23552
	global_load_lds_dwordx4 v134, s[6:7]
	s_add_i32 m0, s72, 0x2000
	s_add_u32 s100, s6, 0x80
	s_addc_u32 s101, s7, 0
	global_load_lds_dwordx4 v130, s[6:7]
	s_add_u32 s6, s6, s16
	s_addc_u32 s7, s7, s17
	s_add_i32 s33, s33, s40
	s_mov_b32 m0, s33
	s_nop 0
	global_load_lds_dwordx4 v134, s[6:7]
	s_add_i32 m0, s33, 0x2000
	s_nop 0
	global_load_lds_dwordx4 v130, s[6:7]
	s_mov_b32 m0, s46
	s_nop 0
	global_load_lds_dwordx4 v136, s[36:37]
	s_mov_b32 m0, s47
	s_nop 0
	global_load_lds_dwordx4 v132, s[36:37]
	s_waitcnt vmcnt(8)
	s_waitcnt lgkmcnt(0)
	s_barrier
	s_waitcnt lgkmcnt(0)
	v_mfma_f32_16x16x32_bf16 v[62:65], v[144:147], v[190:193], v[62:65]
	v_mfma_f32_16x16x32_bf16 v[58:61], v[164:167], v[190:193], v[58:61]
	v_mfma_f32_16x16x32_bf16 v[46:49], v[144:147], v[198:201], v[46:49]
	v_mfma_f32_16x16x32_bf16 v[42:45], v[164:167], v[198:201], v[42:45]
	v_mfma_f32_16x16x32_bf16 v[30:33], v[144:147], v[206:209], v[30:33]
	v_mfma_f32_16x16x32_bf16 v[26:29], v[164:167], v[206:209], v[26:29]
	v_mfma_f32_16x16x32_bf16 v[14:17], v[144:147], v[214:217], v[14:17]
	v_mfma_f32_16x16x32_bf16 v[10:13], v[164:167], v[214:217], v[10:13]
	v_mfma_f32_16x16x32_bf16 v[62:65], v[160:163], v[194:197], v[62:65]
	v_mfma_f32_16x16x32_bf16 v[58:61], v[168:171], v[194:197], v[58:61]
	v_mfma_f32_16x16x32_bf16 v[46:49], v[160:163], v[202:205], v[46:49]
	v_mfma_f32_16x16x32_bf16 v[42:45], v[168:171], v[202:205], v[42:45]
	v_mfma_f32_16x16x32_bf16 v[30:33], v[160:163], v[210:213], v[30:33]
	v_mfma_f32_16x16x32_bf16 v[26:29], v[168:171], v[210:213], v[26:29]
	v_mfma_f32_16x16x32_bf16 v[14:17], v[160:163], v[218:221], v[14:17]
	v_mfma_f32_16x16x32_bf16 v[10:13], v[168:171], v[218:221], v[10:13]
	v_mfma_f32_16x16x32_bf16 v[54:57], v[172:175], v[190:193], v[54:57]
	v_mfma_f32_16x16x32_bf16 v[50:53], v[182:185], v[190:193], v[50:53]
	v_mfma_f32_16x16x32_bf16 v[38:41], v[172:175], v[198:201], v[38:41]
	v_mfma_f32_16x16x32_bf16 v[34:37], v[182:185], v[198:201], v[34:37]
	v_mfma_f32_16x16x32_bf16 v[22:25], v[172:175], v[206:209], v[22:25]
	v_mfma_f32_16x16x32_bf16 v[18:21], v[182:185], v[206:209], v[18:21]
	v_mfma_f32_16x16x32_bf16 v[6:9], v[172:175], v[214:217], v[6:9]
	v_mfma_f32_16x16x32_bf16 v[2:5], v[182:185], v[214:217], v[2:5]
	v_mfma_f32_16x16x32_bf16 v[54:57], v[176:179], v[194:197], v[54:57]
	v_mfma_f32_16x16x32_bf16 v[50:53], v[186:189], v[194:197], v[50:53]
	v_mfma_f32_16x16x32_bf16 v[38:41], v[176:179], v[202:205], v[38:41]
	v_mfma_f32_16x16x32_bf16 v[34:37], v[186:189], v[202:205], v[34:37]
	v_mfma_f32_16x16x32_bf16 v[22:25], v[176:179], v[210:213], v[22:25]
	v_mfma_f32_16x16x32_bf16 v[18:21], v[186:189], v[210:213], v[18:21]
	v_mfma_f32_16x16x32_bf16 v[6:9], v[176:179], v[218:221], v[6:9]
	v_mfma_f32_16x16x32_bf16 v[2:5], v[186:189], v[218:221], v[2:5]
	s_barrier
; #define PG8_STAGE(bufoff, gbase, voff) do { _Pragma("unroll") for (int _i = 0; _i < 2; ++_i) \
;         __builtin_amdgcn_global_load_lds((const unsigned*)((const char*)(gbase) + (voff)[_i]), (PG8_LAS unsigned*)(lds + (bufoff) + ldsw + _i * 8192), 16, 0, 0); } while (0)
; #define PG8_LDA(dst, b, h) do { _Pragma("unroll") for (int m = 0; m < 4; ++m) _Pragma("unroll") for (int k = 0; k < 2; ++k) dst[m][k] = *(const PG8_LAS bf16x8*)(lds + PG8_SA(b, h) + aoff + m * 2048 + k * 1024); } while (0)
; #define PG8_LDB(dst, b, h) do { _Pragma("unroll") for (int n = 0; n < 2; ++n) _Pragma("unroll") for (int k = 0; k < 2; ++k) dst[n][k] = *(const PG8_LAS bf16x8*)(lds + PG8_SB(b, h) + boff + n * 2048 + k * 1024); } while (0)
; #define PG8_MMA(ai, bj, At, Bt) do { __builtin_amdgcn_s_setprio(1); _Pragma("unroll") for (int m = 0; m < 4; ++m) _Pragma("unroll") for (int n = 0; n < 2; ++n) _Pragma("unroll") for (int k = 0; k < 2; ++k) \
;         acc[ai][bj][m][n] = __builtin_amdgcn_mfma_f32_16x16x32_bf16(Bt[n][k], At[m][k], acc[ai][bj][m][n], 0, 0, 0); __builtin_amdgcn_s_setprio(0); } while (0)
; #define PG8_WAIT_V(n) asm volatile("s_waitcnt vmcnt(" #n ")" ::: "memory")
; #define PG8_WAIT_L(n) asm volatile("s_waitcnt lgkmcnt(" #n ")" ::: "memory")
; #define PG8_BAR __builtin_amdgcn_s_barrier()
; #define PG8_SCHED __builtin_amdgcn_sched_barrier(0)
; template <class Epi, class Sched, bool ALIGN_EPI = false, bool SP2 = false>
; __device__ __forceinline__ void gemm_phase(PG8_LAS unsigned char* lds, const Gemm g, const Sched& S, const Epi& E) {
;     ...
;             PG8_LDB(B0, 1, 0); PG8_LDB(B1, 1, 1); PG8_SCHED; PG8_LDA(At, 1, 0); PG8_STAGE(PG8_SA(0, 1), a2 + hstep, voffA);
;             PG8_WAIT_V(8); PG8_WAIT_L(0); PG8_BAR; PG8_MMA(0, 0, At, B0); PG8_MMA(0, 1, At, B1); PG8_BAR; PG8_SCHED;
;             PG8_LDA(At, 1, 1); PG8_STAGE(PG8_SB(1, 0), b3, voffB); PG8_STAGE(PG8_SB(1, 1), b3 + hstep, voffB); PG8_STAGE(PG8_SA(1, 0), a3, voffA);
;             PG8_WAIT_V(8); PG8_WAIT_L(0); PG8_BAR; PG8_MMA(1, 0, At, B0); PG8_MMA(1, 1, At, B1); PG8_BAR; PG8_SCHED;
	s_add_i32 s33, 0, 0x18000
	v_add_u32_e32 v159, s33, v150
	s_add_i32 s72, 0, 0x1c000
	ds_read_b128 v[144:147], v159
	ds_read_b128 v[160:163], v159 offset:1024
	ds_read_b128 v[164:167], v159 offset:2048
	ds_read_b128 v[168:171], v159 offset:3072
	v_add_u32_e32 v159, s72, v150
	ds_read_b128 v[172:175], v159
	ds_read_b128 v[176:179], v159 offset:1024
	ds_read_b128 v[182:185], v159 offset:2048
	ds_read_b128 v[186:189], v159 offset:3072
	s_add_u32 s6, s36, s16
	s_addc_u32 s7, s37, s17
	s_mov_b32 m0, s48
	ds_read_b128 v[190:193], v158 offset:32768
	ds_read_b128 v[194:197], v158 offset:33792
	ds_read_b128 v[198:201], v158 offset:34816
	ds_read_b128 v[202:205], v158 offset:35840
	ds_read_b128 v[206:209], v158 offset:36864
	ds_read_b128 v[210:213], v158 offset:37888
	ds_read_b128 v[214:217], v158 offset:38912
	ds_read_b128 v[218:221], v158 offset:39936
	global_load_lds_dwordx4 v136, s[6:7]
	s_mov_b32 m0, s49
	s_nop 0
	global_load_lds_dwordx4 v132, s[6:7]
	s_waitcnt vmcnt(8)
	s_waitcnt lgkmcnt(0)
	s_barrier
	s_waitcnt lgkmcnt(0)
	v_mfma_f32_16x16x32_bf16 v[122:125], v[144:147], v[190:193], v[122:125]
	v_mfma_f32_16x16x32_bf16 v[126:129], v[164:167], v[190:193], v[126:129]
	v_mfma_f32_16x16x32_bf16 v[110:113], v[144:147], v[198:201], v[110:113]
	v_mfma_f32_16x16x32_bf16 v[106:109], v[164:167], v[198:201], v[106:109]
	v_mfma_f32_16x16x32_bf16 v[94:97], v[144:147], v[206:209], v[94:97]
	v_mfma_f32_16x16x32_bf16 v[90:93], v[164:167], v[206:209], v[90:93]
	v_mfma_f32_16x16x32_bf16 v[78:81], v[144:147], v[214:217], v[78:81]
	v_mfma_f32_16x16x32_bf16 v[74:77], v[164:167], v[214:217], v[74:77]
	v_mfma_f32_16x16x32_bf16 v[122:125], v[160:163], v[194:197], v[122:125]
	v_mfma_f32_16x16x32_bf16 v[126:129], v[168:171], v[194:197], v[126:129]
	v_mfma_f32_16x16x32_bf16 v[110:113], v[160:163], v[202:205], v[110:113]
	v_mfma_f32_16x16x32_bf16 v[106:109], v[168:171], v[202:205], v[106:109]
	v_mfma_f32_16x16x32_bf16 v[94:97], v[160:163], v[210:213], v[94:97]
	v_mfma_f32_16x16x32_bf16 v[90:93], v[168:171], v[210:213], v[90:93]
	v_mfma_f32_16x16x32_bf16 v[78:81], v[160:163], v[218:221], v[78:81]
	v_mfma_f32_16x16x32_bf16 v[74:77], v[168:171], v[218:221], v[74:77]
	v_mfma_f32_16x16x32_bf16 v[118:121], v[172:175], v[190:193], v[118:121]
	v_mfma_f32_16x16x32_bf16 v[114:117], v[182:185], v[190:193], v[114:117]
	v_mfma_f32_16x16x32_bf16 v[102:105], v[172:175], v[198:201], v[102:105]
	v_mfma_f32_16x16x32_bf16 v[98:101], v[182:185], v[198:201], v[98:101]
	v_mfma_f32_16x16x32_bf16 v[86:89], v[172:175], v[206:209], v[86:89]
	v_mfma_f32_16x16x32_bf16 v[82:85], v[182:185], v[206:209], v[82:85]
	v_mfma_f32_16x16x32_bf16 v[70:73], v[172:175], v[214:217], v[70:73]
	v_mfma_f32_16x16x32_bf16 v[66:69], v[182:185], v[214:217], v[66:69]
	v_mfma_f32_16x16x32_bf16 v[118:121], v[176:179], v[194:197], v[118:121]
	v_mfma_f32_16x16x32_bf16 v[114:117], v[186:189], v[194:197], v[114:117]
	v_mfma_f32_16x16x32_bf16 v[102:105], v[176:179], v[202:205], v[102:105]
	v_mfma_f32_16x16x32_bf16 v[98:101], v[186:189], v[202:205], v[98:101]
	v_mfma_f32_16x16x32_bf16 v[86:89], v[176:179], v[210:213], v[86:89]
	v_mfma_f32_16x16x32_bf16 v[82:85], v[186:189], v[210:213], v[82:85]
	v_mfma_f32_16x16x32_bf16 v[70:73], v[176:179], v[218:221], v[70:73]
	v_mfma_f32_16x16x32_bf16 v[66:69], v[186:189], v[218:221], v[66:69]
	s_barrier
	s_add_i32 s6, s33, s40
	s_mov_b32 m0, s6
	ds_read_b128 v[190:193], v158 offset:49152
	ds_read_b128 v[194:197], v158 offset:50176
	ds_read_b128 v[198:201], v158 offset:51200
	ds_read_b128 v[202:205], v158 offset:52224
	ds_read_b128 v[206:209], v158 offset:53248
	ds_read_b128 v[210:213], v158 offset:54272
	ds_read_b128 v[214:217], v158 offset:55296
	ds_read_b128 v[218:221], v158 offset:56320
	global_load_lds_dwordx4 v134, s[100:101]
	s_add_i32 m0, s6, 0x2000
	s_add_i32 s6, s72, s40
	global_load_lds_dwordx4 v130, s[100:101]
	s_add_u32 s100, s100, s16
	s_addc_u32 s101, s101, s17
	s_mov_b32 m0, s6
	s_nop 0
	global_load_lds_dwordx4 v134, s[100:101]
	s_add_i32 m0, s6, 0x2000
	s_nop 0
	global_load_lds_dwordx4 v130, s[100:101]
	s_add_u32 s100, s36, 0x80
	s_addc_u32 s101, s37, 0
	s_mov_b32 m0, s51
	s_nop 0
	global_load_lds_dwordx4 v136, s[100:101]
	s_mov_b32 m0, s54
	s_nop 0
	global_load_lds_dwordx4 v132, s[100:101]
	s_waitcnt vmcnt(8)
	s_waitcnt lgkmcnt(0)
	s_barrier
	s_waitcnt lgkmcnt(0)
	v_mfma_f32_16x16x32_bf16 v[62:65], v[144:147], v[190:193], v[62:65]
	v_mfma_f32_16x16x32_bf16 v[58:61], v[164:167], v[190:193], v[58:61]
	v_mfma_f32_16x16x32_bf16 v[46:49], v[144:147], v[198:201], v[46:49]
	v_mfma_f32_16x16x32_bf16 v[42:45], v[164:167], v[198:201], v[42:45]
	v_mfma_f32_16x16x32_bf16 v[30:33], v[144:147], v[206:209], v[30:33]
	v_mfma_f32_16x16x32_bf16 v[26:29], v[164:167], v[206:209], v[26:29]
	v_mfma_f32_16x16x32_bf16 v[14:17], v[144:147], v[214:217], v[14:17]
	v_mfma_f32_16x16x32_bf16 v[10:13], v[164:167], v[214:217], v[10:13]
	v_mfma_f32_16x16x32_bf16 v[62:65], v[160:163], v[194:197], v[62:65]
	v_mfma_f32_16x16x32_bf16 v[58:61], v[168:171], v[194:197], v[58:61]
	v_mfma_f32_16x16x32_bf16 v[46:49], v[160:163], v[202:205], v[46:49]
	v_mfma_f32_16x16x32_bf16 v[42:45], v[168:171], v[202:205], v[42:45]
	v_mfma_f32_16x16x32_bf16 v[30:33], v[160:163], v[210:213], v[30:33]
	v_mfma_f32_16x16x32_bf16 v[26:29], v[168:171], v[210:213], v[26:29]
	v_mfma_f32_16x16x32_bf16 v[14:17], v[160:163], v[218:221], v[14:17]
	v_mfma_f32_16x16x32_bf16 v[10:13], v[168:171], v[218:221], v[10:13]
	v_mfma_f32_16x16x32_bf16 v[54:57], v[172:175], v[190:193], v[54:57]
	v_mfma_f32_16x16x32_bf16 v[50:53], v[182:185], v[190:193], v[50:53]
	v_mfma_f32_16x16x32_bf16 v[38:41], v[172:175], v[198:201], v[38:41]
	v_mfma_f32_16x16x32_bf16 v[34:37], v[182:185], v[198:201], v[34:37]
	v_mfma_f32_16x16x32_bf16 v[22:25], v[172:175], v[206:209], v[22:25]
	v_mfma_f32_16x16x32_bf16 v[18:21], v[182:185], v[206:209], v[18:21]
	v_mfma_f32_16x16x32_bf16 v[6:9], v[172:175], v[214:217], v[6:9]
	v_mfma_f32_16x16x32_bf16 v[2:5], v[182:185], v[214:217], v[2:5]
	v_mfma_f32_16x16x32_bf16 v[54:57], v[176:179], v[194:197], v[54:57]
	v_mfma_f32_16x16x32_bf16 v[50:53], v[186:189], v[194:197], v[50:53]
	v_mfma_f32_16x16x32_bf16 v[38:41], v[176:179], v[202:205], v[38:41]
	v_mfma_f32_16x16x32_bf16 v[34:37], v[186:189], v[202:205], v[34:37]
	v_mfma_f32_16x16x32_bf16 v[22:25], v[176:179], v[210:213], v[22:25]
	v_mfma_f32_16x16x32_bf16 v[18:21], v[186:189], v[210:213], v[18:21]
	v_mfma_f32_16x16x32_bf16 v[6:9], v[176:179], v[218:221], v[6:9]
	v_mfma_f32_16x16x32_bf16 v[2:5], v[186:189], v[218:221], v[2:5]
	s_barrier
	s_add_u32 s34, s34, 0x100
	s_addc_u32 s35, s35, 0
	s_add_u32 s67, s67, 0x100
	s_addc_u32 s79, s79, 0
	s_cmp_ge_i32 s59, s50
	s_mov_b32 s33, s59
	s_cbranch_scc0 .LBB0_406

; #define PG8_STAGE(bufoff, gbase, voff) do { _Pragma("unroll") for (int _i = 0; _i < 2; ++_i) \
;         __builtin_amdgcn_global_load_lds((const unsigned*)((const char*)(gbase) + (voff)[_i]), (PG8_LAS unsigned*)(lds + (bufoff) + ldsw + _i * 8192), 16, 0, 0); } while (0)
; #define PG8_LDA(dst, b, h) do { _Pragma("unroll") for (int m = 0; m < 4; ++m) _Pragma("unroll") for (int k = 0; k < 2; ++k) dst[m][k] = *(const PG8_LAS bf16x8*)(lds + PG8_SA(b, h) + aoff + m * 2048 + k * 1024); } while (0)
; #define PG8_LDB(dst, b, h) do { _Pragma("unroll") for (int n = 0; n < 2; ++n) _Pragma("unroll") for (int k = 0; k < 2; ++k) dst[n][k] = *(const PG8_LAS bf16x8*)(lds + PG8_SB(b, h) + boff + n * 2048 + k * 1024); } while (0)
; #define PG8_MMA(ai, bj, At, Bt) do { __builtin_amdgcn_s_setprio(1); _Pragma("unroll") for (int m = 0; m < 4; ++m) _Pragma("unroll") for (int n = 0; n < 2; ++n) _Pragma("unroll") for (int k = 0; k < 2; ++k) \
;         acc[ai][bj][m][n] = __builtin_amdgcn_mfma_f32_16x16x32_bf16(Bt[n][k], At[m][k], acc[ai][bj][m][n], 0, 0, 0); __builtin_amdgcn_s_setprio(0); } while (0)
; #define PG8_WAIT_V(n) asm volatile("s_waitcnt vmcnt(" #n ")" ::: "memory")
; #define PG8_WAIT_L(n) asm volatile("s_waitcnt lgkmcnt(" #n ")" ::: "memory")
; template <class Epi, class Sched, bool ALIGN_EPI = false, bool SP2 = false>
; __device__ __forceinline__ void gemm_phase(PG8_LAS unsigned char* lds, const Gemm g, const Sched& S, const Epi& E) {
;     ...
;             const bool last = (t == nt - 2);
;             const char* a1 = cA + (size_t)(t + 1) * kstep;
;             const char* a2 = last ? nA : cA + (size_t)(t + 2) * kstep; const char* b2 = last ? nB : cB + (size_t)(t + 2) * kstep;
;             const char* a3 = a2 + kstep; const char* b3 = b2 + kstep;
;             if (last && has_next) S.a_ready(nxt);
;             if constexpr (SP2) {
;             PG8_LDB(B0, 0, 0); PG8_LDB(B1, 0, 1); PG8_SCHED; PG8_LDA(At, 0, 0); PG8_STAGE(PG8_SA(1, 1), a1 + hstep, voffA);
;             PG8_WAIT_V(8); PG8_WAIT_L(0); PG8_BAR; PG8_MMA(0, 0, At, B0); PG8_MMA(0, 1, At, B1); PG8_BAR; PG8_SCHED;
;             PG8_LDA(At, 0, 1); PG8_STAGE(PG8_SB(0, 0), b2, voffB); PG8_STAGE(PG8_SB(0, 1), b2 + hstep, voffB); PG8_STAGE(PG8_SA(0, 0), a2, voffA);
;             PG8_WAIT_V(8); PG8_WAIT_L(0); PG8_BAR; PG8_MMA(1, 0, At, B0); PG8_MMA(1, 1, At, B1); PG8_BAR; PG8_SCHED;
.LBB0_592:
	s_add_i32 s59, s33, 2
	s_add_u32 s6, s30, 0x80
	s_addc_u32 s7, s31, 0
	s_add_i32 s67, 0, 0x10000
	s_cmp_eq_u32 s56, s33
	s_cselect_b32 s35, s11, s7
	s_cselect_b32 s34, s10, s6
	v_add_u32_e32 v147, s67, v144
	s_cselect_b32 s7, s29, s66
	s_cselect_b32 s6, s28, s65
	s_add_i32 s33, 0, 0x14000
	ds_read_b128 v[148:151], v147
	ds_read_b128 v[158:161], v147 offset:1024
	ds_read_b128 v[162:165], v147 offset:2048
	ds_read_b128 v[166:169], v147 offset:3072
	v_add_u32_e32 v147, s33, v144
	ds_read_b128 v[170:173], v147
	ds_read_b128 v[174:177], v147 offset:1024
	ds_read_b128 v[182:185], v147 offset:2048
	ds_read_b128 v[186:189], v147 offset:3072
	s_add_i32 m0, s44, 0xc000
	ds_read_b128 v[190:193], v146
	ds_read_b128 v[194:197], v146 offset:1024
	ds_read_b128 v[198:201], v146 offset:2048
	ds_read_b128 v[202:205], v146 offset:3072
	ds_read_b128 v[206:209], v146 offset:4096
	ds_read_b128 v[210:213], v146 offset:5120
	ds_read_b128 v[214:217], v146 offset:6144
	ds_read_b128 v[218:221], v146 offset:7168
	global_load_lds_dwordx4 v140, s[30:31]
	s_add_i32 m0, s44, 0xe000
	s_nop 0
	global_load_lds_dwordx4 v142, s[30:31]
	s_waitcnt vmcnt(8)
	s_waitcnt lgkmcnt(0)
	s_barrier
	s_waitcnt lgkmcnt(0)
	v_mfma_f32_16x16x32_bf16 v[122:125], v[148:151], v[190:193], v[122:125]
	v_mfma_f32_16x16x32_bf16 v[126:129], v[162:165], v[190:193], v[126:129]
	v_mfma_f32_16x16x32_bf16 v[110:113], v[148:151], v[198:201], v[110:113]
	v_mfma_f32_16x16x32_bf16 v[106:109], v[162:165], v[198:201], v[106:109]
	v_mfma_f32_16x16x32_bf16 v[94:97], v[148:151], v[206:209], v[94:97]
	v_mfma_f32_16x16x32_bf16 v[90:93], v[162:165], v[206:209], v[90:93]
	v_mfma_f32_16x16x32_bf16 v[78:81], v[148:151], v[214:217], v[78:81]
	v_mfma_f32_16x16x32_bf16 v[74:77], v[162:165], v[214:217], v[74:77]
	v_mfma_f32_16x16x32_bf16 v[122:125], v[158:161], v[194:197], v[122:125]
	v_mfma_f32_16x16x32_bf16 v[126:129], v[166:169], v[194:197], v[126:129]
	v_mfma_f32_16x16x32_bf16 v[110:113], v[158:161], v[202:205], v[110:113]
	v_mfma_f32_16x16x32_bf16 v[106:109], v[166:169], v[202:205], v[106:109]
	v_mfma_f32_16x16x32_bf16 v[94:97], v[158:161], v[210:213], v[94:97]
	v_mfma_f32_16x16x32_bf16 v[90:93], v[166:169], v[210:213], v[90:93]
	v_mfma_f32_16x16x32_bf16 v[78:81], v[158:161], v[218:221], v[78:81]
	v_mfma_f32_16x16x32_bf16 v[74:77], v[166:169], v[218:221], v[74:77]
	v_mfma_f32_16x16x32_bf16 v[118:121], v[170:173], v[190:193], v[118:121]
	v_mfma_f32_16x16x32_bf16 v[114:117], v[182:185], v[190:193], v[114:117]
	v_mfma_f32_16x16x32_bf16 v[102:105], v[170:173], v[198:201], v[102:105]
	v_mfma_f32_16x16x32_bf16 v[98:101], v[182:185], v[198:201], v[98:101]
	v_mfma_f32_16x16x32_bf16 v[86:89], v[170:173], v[206:209], v[86:89]
	v_mfma_f32_16x16x32_bf16 v[82:85], v[182:185], v[206:209], v[82:85]
	v_mfma_f32_16x16x32_bf16 v[70:73], v[170:173], v[214:217], v[70:73]
	v_mfma_f32_16x16x32_bf16 v[66:69], v[182:185], v[214:217], v[66:69]
	v_mfma_f32_16x16x32_bf16 v[118:121], v[174:177], v[194:197], v[118:121]
	v_mfma_f32_16x16x32_bf16 v[114:117], v[186:189], v[194:197], v[114:117]
	v_mfma_f32_16x16x32_bf16 v[102:105], v[174:177], v[202:205], v[102:105]
	v_mfma_f32_16x16x32_bf16 v[98:101], v[186:189], v[202:205], v[98:101]
	v_mfma_f32_16x16x32_bf16 v[86:89], v[174:177], v[210:213], v[86:89]
	v_mfma_f32_16x16x32_bf16 v[82:85], v[186:189], v[210:213], v[82:85]
	v_mfma_f32_16x16x32_bf16 v[70:73], v[174:177], v[218:221], v[70:73]
	v_mfma_f32_16x16x32_bf16 v[66:69], v[186:189], v[218:221], v[66:69]
	s_barrier
	s_add_i32 s67, s67, s38
	s_mov_b32 m0, s67
	ds_read_b128 v[190:193], v146 offset:16384
	ds_read_b128 v[194:197], v146 offset:17408
	ds_read_b128 v[198:201], v146 offset:18432
	ds_read_b128 v[202:205], v146 offset:19456
	ds_read_b128 v[206:209], v146 offset:20480
	ds_read_b128 v[210:213], v146 offset:21504
	ds_read_b128 v[214:217], v146 offset:22528
	ds_read_b128 v[218:221], v146 offset:23552
	global_load_lds_dwordx4 v134, s[6:7]
	s_add_i32 m0, s67, 0x2000
	s_add_u32 s100, s6, 0x80
	s_addc_u32 s101, s7, 0
	global_load_lds_dwordx4 v130, s[6:7]
	s_add_u32 s6, s6, s16
	s_addc_u32 s7, s7, s17
	s_add_i32 s33, s33, s38
	s_mov_b32 m0, s33
	s_nop 0
	global_load_lds_dwordx4 v134, s[6:7]
	s_add_i32 m0, s33, 0x2000
	s_nop 0
	global_load_lds_dwordx4 v130, s[6:7]
	s_mov_b32 m0, s44
	s_nop 0
	global_load_lds_dwordx4 v136, s[34:35]
	s_mov_b32 m0, s45
	s_nop 0
	global_load_lds_dwordx4 v132, s[34:35]
	s_waitcnt vmcnt(8)
	s_waitcnt lgkmcnt(0)
	s_barrier
	s_waitcnt lgkmcnt(0)
	v_mfma_f32_16x16x32_bf16 v[62:65], v[148:151], v[190:193], v[62:65]
	v_mfma_f32_16x16x32_bf16 v[58:61], v[162:165], v[190:193], v[58:61]
	v_mfma_f32_16x16x32_bf16 v[46:49], v[148:151], v[198:201], v[46:49]
	v_mfma_f32_16x16x32_bf16 v[42:45], v[162:165], v[198:201], v[42:45]
	v_mfma_f32_16x16x32_bf16 v[30:33], v[148:151], v[206:209], v[30:33]
	v_mfma_f32_16x16x32_bf16 v[26:29], v[162:165], v[206:209], v[26:29]
	v_mfma_f32_16x16x32_bf16 v[14:17], v[148:151], v[214:217], v[14:17]
	v_mfma_f32_16x16x32_bf16 v[10:13], v[162:165], v[214:217], v[10:13]
	v_mfma_f32_16x16x32_bf16 v[62:65], v[158:161], v[194:197], v[62:65]
	v_mfma_f32_16x16x32_bf16 v[58:61], v[166:169], v[194:197], v[58:61]
	v_mfma_f32_16x16x32_bf16 v[46:49], v[158:161], v[202:205], v[46:49]
	v_mfma_f32_16x16x32_bf16 v[42:45], v[166:169], v[202:205], v[42:45]
	v_mfma_f32_16x16x32_bf16 v[30:33], v[158:161], v[210:213], v[30:33]
	v_mfma_f32_16x16x32_bf16 v[26:29], v[166:169], v[210:213], v[26:29]
	v_mfma_f32_16x16x32_bf16 v[14:17], v[158:161], v[218:221], v[14:17]
	v_mfma_f32_16x16x32_bf16 v[10:13], v[166:169], v[218:221], v[10:13]
	v_mfma_f32_16x16x32_bf16 v[54:57], v[170:173], v[190:193], v[54:57]
	v_mfma_f32_16x16x32_bf16 v[50:53], v[182:185], v[190:193], v[50:53]
	v_mfma_f32_16x16x32_bf16 v[38:41], v[170:173], v[198:201], v[38:41]
	v_mfma_f32_16x16x32_bf16 v[34:37], v[182:185], v[198:201], v[34:37]
	v_mfma_f32_16x16x32_bf16 v[22:25], v[170:173], v[206:209], v[22:25]
	v_mfma_f32_16x16x32_bf16 v[18:21], v[182:185], v[206:209], v[18:21]
	v_mfma_f32_16x16x32_bf16 v[6:9], v[170:173], v[214:217], v[6:9]
	v_mfma_f32_16x16x32_bf16 v[2:5], v[182:185], v[214:217], v[2:5]
	v_mfma_f32_16x16x32_bf16 v[54:57], v[174:177], v[194:197], v[54:57]
	v_mfma_f32_16x16x32_bf16 v[50:53], v[186:189], v[194:197], v[50:53]
	v_mfma_f32_16x16x32_bf16 v[38:41], v[174:177], v[202:205], v[38:41]
	v_mfma_f32_16x16x32_bf16 v[34:37], v[186:189], v[202:205], v[34:37]
	v_mfma_f32_16x16x32_bf16 v[22:25], v[174:177], v[210:213], v[22:25]
	v_mfma_f32_16x16x32_bf16 v[18:21], v[186:189], v[210:213], v[18:21]
	v_mfma_f32_16x16x32_bf16 v[6:9], v[174:177], v[218:221], v[6:9]
	v_mfma_f32_16x16x32_bf16 v[2:5], v[186:189], v[218:221], v[2:5]
	s_barrier
; #define PG8_STAGE(bufoff, gbase, voff) do { _Pragma("unroll") for (int _i = 0; _i < 2; ++_i) \
;         __builtin_amdgcn_global_load_lds((const unsigned*)((const char*)(gbase) + (voff)[_i]), (PG8_LAS unsigned*)(lds + (bufoff) + ldsw + _i * 8192), 16, 0, 0); } while (0)
; #define PG8_LDA(dst, b, h) do { _Pragma("unroll") for (int m = 0; m < 4; ++m) _Pragma("unroll") for (int k = 0; k < 2; ++k) dst[m][k] = *(const PG8_LAS bf16x8*)(lds + PG8_SA(b, h) + aoff + m * 2048 + k * 1024); } while (0)
; #define PG8_LDB(dst, b, h) do { _Pragma("unroll") for (int n = 0; n < 2; ++n) _Pragma("unroll") for (int k = 0; k < 2; ++k) dst[n][k] = *(const PG8_LAS bf16x8*)(lds + PG8_SB(b, h) + boff + n * 2048 + k * 1024); } while (0)
; #define PG8_MMA(ai, bj, At, Bt) do { __builtin_amdgcn_s_setprio(1); _Pragma("unroll") for (int m = 0; m < 4; ++m) _Pragma("unroll") for (int n = 0; n < 2; ++n) _Pragma("unroll") for (int k = 0; k < 2; ++k) \
;         acc[ai][bj][m][n] = __builtin_amdgcn_mfma_f32_16x16x32_bf16(Bt[n][k], At[m][k], acc[ai][bj][m][n], 0, 0, 0); __builtin_amdgcn_s_setprio(0); } while (0)
; #define PG8_WAIT_V(n) asm volatile("s_waitcnt vmcnt(" #n ")" ::: "memory")
; #define PG8_WAIT_L(n) asm volatile("s_waitcnt lgkmcnt(" #n ")" ::: "memory")
; #define PG8_BAR __builtin_amdgcn_s_barrier()
; #define PG8_SCHED __builtin_amdgcn_sched_barrier(0)
; template <class Epi, class Sched, bool ALIGN_EPI = false, bool SP2 = false>
; __device__ __forceinline__ void gemm_phase(PG8_LAS unsigned char* lds, const Gemm g, const Sched& S, const Epi& E) {
;     ...
;             PG8_LDB(B0, 1, 0); PG8_LDB(B1, 1, 1); PG8_SCHED; PG8_LDA(At, 1, 0); PG8_STAGE(PG8_SA(0, 1), a2 + hstep, voffA);
;             PG8_WAIT_V(8); PG8_WAIT_L(0); PG8_BAR; PG8_MMA(0, 0, At, B0); PG8_MMA(0, 1, At, B1); PG8_BAR; PG8_SCHED;
;             PG8_LDA(At, 1, 1); PG8_STAGE(PG8_SB(1, 0), b3, voffB); PG8_STAGE(PG8_SB(1, 1), b3 + hstep, voffB); PG8_STAGE(PG8_SA(1, 0), a3, voffA);
;             PG8_WAIT_V(8); PG8_WAIT_L(0); PG8_BAR; PG8_MMA(1, 0, At, B0); PG8_MMA(1, 1, At, B1); PG8_BAR; PG8_SCHED;
	s_add_i32 s33, 0, 0x18000
	v_add_u32_e32 v147, s33, v144
	s_add_i32 s67, 0, 0x1c000
	ds_read_b128 v[148:151], v147
	ds_read_b128 v[158:161], v147 offset:1024
	ds_read_b128 v[162:165], v147 offset:2048
	ds_read_b128 v[166:169], v147 offset:3072
	v_add_u32_e32 v147, s67, v144
	ds_read_b128 v[170:173], v147
	ds_read_b128 v[174:177], v147 offset:1024
	ds_read_b128 v[182:185], v147 offset:2048
	ds_read_b128 v[186:189], v147 offset:3072
	s_add_u32 s6, s34, s16
	s_addc_u32 s7, s35, s17
	s_mov_b32 m0, s46
	ds_read_b128 v[190:193], v146 offset:32768
	ds_read_b128 v[194:197], v146 offset:33792
	ds_read_b128 v[198:201], v146 offset:34816
	ds_read_b128 v[202:205], v146 offset:35840
	ds_read_b128 v[206:209], v146 offset:36864
	ds_read_b128 v[210:213], v146 offset:37888
	ds_read_b128 v[214:217], v146 offset:38912
	ds_read_b128 v[218:221], v146 offset:39936
	global_load_lds_dwordx4 v136, s[6:7]
	s_mov_b32 m0, s47
	s_nop 0
	global_load_lds_dwordx4 v132, s[6:7]
	s_waitcnt vmcnt(8)
	s_waitcnt lgkmcnt(0)
	s_barrier
	s_waitcnt lgkmcnt(0)
	v_mfma_f32_16x16x32_bf16 v[122:125], v[148:151], v[190:193], v[122:125]
	v_mfma_f32_16x16x32_bf16 v[126:129], v[162:165], v[190:193], v[126:129]
	v_mfma_f32_16x16x32_bf16 v[110:113], v[148:151], v[198:201], v[110:113]
	v_mfma_f32_16x16x32_bf16 v[106:109], v[162:165], v[198:201], v[106:109]
	v_mfma_f32_16x16x32_bf16 v[94:97], v[148:151], v[206:209], v[94:97]
	v_mfma_f32_16x16x32_bf16 v[90:93], v[162:165], v[206:209], v[90:93]
	v_mfma_f32_16x16x32_bf16 v[78:81], v[148:151], v[214:217], v[78:81]
	v_mfma_f32_16x16x32_bf16 v[74:77], v[162:165], v[214:217], v[74:77]
	v_mfma_f32_16x16x32_bf16 v[122:125], v[158:161], v[194:197], v[122:125]
	v_mfma_f32_16x16x32_bf16 v[126:129], v[166:169], v[194:197], v[126:129]
	v_mfma_f32_16x16x32_bf16 v[110:113], v[158:161], v[202:205], v[110:113]
	v_mfma_f32_16x16x32_bf16 v[106:109], v[166:169], v[202:205], v[106:109]
	v_mfma_f32_16x16x32_bf16 v[94:97], v[158:161], v[210:213], v[94:97]
	v_mfma_f32_16x16x32_bf16 v[90:93], v[166:169], v[210:213], v[90:93]
	v_mfma_f32_16x16x32_bf16 v[78:81], v[158:161], v[218:221], v[78:81]
	v_mfma_f32_16x16x32_bf16 v[74:77], v[166:169], v[218:221], v[74:77]
	v_mfma_f32_16x16x32_bf16 v[118:121], v[170:173], v[190:193], v[118:121]
	v_mfma_f32_16x16x32_bf16 v[114:117], v[182:185], v[190:193], v[114:117]
	v_mfma_f32_16x16x32_bf16 v[102:105], v[170:173], v[198:201], v[102:105]
	v_mfma_f32_16x16x32_bf16 v[98:101], v[182:185], v[198:201], v[98:101]
	v_mfma_f32_16x16x32_bf16 v[86:89], v[170:173], v[206:209], v[86:89]
	v_mfma_f32_16x16x32_bf16 v[82:85], v[182:185], v[206:209], v[82:85]
	v_mfma_f32_16x16x32_bf16 v[70:73], v[170:173], v[214:217], v[70:73]
	v_mfma_f32_16x16x32_bf16 v[66:69], v[182:185], v[214:217], v[66:69]
	v_mfma_f32_16x16x32_bf16 v[118:121], v[174:177], v[194:197], v[118:121]
	v_mfma_f32_16x16x32_bf16 v[114:117], v[186:189], v[194:197], v[114:117]
	v_mfma_f32_16x16x32_bf16 v[102:105], v[174:177], v[202:205], v[102:105]
	v_mfma_f32_16x16x32_bf16 v[98:101], v[186:189], v[202:205], v[98:101]
	v_mfma_f32_16x16x32_bf16 v[86:89], v[174:177], v[210:213], v[86:89]
	v_mfma_f32_16x16x32_bf16 v[82:85], v[186:189], v[210:213], v[82:85]
	v_mfma_f32_16x16x32_bf16 v[70:73], v[174:177], v[218:221], v[70:73]
	v_mfma_f32_16x16x32_bf16 v[66:69], v[186:189], v[218:221], v[66:69]
	s_barrier
	s_add_i32 s6, s33, s38
	s_mov_b32 m0, s6
	ds_read_b128 v[190:193], v146 offset:49152
	ds_read_b128 v[194:197], v146 offset:50176
	ds_read_b128 v[198:201], v146 offset:51200
	ds_read_b128 v[202:205], v146 offset:52224
	ds_read_b128 v[206:209], v146 offset:53248
	ds_read_b128 v[210:213], v146 offset:54272
	ds_read_b128 v[214:217], v146 offset:55296
	ds_read_b128 v[218:221], v146 offset:56320
	global_load_lds_dwordx4 v134, s[100:101]
	s_add_i32 m0, s6, 0x2000
	s_add_i32 s6, s67, s38
	global_load_lds_dwordx4 v130, s[100:101]
	s_add_u32 s100, s100, s16
	s_addc_u32 s101, s101, s17
	s_mov_b32 m0, s6
	s_nop 0
	global_load_lds_dwordx4 v134, s[100:101]
	s_add_i32 m0, s6, 0x2000
	s_nop 0
	global_load_lds_dwordx4 v130, s[100:101]
	s_add_u32 s100, s34, 0x80
	s_addc_u32 s101, s35, 0
	s_mov_b32 m0, s51
	s_nop 0
	global_load_lds_dwordx4 v136, s[100:101]
	s_mov_b32 m0, s54
	s_nop 0
	global_load_lds_dwordx4 v132, s[100:101]
	s_waitcnt vmcnt(8)
	s_waitcnt lgkmcnt(0)
	s_barrier
	s_waitcnt lgkmcnt(0)
	v_mfma_f32_16x16x32_bf16 v[62:65], v[148:151], v[190:193], v[62:65]
	v_mfma_f32_16x16x32_bf16 v[58:61], v[162:165], v[190:193], v[58:61]
	v_mfma_f32_16x16x32_bf16 v[46:49], v[148:151], v[198:201], v[46:49]
	v_mfma_f32_16x16x32_bf16 v[42:45], v[162:165], v[198:201], v[42:45]
	v_mfma_f32_16x16x32_bf16 v[30:33], v[148:151], v[206:209], v[30:33]
	v_mfma_f32_16x16x32_bf16 v[26:29], v[162:165], v[206:209], v[26:29]
	v_mfma_f32_16x16x32_bf16 v[14:17], v[148:151], v[214:217], v[14:17]
	v_mfma_f32_16x16x32_bf16 v[10:13], v[162:165], v[214:217], v[10:13]
	v_mfma_f32_16x16x32_bf16 v[62:65], v[158:161], v[194:197], v[62:65]
	v_mfma_f32_16x16x32_bf16 v[58:61], v[166:169], v[194:197], v[58:61]
	v_mfma_f32_16x16x32_bf16 v[46:49], v[158:161], v[202:205], v[46:49]
	v_mfma_f32_16x16x32_bf16 v[42:45], v[166:169], v[202:205], v[42:45]
	v_mfma_f32_16x16x32_bf16 v[30:33], v[158:161], v[210:213], v[30:33]
	v_mfma_f32_16x16x32_bf16 v[26:29], v[166:169], v[210:213], v[26:29]
	v_mfma_f32_16x16x32_bf16 v[14:17], v[158:161], v[218:221], v[14:17]
	v_mfma_f32_16x16x32_bf16 v[10:13], v[166:169], v[218:221], v[10:13]
	v_mfma_f32_16x16x32_bf16 v[54:57], v[170:173], v[190:193], v[54:57]
	v_mfma_f32_16x16x32_bf16 v[50:53], v[182:185], v[190:193], v[50:53]
	v_mfma_f32_16x16x32_bf16 v[38:41], v[170:173], v[198:201], v[38:41]
	v_mfma_f32_16x16x32_bf16 v[34:37], v[182:185], v[198:201], v[34:37]
	v_mfma_f32_16x16x32_bf16 v[22:25], v[170:173], v[206:209], v[22:25]
	v_mfma_f32_16x16x32_bf16 v[18:21], v[182:185], v[206:209], v[18:21]
	v_mfma_f32_16x16x32_bf16 v[6:9], v[170:173], v[214:217], v[6:9]
	v_mfma_f32_16x16x32_bf16 v[2:5], v[182:185], v[214:217], v[2:5]
	v_mfma_f32_16x16x32_bf16 v[54:57], v[174:177], v[194:197], v[54:57]
	v_mfma_f32_16x16x32_bf16 v[50:53], v[186:189], v[194:197], v[50:53]
	v_mfma_f32_16x16x32_bf16 v[38:41], v[174:177], v[202:205], v[38:41]
	v_mfma_f32_16x16x32_bf16 v[34:37], v[186:189], v[202:205], v[34:37]
	v_mfma_f32_16x16x32_bf16 v[22:25], v[174:177], v[210:213], v[22:25]
	v_mfma_f32_16x16x32_bf16 v[18:21], v[186:189], v[210:213], v[18:21]
	v_mfma_f32_16x16x32_bf16 v[6:9], v[174:177], v[218:221], v[6:9]
	v_mfma_f32_16x16x32_bf16 v[2:5], v[186:189], v[218:221], v[2:5]
	s_barrier
	s_add_u32 s30, s30, 0x100
	s_addc_u32 s31, s31, 0
	s_add_u32 s65, s65, 0x100
	s_addc_u32 s66, s66, 0
	s_cmp_ge_i32 s59, s48
	s_mov_b32 s33, s59
	s_cbranch_scc0 .LBB0_592
	s_movk_i32 s66, 0x700

; __device__ __forceinline__ void hyena_item(const Ctx& C, ArgsP a, int ly, int c, bf16_t* yout) {
;     ...
;                 if (d <= 15) HY_MMA(0)
.LBB0_859:
	v_add_co_u32_e32 v211, vcc, 64, v210
	s_nop 1
	v_cndmask_b32_e32 v211, 0, v211, vcc
	v_add_u32_e32 v211, s80, v211
	v_mad_u32_u24 v224, v211, s78, v108
	ds_read_b128 v[212:215], v224
	ds_read_b128 v[216:219], v224 offset:64
	ds_read_b128 v[220:223], v224 offset:128
	ds_read_b128 v[224:227], v224 offset:192
	s_cmp_eq_u64 vcc, exec
	s_cbranch_scc1 .Lhy_fast_859
	s_waitcnt lgkmcnt(3)
	v_cndmask_b32_e32 v215, 0, v215, vcc
	v_cndmask_b32_e32 v214, 0, v214, vcc
	v_cndmask_b32_e32 v213, 0, v213, vcc
	v_cndmask_b32_e32 v212, 0, v212, vcc
	s_nop 1
	v_mfma_f32_16x16x32_bf16 v[62:65], v[94:97], v[212:215], v[62:65]
	v_mfma_f32_16x16x32_bf16 v[58:61], v[90:93], v[212:215], v[58:61]
	v_mfma_f32_16x16x32_bf16 v[54:57], v[98:101], v[212:215], v[54:57]
	v_mfma_f32_16x16x32_bf16 v[50:53], v[102:105], v[212:215], v[50:53]
	s_waitcnt lgkmcnt(2)
	v_cndmask_b32_e32 v215, 0, v219, vcc
	v_cndmask_b32_e32 v214, 0, v218, vcc
	v_cndmask_b32_e32 v213, 0, v217, vcc
	v_cndmask_b32_e32 v212, 0, v216, vcc
	s_nop 1
	v_mfma_f32_16x16x32_bf16 v[62:65], v[82:85], v[212:215], v[62:65]
	v_mfma_f32_16x16x32_bf16 v[58:61], v[74:77], v[212:215], v[58:61]
	v_mfma_f32_16x16x32_bf16 v[54:57], v[94:97], v[212:215], v[54:57]
	v_mfma_f32_16x16x32_bf16 v[50:53], v[90:93], v[212:215], v[50:53]
	s_waitcnt lgkmcnt(1)
	v_cndmask_b32_e32 v215, 0, v223, vcc
	v_cndmask_b32_e32 v214, 0, v222, vcc
	v_cndmask_b32_e32 v213, 0, v221, vcc
	v_cndmask_b32_e32 v212, 0, v220, vcc
	s_nop 1
	v_mfma_f32_16x16x32_bf16 v[62:65], v[70:73], v[212:215], v[62:65]
	v_mfma_f32_16x16x32_bf16 v[58:61], v[66:69], v[212:215], v[58:61]
	v_mfma_f32_16x16x32_bf16 v[54:57], v[82:85], v[212:215], v[54:57]
	v_mfma_f32_16x16x32_bf16 v[50:53], v[74:77], v[212:215], v[50:53]
	s_waitcnt lgkmcnt(0)
	v_cndmask_b32_e32 v215, 0, v227, vcc
	v_cndmask_b32_e32 v214, 0, v226, vcc
	v_cndmask_b32_e32 v213, 0, v225, vcc
	v_cndmask_b32_e32 v212, 0, v224, vcc
	s_nop 1
	v_mfma_f32_16x16x32_bf16 v[62:65], v[86:89], v[212:215], v[62:65]
	v_mfma_f32_16x16x32_bf16 v[58:61], v[78:81], v[212:215], v[58:61]
	v_mfma_f32_16x16x32_bf16 v[54:57], v[70:73], v[212:215], v[54:57]
	v_mfma_f32_16x16x32_bf16 v[50:53], v[66:69], v[212:215], v[50:53]

; __device__ __forceinline__ void hyena_item(const Ctx& C, ArgsP a, int ly, int c, bf16_t* yout) {
;     ...
;                 if (d >= -47 && d <= 31) HY_MMA(1)
.LBB0_860:
	v_add_u32_e32 v211, 0x50, v210
	v_cmp_gt_u32_e32 vcc, 64, v211
	s_nop 1
	v_cndmask_b32_e32 v211, 0, v211, vcc
	v_add_u32_e32 v211, s80, v211
	v_mad_u32_u24 v224, v211, s78, v108
	ds_read_b128 v[212:215], v224
	ds_read_b128 v[216:219], v224 offset:64
	ds_read_b128 v[220:223], v224 offset:128
	ds_read_b128 v[224:227], v224 offset:192
	s_cmp_eq_u64 vcc, exec
	s_cbranch_scc1 .Lhy_fast_860
	s_waitcnt lgkmcnt(3)
	v_cndmask_b32_e32 v215, 0, v215, vcc
	v_cndmask_b32_e32 v214, 0, v214, vcc
	v_cndmask_b32_e32 v213, 0, v213, vcc
	v_cndmask_b32_e32 v212, 0, v212, vcc
	s_nop 1
	v_mfma_f32_16x16x32_bf16 v[46:49], v[94:97], v[212:215], v[46:49]
	v_mfma_f32_16x16x32_bf16 v[42:45], v[90:93], v[212:215], v[42:45]
	v_mfma_f32_16x16x32_bf16 v[38:41], v[98:101], v[212:215], v[38:41]
	v_mfma_f32_16x16x32_bf16 v[34:37], v[102:105], v[212:215], v[34:37]
	s_waitcnt lgkmcnt(2)
	v_cndmask_b32_e32 v215, 0, v219, vcc
	v_cndmask_b32_e32 v214, 0, v218, vcc
	v_cndmask_b32_e32 v213, 0, v217, vcc
	v_cndmask_b32_e32 v212, 0, v216, vcc
	s_nop 1
	v_mfma_f32_16x16x32_bf16 v[46:49], v[82:85], v[212:215], v[46:49]
	v_mfma_f32_16x16x32_bf16 v[42:45], v[74:77], v[212:215], v[42:45]
	v_mfma_f32_16x16x32_bf16 v[38:41], v[94:97], v[212:215], v[38:41]
	v_mfma_f32_16x16x32_bf16 v[34:37], v[90:93], v[212:215], v[34:37]
	s_waitcnt lgkmcnt(1)
	v_cndmask_b32_e32 v215, 0, v223, vcc
	v_cndmask_b32_e32 v214, 0, v222, vcc
	v_cndmask_b32_e32 v213, 0, v221, vcc
	v_cndmask_b32_e32 v212, 0, v220, vcc
	s_nop 1
	v_mfma_f32_16x16x32_bf16 v[46:49], v[70:73], v[212:215], v[46:49]
	v_mfma_f32_16x16x32_bf16 v[42:45], v[66:69], v[212:215], v[42:45]
	v_mfma_f32_16x16x32_bf16 v[38:41], v[82:85], v[212:215], v[38:41]
	v_mfma_f32_16x16x32_bf16 v[34:37], v[74:77], v[212:215], v[34:37]
	s_waitcnt lgkmcnt(0)
	v_cndmask_b32_e32 v215, 0, v227, vcc
	v_cndmask_b32_e32 v214, 0, v226, vcc
	v_cndmask_b32_e32 v213, 0, v225, vcc
	v_cndmask_b32_e32 v212, 0, v224, vcc
	s_nop 1
	v_mfma_f32_16x16x32_bf16 v[46:49], v[86:89], v[212:215], v[46:49]
	v_mfma_f32_16x16x32_bf16 v[42:45], v[78:81], v[212:215], v[42:45]
	v_mfma_f32_16x16x32_bf16 v[38:41], v[70:73], v[212:215], v[38:41]
	v_mfma_f32_16x16x32_bf16 v[34:37], v[66:69], v[212:215], v[34:37]

; __device__ __forceinline__ void hyena_item(const Ctx& C, ArgsP a, int ly, int c, bf16_t* yout) {
;     ...
;                 if (d >= -31 && d <= 47) HY_MMA(2)
.LBB0_861:
	v_add_u32_e32 v211, 0x60, v210
	v_cmp_gt_u32_e32 vcc, 64, v211
	s_nop 1
	v_cndmask_b32_e32 v211, 0, v211, vcc
	v_add_u32_e32 v211, s80, v211
	v_mad_u32_u24 v224, v211, s78, v108
	ds_read_b128 v[212:215], v224
	ds_read_b128 v[216:219], v224 offset:64
	ds_read_b128 v[220:223], v224 offset:128
	ds_read_b128 v[224:227], v224 offset:192
	s_cmp_eq_u64 vcc, exec
	s_cbranch_scc1 .Lhy_fast_861
	s_waitcnt lgkmcnt(3)
	v_cndmask_b32_e32 v215, 0, v215, vcc
	v_cndmask_b32_e32 v214, 0, v214, vcc
	v_cndmask_b32_e32 v213, 0, v213, vcc
	v_cndmask_b32_e32 v212, 0, v212, vcc
	s_nop 1
	v_mfma_f32_16x16x32_bf16 v[30:33], v[94:97], v[212:215], v[30:33]
	v_mfma_f32_16x16x32_bf16 v[26:29], v[90:93], v[212:215], v[26:29]
	v_mfma_f32_16x16x32_bf16 v[22:25], v[98:101], v[212:215], v[22:25]
	v_mfma_f32_16x16x32_bf16 v[18:21], v[102:105], v[212:215], v[18:21]
	s_waitcnt lgkmcnt(2)
	v_cndmask_b32_e32 v215, 0, v219, vcc
	v_cndmask_b32_e32 v214, 0, v218, vcc
	v_cndmask_b32_e32 v213, 0, v217, vcc
	v_cndmask_b32_e32 v212, 0, v216, vcc
	s_nop 1
	v_mfma_f32_16x16x32_bf16 v[30:33], v[82:85], v[212:215], v[30:33]
	v_mfma_f32_16x16x32_bf16 v[26:29], v[74:77], v[212:215], v[26:29]
	v_mfma_f32_16x16x32_bf16 v[22:25], v[94:97], v[212:215], v[22:25]
	v_mfma_f32_16x16x32_bf16 v[18:21], v[90:93], v[212:215], v[18:21]
	s_waitcnt lgkmcnt(1)
	v_cndmask_b32_e32 v215, 0, v223, vcc
	v_cndmask_b32_e32 v214, 0, v222, vcc
	v_cndmask_b32_e32 v213, 0, v221, vcc
	v_cndmask_b32_e32 v212, 0, v220, vcc
	s_nop 1
	v_mfma_f32_16x16x32_bf16 v[30:33], v[70:73], v[212:215], v[30:33]
	v_mfma_f32_16x16x32_bf16 v[26:29], v[66:69], v[212:215], v[26:29]
	v_mfma_f32_16x16x32_bf16 v[22:25], v[82:85], v[212:215], v[22:25]
	v_mfma_f32_16x16x32_bf16 v[18:21], v[74:77], v[212:215], v[18:21]
	s_waitcnt lgkmcnt(0)
	v_cndmask_b32_e32 v215, 0, v227, vcc
	v_cndmask_b32_e32 v214, 0, v226, vcc
	v_cndmask_b32_e32 v213, 0, v225, vcc
	v_cndmask_b32_e32 v212, 0, v224, vcc
	s_nop 1
	v_mfma_f32_16x16x32_bf16 v[30:33], v[86:89], v[212:215], v[30:33]
	v_mfma_f32_16x16x32_bf16 v[26:29], v[78:81], v[212:215], v[26:29]
	v_mfma_f32_16x16x32_bf16 v[22:25], v[70:73], v[212:215], v[22:25]
	v_mfma_f32_16x16x32_bf16 v[18:21], v[66:69], v[212:215], v[18:21]

; __device__ __forceinline__ void hyena_item(const Ctx& C, ArgsP a, int ly, int c, bf16_t* yout) {
;     ...
;                 if (d >= -15) HY_MMA(3)
.LBB0_862:
	v_add_u32_e32 v210, 0x70, v210
	v_cmp_gt_u32_e32 vcc, 64, v210
	s_nop 1
	v_cndmask_b32_e32 v210, 0, v210, vcc
	v_add_u32_e32 v210, s80, v210
	v_mad_u32_u24 v222, v210, s78, v108
	ds_read_b128 v[210:213], v222
	ds_read_b128 v[214:217], v222 offset:64
	ds_read_b128 v[218:221], v222 offset:128
	ds_read_b128 v[222:225], v222 offset:192
	s_cmp_eq_u64 vcc, exec
	s_cbranch_scc1 .Lhy_fast_862
	s_waitcnt lgkmcnt(3)
	v_cndmask_b32_e32 v213, 0, v213, vcc
	v_cndmask_b32_e32 v212, 0, v212, vcc
	v_cndmask_b32_e32 v211, 0, v211, vcc
	v_cndmask_b32_e32 v210, 0, v210, vcc
	s_nop 1
	v_mfma_f32_16x16x32_bf16 v[14:17], v[94:97], v[210:213], v[14:17]
	v_mfma_f32_16x16x32_bf16 v[10:13], v[90:93], v[210:213], v[10:13]
	v_mfma_f32_16x16x32_bf16 v[6:9], v[98:101], v[210:213], v[6:9]
	s_waitcnt lgkmcnt(2)
	v_cndmask_b32_e32 v101, 0, v217, vcc
	v_cndmask_b32_e32 v100, 0, v216, vcc
	v_cndmask_b32_e32 v99, 0, v215, vcc
	v_mfma_f32_16x16x32_bf16 v[2:5], v[102:105], v[210:213], v[2:5]
	v_cndmask_b32_e32 v98, 0, v214, vcc
	s_nop 1
	v_mfma_f32_16x16x32_bf16 v[14:17], v[82:85], v[98:101], v[14:17]
	v_mfma_f32_16x16x32_bf16 v[10:13], v[74:77], v[98:101], v[10:13]
	v_mfma_f32_16x16x32_bf16 v[6:9], v[94:97], v[98:101], v[6:9]
	v_mfma_f32_16x16x32_bf16 v[2:5], v[90:93], v[98:101], v[2:5]
	s_waitcnt lgkmcnt(1)
	v_cndmask_b32_e32 v93, 0, v221, vcc
	v_cndmask_b32_e32 v92, 0, v220, vcc
	v_cndmask_b32_e32 v91, 0, v219, vcc
	v_cndmask_b32_e32 v90, 0, v218, vcc
	s_nop 1
	v_mfma_f32_16x16x32_bf16 v[14:17], v[70:73], v[90:93], v[14:17]
	v_mfma_f32_16x16x32_bf16 v[10:13], v[66:69], v[90:93], v[10:13]
	v_mfma_f32_16x16x32_bf16 v[6:9], v[82:85], v[90:93], v[6:9]
	v_mfma_f32_16x16x32_bf16 v[2:5], v[74:77], v[90:93], v[2:5]
	s_waitcnt lgkmcnt(0)
	v_cndmask_b32_e32 v77, 0, v225, vcc
	v_cndmask_b32_e32 v76, 0, v224, vcc
	v_cndmask_b32_e32 v75, 0, v223, vcc
	v_cndmask_b32_e32 v74, 0, v222, vcc
	s_nop 1
	v_mfma_f32_16x16x32_bf16 v[14:17], v[86:89], v[74:77], v[14:17]
	v_mfma_f32_16x16x32_bf16 v[10:13], v[78:81], v[74:77], v[10:13]
	v_mfma_f32_16x16x32_bf16 v[6:9], v[70:73], v[74:77], v[6:9]
	v_mfma_f32_16x16x32_bf16 v[2:5], v[66:69], v[74:77], v[2:5]

.Lhy_fast_859:
	s_waitcnt lgkmcnt(3)
	v_mfma_f32_16x16x32_bf16 v[62:65], v[94:97], v[212:215], v[62:65]
	v_mfma_f32_16x16x32_bf16 v[58:61], v[90:93], v[212:215], v[58:61]
	v_mfma_f32_16x16x32_bf16 v[54:57], v[98:101], v[212:215], v[54:57]
	v_mfma_f32_16x16x32_bf16 v[50:53], v[102:105], v[212:215], v[50:53]
	s_waitcnt lgkmcnt(2)
	v_mfma_f32_16x16x32_bf16 v[62:65], v[82:85], v[216:219], v[62:65]
	v_mfma_f32_16x16x32_bf16 v[58:61], v[74:77], v[216:219], v[58:61]
	v_mfma_f32_16x16x32_bf16 v[54:57], v[94:97], v[216:219], v[54:57]
	v_mfma_f32_16x16x32_bf16 v[50:53], v[90:93], v[216:219], v[50:53]
	s_waitcnt lgkmcnt(1)
	v_mfma_f32_16x16x32_bf16 v[62:65], v[70:73], v[220:223], v[62:65]
	v_mfma_f32_16x16x32_bf16 v[58:61], v[66:69], v[220:223], v[58:61]
	v_mfma_f32_16x16x32_bf16 v[54:57], v[82:85], v[220:223], v[54:57]
	v_mfma_f32_16x16x32_bf16 v[50:53], v[74:77], v[220:223], v[50:53]
	s_waitcnt lgkmcnt(0)
	v_mfma_f32_16x16x32_bf16 v[62:65], v[86:89], v[224:227], v[62:65]
	v_mfma_f32_16x16x32_bf16 v[58:61], v[78:81], v[224:227], v[58:61]
	v_mfma_f32_16x16x32_bf16 v[54:57], v[70:73], v[224:227], v[54:57]
	v_mfma_f32_16x16x32_bf16 v[50:53], v[66:69], v[224:227], v[50:53]
	s_branch .Lhy_join_859
.Lhy_fast_860:
	s_waitcnt lgkmcnt(3)
	v_mfma_f32_16x16x32_bf16 v[46:49], v[94:97], v[212:215], v[46:49]
	v_mfma_f32_16x16x32_bf16 v[42:45], v[90:93], v[212:215], v[42:45]
	v_mfma_f32_16x16x32_bf16 v[38:41], v[98:101], v[212:215], v[38:41]
	v_mfma_f32_16x16x32_bf16 v[34:37], v[102:105], v[212:215], v[34:37]
	s_waitcnt lgkmcnt(2)
	v_mfma_f32_16x16x32_bf16 v[46:49], v[82:85], v[216:219], v[46:49]
	v_mfma_f32_16x16x32_bf16 v[42:45], v[74:77], v[216:219], v[42:45]
	v_mfma_f32_16x16x32_bf16 v[38:41], v[94:97], v[216:219], v[38:41]
	v_mfma_f32_16x16x32_bf16 v[34:37], v[90:93], v[216:219], v[34:37]
	s_waitcnt lgkmcnt(1)
	v_mfma_f32_16x16x32_bf16 v[46:49], v[70:73], v[220:223], v[46:49]
	v_mfma_f32_16x16x32_bf16 v[42:45], v[66:69], v[220:223], v[42:45]
	v_mfma_f32_16x16x32_bf16 v[38:41], v[82:85], v[220:223], v[38:41]
	v_mfma_f32_16x16x32_bf16 v[34:37], v[74:77], v[220:223], v[34:37]
	s_waitcnt lgkmcnt(0)
	v_mfma_f32_16x16x32_bf16 v[46:49], v[86:89], v[224:227], v[46:49]
	v_mfma_f32_16x16x32_bf16 v[42:45], v[78:81], v[224:227], v[42:45]
	v_mfma_f32_16x16x32_bf16 v[38:41], v[70:73], v[224:227], v[38:41]
	v_mfma_f32_16x16x32_bf16 v[34:37], v[66:69], v[224:227], v[34:37]
	s_branch .Lhy_join_860
.Lhy_fast_861:
	s_waitcnt lgkmcnt(3)
	v_mfma_f32_16x16x32_bf16 v[30:33], v[94:97], v[212:215], v[30:33]
	v_mfma_f32_16x16x32_bf16 v[26:29], v[90:93], v[212:215], v[26:29]
	v_mfma_f32_16x16x32_bf16 v[22:25], v[98:101], v[212:215], v[22:25]
	v_mfma_f32_16x16x32_bf16 v[18:21], v[102:105], v[212:215], v[18:21]
	s_waitcnt lgkmcnt(2)
	v_mfma_f32_16x16x32_bf16 v[30:33], v[82:85], v[216:219], v[30:33]
	v_mfma_f32_16x16x32_bf16 v[26:29], v[74:77], v[216:219], v[26:29]
	v_mfma_f32_16x16x32_bf16 v[22:25], v[94:97], v[216:219], v[22:25]
	v_mfma_f32_16x16x32_bf16 v[18:21], v[90:93], v[216:219], v[18:21]
	s_waitcnt lgkmcnt(1)
	v_mfma_f32_16x16x32_bf16 v[30:33], v[70:73], v[220:223], v[30:33]
	v_mfma_f32_16x16x32_bf16 v[26:29], v[66:69], v[220:223], v[26:29]
	v_mfma_f32_16x16x32_bf16 v[22:25], v[82:85], v[220:223], v[22:25]
	v_mfma_f32_16x16x32_bf16 v[18:21], v[74:77], v[220:223], v[18:21]
	s_waitcnt lgkmcnt(0)
	v_mfma_f32_16x16x32_bf16 v[30:33], v[86:89], v[224:227], v[30:33]
	v_mfma_f32_16x16x32_bf16 v[26:29], v[78:81], v[224:227], v[26:29]
	v_mfma_f32_16x16x32_bf16 v[22:25], v[70:73], v[224:227], v[22:25]
	v_mfma_f32_16x16x32_bf16 v[18:21], v[66:69], v[224:227], v[18:21]
	s_branch .Lhy_join_861
.Lhy_fast_862:
	s_waitcnt lgkmcnt(3)
	v_mfma_f32_16x16x32_bf16 v[14:17], v[94:97], v[210:213], v[14:17]
	v_mfma_f32_16x16x32_bf16 v[10:13], v[90:93], v[210:213], v[10:13]
	v_mfma_f32_16x16x32_bf16 v[6:9], v[98:101], v[210:213], v[6:9]
	s_waitcnt lgkmcnt(2)
	v_mfma_f32_16x16x32_bf16 v[2:5], v[102:105], v[210:213], v[2:5]
	v_mfma_f32_16x16x32_bf16 v[14:17], v[82:85], v[214:217], v[14:17]
	v_mfma_f32_16x16x32_bf16 v[10:13], v[74:77], v[214:217], v[10:13]
	v_mfma_f32_16x16x32_bf16 v[6:9], v[94:97], v[214:217], v[6:9]
	v_mfma_f32_16x16x32_bf16 v[2:5], v[90:93], v[214:217], v[2:5]
	s_waitcnt lgkmcnt(1)
	v_mfma_f32_16x16x32_bf16 v[14:17], v[70:73], v[218:221], v[14:17]
	v_mfma_f32_16x16x32_bf16 v[10:13], v[66:69], v[218:221], v[10:13]
	v_mfma_f32_16x16x32_bf16 v[6:9], v[82:85], v[218:221], v[6:9]
	v_mfma_f32_16x16x32_bf16 v[2:5], v[74:77], v[218:221], v[2:5]
	s_waitcnt lgkmcnt(0)
	v_mfma_f32_16x16x32_bf16 v[14:17], v[86:89], v[222:225], v[14:17]
	v_mfma_f32_16x16x32_bf16 v[10:13], v[78:81], v[222:225], v[10:13]
	v_mfma_f32_16x16x32_bf16 v[6:9], v[70:73], v[222:225], v[6:9]
	v_mfma_f32_16x16x32_bf16 v[2:5], v[66:69], v[222:225], v[2:5]
	s_branch .Lhy_join_862

; #define PG8_STAGE(bufoff, gbase, voff) do { _Pragma("unroll") for (int _i = 0; _i < 2; ++_i) \
;         __builtin_amdgcn_global_load_lds((const unsigned*)((const char*)(gbase) + (voff)[_i]), (PG8_LAS unsigned*)(lds + (bufoff) + ldsw + _i * 8192), 16, 0, 0); } while (0)
; #define PG8_LDA(dst, b, h) do { _Pragma("unroll") for (int m = 0; m < 4; ++m) _Pragma("unroll") for (int k = 0; k < 2; ++k) dst[m][k] = *(const PG8_LAS bf16x8*)(lds + PG8_SA(b, h) + aoff + m * 2048 + k * 1024); } while (0)
; #define PG8_LDB(dst, b, h) do { _Pragma("unroll") for (int n = 0; n < 2; ++n) _Pragma("unroll") for (int k = 0; k < 2; ++k) dst[n][k] = *(const PG8_LAS bf16x8*)(lds + PG8_SB(b, h) + boff + n * 2048 + k * 1024); } while (0)
; #define PG8_MMA(ai, bj, At, Bt) do { __builtin_amdgcn_s_setprio(1); _Pragma("unroll") for (int m = 0; m < 4; ++m) _Pragma("unroll") for (int n = 0; n < 2; ++n) _Pragma("unroll") for (int k = 0; k < 2; ++k) \
;         acc[ai][bj][m][n] = __builtin_amdgcn_mfma_f32_16x16x32_bf16(Bt[n][k], At[m][k], acc[ai][bj][m][n], 0, 0, 0); __builtin_amdgcn_s_setprio(0); } while (0)
; #define PG8_WAIT_V(n) asm volatile("s_waitcnt vmcnt(" #n ")" ::: "memory")
; #define PG8_WAIT_L(n) asm volatile("s_waitcnt lgkmcnt(" #n ")" ::: "memory")
; template <class Epi, class Sched, bool ALIGN_EPI = false, bool SP2 = false>
; __device__ __forceinline__ void gemm_phase(PG8_LAS unsigned char* lds, const Gemm g, const Sched& S, const Epi& E) {
;     ...
;             const bool last = (t == nt - 2);
;             const char* a1 = cA + (size_t)(t + 1) * kstep;
;             const char* a2 = last ? nA : cA + (size_t)(t + 2) * kstep; const char* b2 = last ? nB : cB + (size_t)(t + 2) * kstep;
;             const char* a3 = a2 + kstep; const char* b3 = b2 + kstep;
;             if (last && has_next) S.a_ready(nxt);
;             if constexpr (SP2) {
;             PG8_LDB(B0, 0, 0); PG8_LDB(B1, 0, 1); PG8_SCHED; PG8_LDA(At, 0, 0); PG8_STAGE(PG8_SA(1, 1), a1 + hstep, voffA);
;             PG8_WAIT_V(8); PG8_WAIT_L(0); PG8_BAR; PG8_MMA(0, 0, At, B0); PG8_MMA(0, 1, At, B1); PG8_BAR; PG8_SCHED;
;             PG8_LDA(At, 0, 1); PG8_STAGE(PG8_SB(0, 0), b2, voffB); PG8_STAGE(PG8_SB(0, 1), b2 + hstep, voffB); PG8_STAGE(PG8_SA(0, 0), a2, voffA);
;             PG8_WAIT_V(8); PG8_WAIT_L(0); PG8_BAR; PG8_MMA(1, 0, At, B0); PG8_MMA(1, 1, At, B1); PG8_BAR; PG8_SCHED;
.LBB0_1024:
	s_add_i32 s59, s33, 2
	s_add_u32 s6, s40, 0x80
	s_addc_u32 s7, s41, 0
	s_add_i32 s72, 0, 0x10000
	s_cmp_eq_u32 s54, s33
	s_cselect_b32 s43, s13, s7
	s_cselect_b32 s42, s12, s6
	s_cselect_b32 s7, s39, s80
	s_cselect_b32 s6, s38, s79
	s_add_i32 s33, 0, 0x14000
	v_add_u32_e32 v166, s72, v148
	v_add_u32_e32 v178, s33, v148
	ds_read_b128 v[144:147], v166
	ds_read_b128 v[158:161], v166 offset:1024
	ds_read_b128 v[162:165], v166 offset:2048
	ds_read_b128 v[166:169], v166 offset:3072
	ds_read_b128 v[170:173], v178
	ds_read_b128 v[174:177], v178 offset:1024
	ds_read_b128 v[182:185], v178 offset:2048
	ds_read_b128 v[186:189], v178 offset:3072
	s_add_i32 m0, s45, 0xc000
	ds_read_b128 v[190:193], v151
	ds_read_b128 v[194:197], v151 offset:1024
	ds_read_b128 v[198:201], v151 offset:2048
	ds_read_b128 v[202:205], v151 offset:3072
	ds_read_b128 v[206:209], v151 offset:4096
	ds_read_b128 v[210:213], v151 offset:5120
	ds_read_b128 v[214:217], v151 offset:6144
	ds_read_b128 v[218:221], v151 offset:7168
	global_load_lds_dwordx4 v140, s[40:41]
	s_add_i32 m0, s45, 0xe000
	s_nop 0
	global_load_lds_dwordx4 v142, s[40:41]
	s_waitcnt vmcnt(8)
	s_waitcnt lgkmcnt(0)
	s_barrier
	s_waitcnt lgkmcnt(0)
	v_mfma_f32_16x16x32_bf16 v[126:129], v[144:147], v[190:193], v[126:129]
	v_mfma_f32_16x16x32_bf16 v[122:125], v[162:165], v[190:193], v[122:125]
	v_mfma_f32_16x16x32_bf16 v[110:113], v[144:147], v[198:201], v[110:113]
	v_mfma_f32_16x16x32_bf16 v[106:109], v[162:165], v[198:201], v[106:109]
	v_mfma_f32_16x16x32_bf16 v[94:97], v[144:147], v[206:209], v[94:97]
	v_mfma_f32_16x16x32_bf16 v[90:93], v[162:165], v[206:209], v[90:93]
	v_mfma_f32_16x16x32_bf16 v[78:81], v[144:147], v[214:217], v[78:81]
	v_mfma_f32_16x16x32_bf16 v[74:77], v[162:165], v[214:217], v[74:77]
	v_mfma_f32_16x16x32_bf16 v[126:129], v[158:161], v[194:197], v[126:129]
	v_mfma_f32_16x16x32_bf16 v[122:125], v[166:169], v[194:197], v[122:125]
	v_mfma_f32_16x16x32_bf16 v[110:113], v[158:161], v[202:205], v[110:113]
	v_mfma_f32_16x16x32_bf16 v[106:109], v[166:169], v[202:205], v[106:109]
	v_mfma_f32_16x16x32_bf16 v[94:97], v[158:161], v[210:213], v[94:97]
	v_mfma_f32_16x16x32_bf16 v[90:93], v[166:169], v[210:213], v[90:93]
	v_mfma_f32_16x16x32_bf16 v[78:81], v[158:161], v[218:221], v[78:81]
	v_mfma_f32_16x16x32_bf16 v[74:77], v[166:169], v[218:221], v[74:77]
	v_mfma_f32_16x16x32_bf16 v[118:121], v[170:173], v[190:193], v[118:121]
	v_mfma_f32_16x16x32_bf16 v[114:117], v[182:185], v[190:193], v[114:117]
	v_mfma_f32_16x16x32_bf16 v[102:105], v[170:173], v[198:201], v[102:105]
	v_mfma_f32_16x16x32_bf16 v[98:101], v[182:185], v[198:201], v[98:101]
	v_mfma_f32_16x16x32_bf16 v[86:89], v[170:173], v[206:209], v[86:89]
	v_mfma_f32_16x16x32_bf16 v[82:85], v[182:185], v[206:209], v[82:85]
	v_mfma_f32_16x16x32_bf16 v[70:73], v[170:173], v[214:217], v[70:73]
	v_mfma_f32_16x16x32_bf16 v[66:69], v[182:185], v[214:217], v[66:69]
	v_mfma_f32_16x16x32_bf16 v[118:121], v[174:177], v[194:197], v[118:121]
	v_mfma_f32_16x16x32_bf16 v[114:117], v[186:189], v[194:197], v[114:117]
	v_mfma_f32_16x16x32_bf16 v[102:105], v[174:177], v[202:205], v[102:105]
	v_mfma_f32_16x16x32_bf16 v[98:101], v[186:189], v[202:205], v[98:101]
	v_mfma_f32_16x16x32_bf16 v[86:89], v[174:177], v[210:213], v[86:89]
	v_mfma_f32_16x16x32_bf16 v[82:85], v[186:189], v[210:213], v[82:85]
	v_mfma_f32_16x16x32_bf16 v[70:73], v[174:177], v[218:221], v[70:73]
	v_mfma_f32_16x16x32_bf16 v[66:69], v[186:189], v[218:221], v[66:69]
	s_barrier
	s_add_i32 s72, s72, s44
	s_mov_b32 m0, s72
	ds_read_b128 v[190:193], v151 offset:16384
	ds_read_b128 v[194:197], v151 offset:17408
	ds_read_b128 v[198:201], v151 offset:18432
	ds_read_b128 v[202:205], v151 offset:19456
	ds_read_b128 v[206:209], v151 offset:20480
	ds_read_b128 v[210:213], v151 offset:21504
	ds_read_b128 v[214:217], v151 offset:22528
	ds_read_b128 v[218:221], v151 offset:23552
	global_load_lds_dwordx4 v132, s[6:7]
	s_add_i32 m0, s72, 0x2000
	s_add_u32 s100, s6, 0x80
	s_addc_u32 s101, s7, 0
	global_load_lds_dwordx4 v136, s[6:7]
	s_add_u32 s6, s6, s22
	s_addc_u32 s7, s7, s23
	s_add_i32 s33, s33, s44
	s_mov_b32 m0, s33
	s_nop 0
	global_load_lds_dwordx4 v132, s[6:7]
	s_add_i32 m0, s33, 0x2000
	s_nop 0
	global_load_lds_dwordx4 v136, s[6:7]
	s_mov_b32 m0, s45
	s_nop 0
	global_load_lds_dwordx4 v130, s[42:43]
	s_mov_b32 m0, s46
	s_nop 0
	global_load_lds_dwordx4 v134, s[42:43]
	s_waitcnt vmcnt(8)
	s_waitcnt lgkmcnt(0)
	s_barrier
	s_waitcnt lgkmcnt(0)
	v_mfma_f32_16x16x32_bf16 v[62:65], v[144:147], v[190:193], v[62:65]
	v_mfma_f32_16x16x32_bf16 v[58:61], v[162:165], v[190:193], v[58:61]
	v_mfma_f32_16x16x32_bf16 v[46:49], v[144:147], v[198:201], v[46:49]
	v_mfma_f32_16x16x32_bf16 v[42:45], v[162:165], v[198:201], v[42:45]
	v_mfma_f32_16x16x32_bf16 v[30:33], v[144:147], v[206:209], v[30:33]
	v_mfma_f32_16x16x32_bf16 v[26:29], v[162:165], v[206:209], v[26:29]
	v_mfma_f32_16x16x32_bf16 v[14:17], v[144:147], v[214:217], v[14:17]
	v_mfma_f32_16x16x32_bf16 v[10:13], v[162:165], v[214:217], v[10:13]
	v_mfma_f32_16x16x32_bf16 v[62:65], v[158:161], v[194:197], v[62:65]
	v_mfma_f32_16x16x32_bf16 v[58:61], v[166:169], v[194:197], v[58:61]
	v_mfma_f32_16x16x32_bf16 v[46:49], v[158:161], v[202:205], v[46:49]
	v_mfma_f32_16x16x32_bf16 v[42:45], v[166:169], v[202:205], v[42:45]
	v_mfma_f32_16x16x32_bf16 v[30:33], v[158:161], v[210:213], v[30:33]
	v_mfma_f32_16x16x32_bf16 v[26:29], v[166:169], v[210:213], v[26:29]
	v_mfma_f32_16x16x32_bf16 v[14:17], v[158:161], v[218:221], v[14:17]
	v_mfma_f32_16x16x32_bf16 v[10:13], v[166:169], v[218:221], v[10:13]
	v_mfma_f32_16x16x32_bf16 v[54:57], v[170:173], v[190:193], v[54:57]
	v_mfma_f32_16x16x32_bf16 v[50:53], v[182:185], v[190:193], v[50:53]
	v_mfma_f32_16x16x32_bf16 v[38:41], v[170:173], v[198:201], v[38:41]
	v_mfma_f32_16x16x32_bf16 v[34:37], v[182:185], v[198:201], v[34:37]
	v_mfma_f32_16x16x32_bf16 v[22:25], v[170:173], v[206:209], v[22:25]
	v_mfma_f32_16x16x32_bf16 v[18:21], v[182:185], v[206:209], v[18:21]
	v_mfma_f32_16x16x32_bf16 v[6:9], v[170:173], v[214:217], v[6:9]
	v_mfma_f32_16x16x32_bf16 v[2:5], v[182:185], v[214:217], v[2:5]
	v_mfma_f32_16x16x32_bf16 v[54:57], v[174:177], v[194:197], v[54:57]
	v_mfma_f32_16x16x32_bf16 v[50:53], v[186:189], v[194:197], v[50:53]
	v_mfma_f32_16x16x32_bf16 v[38:41], v[174:177], v[202:205], v[38:41]
	v_mfma_f32_16x16x32_bf16 v[34:37], v[186:189], v[202:205], v[34:37]
	v_mfma_f32_16x16x32_bf16 v[22:25], v[174:177], v[210:213], v[22:25]
	v_mfma_f32_16x16x32_bf16 v[18:21], v[186:189], v[210:213], v[18:21]
	v_mfma_f32_16x16x32_bf16 v[6:9], v[174:177], v[218:221], v[6:9]
	v_mfma_f32_16x16x32_bf16 v[2:5], v[186:189], v[218:221], v[2:5]
	s_barrier
; #define PG8_STAGE(bufoff, gbase, voff) do { _Pragma("unroll") for (int _i = 0; _i < 2; ++_i) \
;         __builtin_amdgcn_global_load_lds((const unsigned*)((const char*)(gbase) + (voff)[_i]), (PG8_LAS unsigned*)(lds + (bufoff) + ldsw + _i * 8192), 16, 0, 0); } while (0)
; #define PG8_LDA(dst, b, h) do { _Pragma("unroll") for (int m = 0; m < 4; ++m) _Pragma("unroll") for (int k = 0; k < 2; ++k) dst[m][k] = *(const PG8_LAS bf16x8*)(lds + PG8_SA(b, h) + aoff + m * 2048 + k * 1024); } while (0)
; #define PG8_LDB(dst, b, h) do { _Pragma("unroll") for (int n = 0; n < 2; ++n) _Pragma("unroll") for (int k = 0; k < 2; ++k) dst[n][k] = *(const PG8_LAS bf16x8*)(lds + PG8_SB(b, h) + boff + n * 2048 + k * 1024); } while (0)
; #define PG8_MMA(ai, bj, At, Bt) do { __builtin_amdgcn_s_setprio(1); _Pragma("unroll") for (int m = 0; m < 4; ++m) _Pragma("unroll") for (int n = 0; n < 2; ++n) _Pragma("unroll") for (int k = 0; k < 2; ++k) \
;         acc[ai][bj][m][n] = __builtin_amdgcn_mfma_f32_16x16x32_bf16(Bt[n][k], At[m][k], acc[ai][bj][m][n], 0, 0, 0); __builtin_amdgcn_s_setprio(0); } while (0)
; #define PG8_WAIT_V(n) asm volatile("s_waitcnt vmcnt(" #n ")" ::: "memory")
; #define PG8_WAIT_L(n) asm volatile("s_waitcnt lgkmcnt(" #n ")" ::: "memory")
; #define PG8_BAR __builtin_amdgcn_s_barrier()
; #define PG8_SCHED __builtin_amdgcn_sched_barrier(0)
; template <class Epi, class Sched, bool ALIGN_EPI = false, bool SP2 = false>
; __device__ __forceinline__ void gemm_phase(PG8_LAS unsigned char* lds, const Gemm g, const Sched& S, const Epi& E) {
;     ...
;             PG8_LDB(B0, 1, 0); PG8_LDB(B1, 1, 1); PG8_SCHED; PG8_LDA(At, 1, 0); PG8_STAGE(PG8_SA(0, 1), a2 + hstep, voffA);
;             PG8_WAIT_V(8); PG8_WAIT_L(0); PG8_BAR; PG8_MMA(0, 0, At, B0); PG8_MMA(0, 1, At, B1); PG8_BAR; PG8_SCHED;
;             PG8_LDA(At, 1, 1); PG8_STAGE(PG8_SB(1, 0), b3, voffB); PG8_STAGE(PG8_SB(1, 1), b3 + hstep, voffB); PG8_STAGE(PG8_SA(1, 0), a3, voffA);
;             PG8_WAIT_V(8); PG8_WAIT_L(0); PG8_BAR; PG8_MMA(1, 0, At, B0); PG8_MMA(1, 1, At, B1); PG8_BAR; PG8_SCHED;
	s_add_i32 s33, 0, 0x18000
	s_add_i32 s72, 0, 0x1c000
	v_add_u32_e32 v166, s33, v148
	v_add_u32_e32 v181, s72, v148
	ds_read_b128 v[144:147], v166
	ds_read_b128 v[158:161], v166 offset:1024
	ds_read_b128 v[162:165], v166 offset:2048
	ds_read_b128 v[166:169], v166 offset:3072
	ds_read_b128 v[170:173], v181
	ds_read_b128 v[174:177], v181 offset:1024
	ds_read_b128 v[182:185], v181 offset:2048
	ds_read_b128 v[186:189], v181 offset:3072
	s_add_u32 s6, s42, s22
	s_addc_u32 s7, s43, s23
	s_mov_b32 m0, s47
	ds_read_b128 v[190:193], v151 offset:32768
	ds_read_b128 v[194:197], v151 offset:33792
	ds_read_b128 v[198:201], v151 offset:34816
	ds_read_b128 v[202:205], v151 offset:35840
	ds_read_b128 v[206:209], v151 offset:36864
	ds_read_b128 v[210:213], v151 offset:37888
	ds_read_b128 v[214:217], v151 offset:38912
	ds_read_b128 v[218:221], v151 offset:39936
	global_load_lds_dwordx4 v130, s[6:7]
	s_mov_b32 m0, s48
	s_nop 0
	global_load_lds_dwordx4 v134, s[6:7]
	s_waitcnt vmcnt(8)
	s_waitcnt lgkmcnt(0)
	s_barrier
	s_waitcnt lgkmcnt(0)
	v_mfma_f32_16x16x32_bf16 v[126:129], v[144:147], v[190:193], v[126:129]
	v_mfma_f32_16x16x32_bf16 v[122:125], v[162:165], v[190:193], v[122:125]
	v_mfma_f32_16x16x32_bf16 v[110:113], v[144:147], v[198:201], v[110:113]
	v_mfma_f32_16x16x32_bf16 v[106:109], v[162:165], v[198:201], v[106:109]
	v_mfma_f32_16x16x32_bf16 v[94:97], v[144:147], v[206:209], v[94:97]
	v_mfma_f32_16x16x32_bf16 v[90:93], v[162:165], v[206:209], v[90:93]
	v_mfma_f32_16x16x32_bf16 v[78:81], v[144:147], v[214:217], v[78:81]
	v_mfma_f32_16x16x32_bf16 v[74:77], v[162:165], v[214:217], v[74:77]
	v_mfma_f32_16x16x32_bf16 v[126:129], v[158:161], v[194:197], v[126:129]
	v_mfma_f32_16x16x32_bf16 v[122:125], v[166:169], v[194:197], v[122:125]
	v_mfma_f32_16x16x32_bf16 v[110:113], v[158:161], v[202:205], v[110:113]
	v_mfma_f32_16x16x32_bf16 v[106:109], v[166:169], v[202:205], v[106:109]
	v_mfma_f32_16x16x32_bf16 v[94:97], v[158:161], v[210:213], v[94:97]
	v_mfma_f32_16x16x32_bf16 v[90:93], v[166:169], v[210:213], v[90:93]
	v_mfma_f32_16x16x32_bf16 v[78:81], v[158:161], v[218:221], v[78:81]
	v_mfma_f32_16x16x32_bf16 v[74:77], v[166:169], v[218:221], v[74:77]
	v_mfma_f32_16x16x32_bf16 v[118:121], v[170:173], v[190:193], v[118:121]
	v_mfma_f32_16x16x32_bf16 v[114:117], v[182:185], v[190:193], v[114:117]
	v_mfma_f32_16x16x32_bf16 v[102:105], v[170:173], v[198:201], v[102:105]
	v_mfma_f32_16x16x32_bf16 v[98:101], v[182:185], v[198:201], v[98:101]
	v_mfma_f32_16x16x32_bf16 v[86:89], v[170:173], v[206:209], v[86:89]
	v_mfma_f32_16x16x32_bf16 v[82:85], v[182:185], v[206:209], v[82:85]
	v_mfma_f32_16x16x32_bf16 v[70:73], v[170:173], v[214:217], v[70:73]
	v_mfma_f32_16x16x32_bf16 v[66:69], v[182:185], v[214:217], v[66:69]
	v_mfma_f32_16x16x32_bf16 v[118:121], v[174:177], v[194:197], v[118:121]
	v_mfma_f32_16x16x32_bf16 v[114:117], v[186:189], v[194:197], v[114:117]
	v_mfma_f32_16x16x32_bf16 v[102:105], v[174:177], v[202:205], v[102:105]
	v_mfma_f32_16x16x32_bf16 v[98:101], v[186:189], v[202:205], v[98:101]
	v_mfma_f32_16x16x32_bf16 v[86:89], v[174:177], v[210:213], v[86:89]
	v_mfma_f32_16x16x32_bf16 v[82:85], v[186:189], v[210:213], v[82:85]
	v_mfma_f32_16x16x32_bf16 v[70:73], v[174:177], v[218:221], v[70:73]
	v_mfma_f32_16x16x32_bf16 v[66:69], v[186:189], v[218:221], v[66:69]
	s_barrier
	s_add_i32 s6, s33, s44
	s_mov_b32 m0, s6
	ds_read_b128 v[190:193], v151 offset:49152
	ds_read_b128 v[194:197], v151 offset:50176
	ds_read_b128 v[198:201], v151 offset:51200
	ds_read_b128 v[202:205], v151 offset:52224
	ds_read_b128 v[206:209], v151 offset:53248
	ds_read_b128 v[210:213], v151 offset:54272
	ds_read_b128 v[214:217], v151 offset:55296
	ds_read_b128 v[218:221], v151 offset:56320
	global_load_lds_dwordx4 v132, s[100:101]
	s_add_i32 m0, s6, 0x2000
	s_add_i32 s6, s72, s44
	global_load_lds_dwordx4 v136, s[100:101]
	s_add_u32 s100, s100, s22
	s_addc_u32 s101, s101, s23
	s_mov_b32 m0, s6
	s_nop 0
	global_load_lds_dwordx4 v132, s[100:101]
	s_add_i32 m0, s6, 0x2000
	s_nop 0
	global_load_lds_dwordx4 v136, s[100:101]
	s_add_u32 s100, s42, 0x80
	s_addc_u32 s101, s43, 0
	s_mov_b32 m0, s50
	s_nop 0
	global_load_lds_dwordx4 v130, s[100:101]
	s_mov_b32 m0, s51
	s_nop 0
	global_load_lds_dwordx4 v134, s[100:101]
	s_waitcnt vmcnt(8)
	s_waitcnt lgkmcnt(0)
	s_barrier
	s_waitcnt lgkmcnt(0)
	v_mfma_f32_16x16x32_bf16 v[62:65], v[144:147], v[190:193], v[62:65]
	v_mfma_f32_16x16x32_bf16 v[58:61], v[162:165], v[190:193], v[58:61]
	v_mfma_f32_16x16x32_bf16 v[46:49], v[144:147], v[198:201], v[46:49]
	v_mfma_f32_16x16x32_bf16 v[42:45], v[162:165], v[198:201], v[42:45]
	v_mfma_f32_16x16x32_bf16 v[30:33], v[144:147], v[206:209], v[30:33]
	v_mfma_f32_16x16x32_bf16 v[26:29], v[162:165], v[206:209], v[26:29]
	v_mfma_f32_16x16x32_bf16 v[14:17], v[144:147], v[214:217], v[14:17]
	v_mfma_f32_16x16x32_bf16 v[10:13], v[162:165], v[214:217], v[10:13]
	v_mfma_f32_16x16x32_bf16 v[62:65], v[158:161], v[194:197], v[62:65]
	v_mfma_f32_16x16x32_bf16 v[58:61], v[166:169], v[194:197], v[58:61]
	v_mfma_f32_16x16x32_bf16 v[46:49], v[158:161], v[202:205], v[46:49]
	v_mfma_f32_16x16x32_bf16 v[42:45], v[166:169], v[202:205], v[42:45]
	v_mfma_f32_16x16x32_bf16 v[30:33], v[158:161], v[210:213], v[30:33]
	v_mfma_f32_16x16x32_bf16 v[26:29], v[166:169], v[210:213], v[26:29]
	v_mfma_f32_16x16x32_bf16 v[14:17], v[158:161], v[218:221], v[14:17]
	v_mfma_f32_16x16x32_bf16 v[10:13], v[166:169], v[218:221], v[10:13]
	v_mfma_f32_16x16x32_bf16 v[54:57], v[170:173], v[190:193], v[54:57]
	v_mfma_f32_16x16x32_bf16 v[50:53], v[182:185], v[190:193], v[50:53]
	v_mfma_f32_16x16x32_bf16 v[38:41], v[170:173], v[198:201], v[38:41]
	v_mfma_f32_16x16x32_bf16 v[34:37], v[182:185], v[198:201], v[34:37]
	v_mfma_f32_16x16x32_bf16 v[22:25], v[170:173], v[206:209], v[22:25]
	v_mfma_f32_16x16x32_bf16 v[18:21], v[182:185], v[206:209], v[18:21]
	v_mfma_f32_16x16x32_bf16 v[6:9], v[170:173], v[214:217], v[6:9]
	v_mfma_f32_16x16x32_bf16 v[2:5], v[182:185], v[214:217], v[2:5]
	v_mfma_f32_16x16x32_bf16 v[54:57], v[174:177], v[194:197], v[54:57]
	v_mfma_f32_16x16x32_bf16 v[50:53], v[186:189], v[194:197], v[50:53]
	v_mfma_f32_16x16x32_bf16 v[38:41], v[174:177], v[202:205], v[38:41]
	v_mfma_f32_16x16x32_bf16 v[34:37], v[186:189], v[202:205], v[34:37]
	v_mfma_f32_16x16x32_bf16 v[22:25], v[174:177], v[210:213], v[22:25]
	v_mfma_f32_16x16x32_bf16 v[18:21], v[186:189], v[210:213], v[18:21]
	v_mfma_f32_16x16x32_bf16 v[6:9], v[174:177], v[218:221], v[6:9]
	v_mfma_f32_16x16x32_bf16 v[2:5], v[186:189], v[218:221], v[2:5]
	s_barrier
	s_add_u32 s40, s40, 0x100
	s_addc_u32 s41, s41, 0
	s_add_u32 s79, s79, 0x100
	s_addc_u32 s80, s80, 0
	s_cmp_ge_i32 s59, s49
	s_mov_b32 s33, s59
	s_cbranch_scc0 .LBB0_1024

; #define PG8_STAGE(bufoff, gbase, voff) do { _Pragma("unroll") for (int _i = 0; _i < 2; ++_i) \
;         __builtin_amdgcn_global_load_lds((const unsigned*)((const char*)(gbase) + (voff)[_i]), (PG8_LAS unsigned*)(lds + (bufoff) + ldsw + _i * 8192), 16, 0, 0); } while (0)
; #define PG8_LDA(dst, b, h) do { _Pragma("unroll") for (int m = 0; m < 4; ++m) _Pragma("unroll") for (int k = 0; k < 2; ++k) dst[m][k] = *(const PG8_LAS bf16x8*)(lds + PG8_SA(b, h) + aoff + m * 2048 + k * 1024); } while (0)
; #define PG8_LDB(dst, b, h) do { _Pragma("unroll") for (int n = 0; n < 2; ++n) _Pragma("unroll") for (int k = 0; k < 2; ++k) dst[n][k] = *(const PG8_LAS bf16x8*)(lds + PG8_SB(b, h) + boff + n * 2048 + k * 1024); } while (0)
; #define PG8_MMA(ai, bj, At, Bt) do { __builtin_amdgcn_s_setprio(1); _Pragma("unroll") for (int m = 0; m < 4; ++m) _Pragma("unroll") for (int n = 0; n < 2; ++n) _Pragma("unroll") for (int k = 0; k < 2; ++k) \
;         acc[ai][bj][m][n] = __builtin_amdgcn_mfma_f32_16x16x32_bf16(Bt[n][k], At[m][k], acc[ai][bj][m][n], 0, 0, 0); __builtin_amdgcn_s_setprio(0); } while (0)
; #define PG8_WAIT_V(n) asm volatile("s_waitcnt vmcnt(" #n ")" ::: "memory")
; #define PG8_WAIT_L(n) asm volatile("s_waitcnt lgkmcnt(" #n ")" ::: "memory")
; template <class Epi, class Sched, bool ALIGN_EPI = false, bool SP2 = false>
; __device__ __forceinline__ void gemm_phase(PG8_LAS unsigned char* lds, const Gemm g, const Sched& S, const Epi& E) {
;     ...
;             const bool last = (t == nt - 2);
;             const char* a1 = cA + (size_t)(t + 1) * kstep;
;             const char* a2 = last ? nA : cA + (size_t)(t + 2) * kstep; const char* b2 = last ? nB : cB + (size_t)(t + 2) * kstep;
;             const char* a3 = a2 + kstep; const char* b3 = b2 + kstep;
;             if (last && has_next) S.a_ready(nxt);
;             if constexpr (SP2) {
;             PG8_LDB(B0, 0, 0); PG8_LDB(B1, 0, 1); PG8_SCHED; PG8_LDA(At, 0, 0); PG8_STAGE(PG8_SA(1, 1), a1 + hstep, voffA);
;             PG8_WAIT_V(8); PG8_WAIT_L(0); PG8_BAR; PG8_MMA(0, 0, At, B0); PG8_MMA(0, 1, At, B1); PG8_BAR; PG8_SCHED;
;             PG8_LDA(At, 0, 1); PG8_STAGE(PG8_SB(0, 0), b2, voffB); PG8_STAGE(PG8_SB(0, 1), b2 + hstep, voffB); PG8_STAGE(PG8_SA(0, 0), a2, voffA);
;             PG8_WAIT_V(8); PG8_WAIT_L(0); PG8_BAR; PG8_MMA(1, 0, At, B0); PG8_MMA(1, 1, At, B1); PG8_BAR; PG8_SCHED;
.LBB0_1130:
	s_add_i32 s59, s33, 2
	s_add_u32 s6, s34, 0x80
	s_addc_u32 s7, s35, 0
	s_add_i32 s72, 0, 0x10000
	s_cmp_eq_u32 s65, s33
	s_cselect_b32 s37, s11, s7
	s_cselect_b32 s36, s10, s6
	v_add_u32_e32 v148, s72, v150
	s_cselect_b32 s7, s31, s54
	s_cselect_b32 s6, s30, s2
	s_add_i32 s33, 0, 0x14000
	ds_read_b128 v[144:147], v148
	ds_read_b128 v[160:163], v148 offset:1024
	ds_read_b128 v[164:167], v148 offset:2048
	ds_read_b128 v[168:171], v148 offset:3072
	v_add_u32_e32 v148, s33, v150
	ds_read_b128 v[172:175], v148
	ds_read_b128 v[176:179], v148 offset:1024
	ds_read_b128 v[182:185], v148 offset:2048
	ds_read_b128 v[186:189], v148 offset:3072
	s_add_i32 m0, s49, 0xc000
	ds_read_b128 v[190:193], v158
	ds_read_b128 v[194:197], v158 offset:1024
	ds_read_b128 v[198:201], v158 offset:2048
	ds_read_b128 v[202:205], v158 offset:3072
	ds_read_b128 v[206:209], v158 offset:4096
	ds_read_b128 v[210:213], v158 offset:5120
	ds_read_b128 v[214:217], v158 offset:6144
	ds_read_b128 v[218:221], v158 offset:7168
	global_load_lds_dwordx4 v140, s[34:35]
	s_add_i32 m0, s49, 0xe000
	s_nop 0
	global_load_lds_dwordx4 v142, s[34:35]
	s_waitcnt vmcnt(8)
	s_waitcnt lgkmcnt(0)
	s_barrier
	s_waitcnt lgkmcnt(0)
	v_mfma_f32_16x16x32_bf16 v[122:125], v[144:147], v[190:193], v[122:125]
	v_mfma_f32_16x16x32_bf16 v[126:129], v[164:167], v[190:193], v[126:129]
	v_mfma_f32_16x16x32_bf16 v[110:113], v[144:147], v[198:201], v[110:113]
	v_mfma_f32_16x16x32_bf16 v[106:109], v[164:167], v[198:201], v[106:109]
	v_mfma_f32_16x16x32_bf16 v[94:97], v[144:147], v[206:209], v[94:97]
	v_mfma_f32_16x16x32_bf16 v[90:93], v[164:167], v[206:209], v[90:93]
	v_mfma_f32_16x16x32_bf16 v[78:81], v[144:147], v[214:217], v[78:81]
	v_mfma_f32_16x16x32_bf16 v[74:77], v[164:167], v[214:217], v[74:77]
	v_mfma_f32_16x16x32_bf16 v[122:125], v[160:163], v[194:197], v[122:125]
	v_mfma_f32_16x16x32_bf16 v[126:129], v[168:171], v[194:197], v[126:129]
	v_mfma_f32_16x16x32_bf16 v[110:113], v[160:163], v[202:205], v[110:113]
	v_mfma_f32_16x16x32_bf16 v[106:109], v[168:171], v[202:205], v[106:109]
	v_mfma_f32_16x16x32_bf16 v[94:97], v[160:163], v[210:213], v[94:97]
	v_mfma_f32_16x16x32_bf16 v[90:93], v[168:171], v[210:213], v[90:93]
	v_mfma_f32_16x16x32_bf16 v[78:81], v[160:163], v[218:221], v[78:81]
	v_mfma_f32_16x16x32_bf16 v[74:77], v[168:171], v[218:221], v[74:77]
	v_mfma_f32_16x16x32_bf16 v[118:121], v[172:175], v[190:193], v[118:121]
	v_mfma_f32_16x16x32_bf16 v[114:117], v[182:185], v[190:193], v[114:117]
	v_mfma_f32_16x16x32_bf16 v[102:105], v[172:175], v[198:201], v[102:105]
	v_mfma_f32_16x16x32_bf16 v[98:101], v[182:185], v[198:201], v[98:101]
	v_mfma_f32_16x16x32_bf16 v[86:89], v[172:175], v[206:209], v[86:89]
	v_mfma_f32_16x16x32_bf16 v[82:85], v[182:185], v[206:209], v[82:85]
	v_mfma_f32_16x16x32_bf16 v[70:73], v[172:175], v[214:217], v[70:73]
	v_mfma_f32_16x16x32_bf16 v[66:69], v[182:185], v[214:217], v[66:69]
	v_mfma_f32_16x16x32_bf16 v[118:121], v[176:179], v[194:197], v[118:121]
	v_mfma_f32_16x16x32_bf16 v[114:117], v[186:189], v[194:197], v[114:117]
	v_mfma_f32_16x16x32_bf16 v[102:105], v[176:179], v[202:205], v[102:105]
	v_mfma_f32_16x16x32_bf16 v[98:101], v[186:189], v[202:205], v[98:101]
	v_mfma_f32_16x16x32_bf16 v[86:89], v[176:179], v[210:213], v[86:89]
	v_mfma_f32_16x16x32_bf16 v[82:85], v[186:189], v[210:213], v[82:85]
	v_mfma_f32_16x16x32_bf16 v[70:73], v[176:179], v[218:221], v[70:73]
	v_mfma_f32_16x16x32_bf16 v[66:69], v[186:189], v[218:221], v[66:69]
	s_barrier
	s_add_i32 s72, s72, s43
	s_mov_b32 m0, s72
	ds_read_b128 v[190:193], v158 offset:16384
	ds_read_b128 v[194:197], v158 offset:17408
	ds_read_b128 v[198:201], v158 offset:18432
	ds_read_b128 v[202:205], v158 offset:19456
	ds_read_b128 v[206:209], v158 offset:20480
	ds_read_b128 v[210:213], v158 offset:21504
	ds_read_b128 v[214:217], v158 offset:22528
	ds_read_b128 v[218:221], v158 offset:23552
	global_load_lds_dwordx4 v134, s[6:7]
	s_add_i32 m0, s72, 0x2000
	s_add_u32 s100, s6, 0x80
	s_addc_u32 s101, s7, 0
	global_load_lds_dwordx4 v130, s[6:7]
	s_add_u32 s6, s6, s16
	s_addc_u32 s7, s7, s17
	s_add_i32 s33, s33, s43
	s_mov_b32 m0, s33
	s_nop 0
	global_load_lds_dwordx4 v134, s[6:7]
	s_add_i32 m0, s33, 0x2000
	s_nop 0
	global_load_lds_dwordx4 v130, s[6:7]
	s_mov_b32 m0, s49
	s_nop 0
	global_load_lds_dwordx4 v136, s[36:37]
	s_mov_b32 m0, s50
	s_nop 0
	global_load_lds_dwordx4 v132, s[36:37]
	s_waitcnt vmcnt(8)
	s_waitcnt lgkmcnt(0)
	s_barrier
	s_waitcnt lgkmcnt(0)
	v_mfma_f32_16x16x32_bf16 v[62:65], v[144:147], v[190:193], v[62:65]
	v_mfma_f32_16x16x32_bf16 v[58:61], v[164:167], v[190:193], v[58:61]
	v_mfma_f32_16x16x32_bf16 v[46:49], v[144:147], v[198:201], v[46:49]
	v_mfma_f32_16x16x32_bf16 v[42:45], v[164:167], v[198:201], v[42:45]
	v_mfma_f32_16x16x32_bf16 v[30:33], v[144:147], v[206:209], v[30:33]
	v_mfma_f32_16x16x32_bf16 v[26:29], v[164:167], v[206:209], v[26:29]
	v_mfma_f32_16x16x32_bf16 v[14:17], v[144:147], v[214:217], v[14:17]
	v_mfma_f32_16x16x32_bf16 v[10:13], v[164:167], v[214:217], v[10:13]
	v_mfma_f32_16x16x32_bf16 v[62:65], v[160:163], v[194:197], v[62:65]
	v_mfma_f32_16x16x32_bf16 v[58:61], v[168:171], v[194:197], v[58:61]
	v_mfma_f32_16x16x32_bf16 v[46:49], v[160:163], v[202:205], v[46:49]
	v_mfma_f32_16x16x32_bf16 v[42:45], v[168:171], v[202:205], v[42:45]
	v_mfma_f32_16x16x32_bf16 v[30:33], v[160:163], v[210:213], v[30:33]
	v_mfma_f32_16x16x32_bf16 v[26:29], v[168:171], v[210:213], v[26:29]
	v_mfma_f32_16x16x32_bf16 v[14:17], v[160:163], v[218:221], v[14:17]
	v_mfma_f32_16x16x32_bf16 v[10:13], v[168:171], v[218:221], v[10:13]
	v_mfma_f32_16x16x32_bf16 v[54:57], v[172:175], v[190:193], v[54:57]
	v_mfma_f32_16x16x32_bf16 v[50:53], v[182:185], v[190:193], v[50:53]
	v_mfma_f32_16x16x32_bf16 v[38:41], v[172:175], v[198:201], v[38:41]
	v_mfma_f32_16x16x32_bf16 v[34:37], v[182:185], v[198:201], v[34:37]
	v_mfma_f32_16x16x32_bf16 v[22:25], v[172:175], v[206:209], v[22:25]
	v_mfma_f32_16x16x32_bf16 v[18:21], v[182:185], v[206:209], v[18:21]
	v_mfma_f32_16x16x32_bf16 v[6:9], v[172:175], v[214:217], v[6:9]
	v_mfma_f32_16x16x32_bf16 v[2:5], v[182:185], v[214:217], v[2:5]
	v_mfma_f32_16x16x32_bf16 v[54:57], v[176:179], v[194:197], v[54:57]
	v_mfma_f32_16x16x32_bf16 v[50:53], v[186:189], v[194:197], v[50:53]
	v_mfma_f32_16x16x32_bf16 v[38:41], v[176:179], v[202:205], v[38:41]
	v_mfma_f32_16x16x32_bf16 v[34:37], v[186:189], v[202:205], v[34:37]
	v_mfma_f32_16x16x32_bf16 v[22:25], v[176:179], v[210:213], v[22:25]
	v_mfma_f32_16x16x32_bf16 v[18:21], v[186:189], v[210:213], v[18:21]
	v_mfma_f32_16x16x32_bf16 v[6:9], v[176:179], v[218:221], v[6:9]
	v_mfma_f32_16x16x32_bf16 v[2:5], v[186:189], v[218:221], v[2:5]
	s_barrier
; #define PG8_STAGE(bufoff, gbase, voff) do { _Pragma("unroll") for (int _i = 0; _i < 2; ++_i) \
;         __builtin_amdgcn_global_load_lds((const unsigned*)((const char*)(gbase) + (voff)[_i]), (PG8_LAS unsigned*)(lds + (bufoff) + ldsw + _i * 8192), 16, 0, 0); } while (0)
; #define PG8_LDA(dst, b, h) do { _Pragma("unroll") for (int m = 0; m < 4; ++m) _Pragma("unroll") for (int k = 0; k < 2; ++k) dst[m][k] = *(const PG8_LAS bf16x8*)(lds + PG8_SA(b, h) + aoff + m * 2048 + k * 1024); } while (0)
; #define PG8_LDB(dst, b, h) do { _Pragma("unroll") for (int n = 0; n < 2; ++n) _Pragma("unroll") for (int k = 0; k < 2; ++k) dst[n][k] = *(const PG8_LAS bf16x8*)(lds + PG8_SB(b, h) + boff + n * 2048 + k * 1024); } while (0)
; #define PG8_MMA(ai, bj, At, Bt) do { __builtin_amdgcn_s_setprio(1); _Pragma("unroll") for (int m = 0; m < 4; ++m) _Pragma("unroll") for (int n = 0; n < 2; ++n) _Pragma("unroll") for (int k = 0; k < 2; ++k) \
;         acc[ai][bj][m][n] = __builtin_amdgcn_mfma_f32_16x16x32_bf16(Bt[n][k], At[m][k], acc[ai][bj][m][n], 0, 0, 0); __builtin_amdgcn_s_setprio(0); } while (0)
; #define PG8_WAIT_V(n) asm volatile("s_waitcnt vmcnt(" #n ")" ::: "memory")
; #define PG8_WAIT_L(n) asm volatile("s_waitcnt lgkmcnt(" #n ")" ::: "memory")
; #define PG8_BAR __builtin_amdgcn_s_barrier()
; #define PG8_SCHED __builtin_amdgcn_sched_barrier(0)
; template <class Epi, class Sched, bool ALIGN_EPI = false, bool SP2 = false>
; __device__ __forceinline__ void gemm_phase(PG8_LAS unsigned char* lds, const Gemm g, const Sched& S, const Epi& E) {
;     ...
;             PG8_LDB(B0, 1, 0); PG8_LDB(B1, 1, 1); PG8_SCHED; PG8_LDA(At, 1, 0); PG8_STAGE(PG8_SA(0, 1), a2 + hstep, voffA);
;             PG8_WAIT_V(8); PG8_WAIT_L(0); PG8_BAR; PG8_MMA(0, 0, At, B0); PG8_MMA(0, 1, At, B1); PG8_BAR; PG8_SCHED;
;             PG8_LDA(At, 1, 1); PG8_STAGE(PG8_SB(1, 0), b3, voffB); PG8_STAGE(PG8_SB(1, 1), b3 + hstep, voffB); PG8_STAGE(PG8_SA(1, 0), a3, voffA);
;             PG8_WAIT_V(8); PG8_WAIT_L(0); PG8_BAR; PG8_MMA(1, 0, At, B0); PG8_MMA(1, 1, At, B1); PG8_BAR; PG8_SCHED;
	s_add_i32 s33, 0, 0x18000
	v_add_u32_e32 v159, s33, v150
	s_add_i32 s72, 0, 0x1c000
	ds_read_b128 v[144:147], v159
	ds_read_b128 v[160:163], v159 offset:1024
	ds_read_b128 v[164:167], v159 offset:2048
	ds_read_b128 v[168:171], v159 offset:3072
	v_add_u32_e32 v159, s72, v150
	ds_read_b128 v[172:175], v159
	ds_read_b128 v[176:179], v159 offset:1024
	ds_read_b128 v[182:185], v159 offset:2048
	ds_read_b128 v[186:189], v159 offset:3072
	s_add_u32 s6, s36, s16
	s_addc_u32 s7, s37, s17
	s_mov_b32 m0, s51
	ds_read_b128 v[190:193], v158 offset:32768
	ds_read_b128 v[194:197], v158 offset:33792
	ds_read_b128 v[198:201], v158 offset:34816
	ds_read_b128 v[202:205], v158 offset:35840
	ds_read_b128 v[206:209], v158 offset:36864
	ds_read_b128 v[210:213], v158 offset:37888
	ds_read_b128 v[214:217], v158 offset:38912
	ds_read_b128 v[218:221], v158 offset:39936
	global_load_lds_dwordx4 v136, s[6:7]
	s_mov_b32 m0, s56
	s_nop 0
	global_load_lds_dwordx4 v132, s[6:7]
	s_waitcnt vmcnt(8)
	s_waitcnt lgkmcnt(0)
	s_barrier
	s_waitcnt lgkmcnt(0)
	v_mfma_f32_16x16x32_bf16 v[122:125], v[144:147], v[190:193], v[122:125]
	v_mfma_f32_16x16x32_bf16 v[126:129], v[164:167], v[190:193], v[126:129]
	v_mfma_f32_16x16x32_bf16 v[110:113], v[144:147], v[198:201], v[110:113]
	v_mfma_f32_16x16x32_bf16 v[106:109], v[164:167], v[198:201], v[106:109]
	v_mfma_f32_16x16x32_bf16 v[94:97], v[144:147], v[206:209], v[94:97]
	v_mfma_f32_16x16x32_bf16 v[90:93], v[164:167], v[206:209], v[90:93]
	v_mfma_f32_16x16x32_bf16 v[78:81], v[144:147], v[214:217], v[78:81]
	v_mfma_f32_16x16x32_bf16 v[74:77], v[164:167], v[214:217], v[74:77]
	v_mfma_f32_16x16x32_bf16 v[122:125], v[160:163], v[194:197], v[122:125]
	v_mfma_f32_16x16x32_bf16 v[126:129], v[168:171], v[194:197], v[126:129]
	v_mfma_f32_16x16x32_bf16 v[110:113], v[160:163], v[202:205], v[110:113]
	v_mfma_f32_16x16x32_bf16 v[106:109], v[168:171], v[202:205], v[106:109]
	v_mfma_f32_16x16x32_bf16 v[94:97], v[160:163], v[210:213], v[94:97]
	v_mfma_f32_16x16x32_bf16 v[90:93], v[168:171], v[210:213], v[90:93]
	v_mfma_f32_16x16x32_bf16 v[78:81], v[160:163], v[218:221], v[78:81]
	v_mfma_f32_16x16x32_bf16 v[74:77], v[168:171], v[218:221], v[74:77]
	v_mfma_f32_16x16x32_bf16 v[118:121], v[172:175], v[190:193], v[118:121]
	v_mfma_f32_16x16x32_bf16 v[114:117], v[182:185], v[190:193], v[114:117]
	v_mfma_f32_16x16x32_bf16 v[102:105], v[172:175], v[198:201], v[102:105]
	v_mfma_f32_16x16x32_bf16 v[98:101], v[182:185], v[198:201], v[98:101]
	v_mfma_f32_16x16x32_bf16 v[86:89], v[172:175], v[206:209], v[86:89]
	v_mfma_f32_16x16x32_bf16 v[82:85], v[182:185], v[206:209], v[82:85]
	v_mfma_f32_16x16x32_bf16 v[70:73], v[172:175], v[214:217], v[70:73]
	v_mfma_f32_16x16x32_bf16 v[66:69], v[182:185], v[214:217], v[66:69]
	v_mfma_f32_16x16x32_bf16 v[118:121], v[176:179], v[194:197], v[118:121]
	v_mfma_f32_16x16x32_bf16 v[114:117], v[186:189], v[194:197], v[114:117]
	v_mfma_f32_16x16x32_bf16 v[102:105], v[176:179], v[202:205], v[102:105]
	v_mfma_f32_16x16x32_bf16 v[98:101], v[186:189], v[202:205], v[98:101]
	v_mfma_f32_16x16x32_bf16 v[86:89], v[176:179], v[210:213], v[86:89]
	v_mfma_f32_16x16x32_bf16 v[82:85], v[186:189], v[210:213], v[82:85]
	v_mfma_f32_16x16x32_bf16 v[70:73], v[176:179], v[218:221], v[70:73]
	v_mfma_f32_16x16x32_bf16 v[66:69], v[186:189], v[218:221], v[66:69]
	s_barrier
	s_add_i32 s6, s33, s43
	s_mov_b32 m0, s6
	ds_read_b128 v[190:193], v158 offset:49152
	ds_read_b128 v[194:197], v158 offset:50176
	ds_read_b128 v[198:201], v158 offset:51200
	ds_read_b128 v[202:205], v158 offset:52224
	ds_read_b128 v[206:209], v158 offset:53248
	ds_read_b128 v[210:213], v158 offset:54272
	ds_read_b128 v[214:217], v158 offset:55296
	ds_read_b128 v[218:221], v158 offset:56320
	global_load_lds_dwordx4 v134, s[100:101]
	s_add_i32 m0, s6, 0x2000
	s_add_i32 s6, s72, s43
	global_load_lds_dwordx4 v130, s[100:101]
	s_add_u32 s100, s100, s16
	s_addc_u32 s101, s101, s17
	s_mov_b32 m0, s6
	s_nop 0
	global_load_lds_dwordx4 v134, s[100:101]
	s_add_i32 m0, s6, 0x2000
	s_nop 0
	global_load_lds_dwordx4 v130, s[100:101]
	s_add_u32 s100, s36, 0x80
	s_addc_u32 s101, s37, 0
	s_mov_b32 m0, s60
	s_nop 0
	global_load_lds_dwordx4 v136, s[100:101]
	s_mov_b32 m0, s64
	s_nop 0
	global_load_lds_dwordx4 v132, s[100:101]
	s_waitcnt vmcnt(8)
	s_waitcnt lgkmcnt(0)
	s_barrier
	s_waitcnt lgkmcnt(0)
	v_mfma_f32_16x16x32_bf16 v[62:65], v[144:147], v[190:193], v[62:65]
	v_mfma_f32_16x16x32_bf16 v[58:61], v[164:167], v[190:193], v[58:61]
	v_mfma_f32_16x16x32_bf16 v[46:49], v[144:147], v[198:201], v[46:49]
	v_mfma_f32_16x16x32_bf16 v[42:45], v[164:167], v[198:201], v[42:45]
	v_mfma_f32_16x16x32_bf16 v[30:33], v[144:147], v[206:209], v[30:33]
	v_mfma_f32_16x16x32_bf16 v[26:29], v[164:167], v[206:209], v[26:29]
	v_mfma_f32_16x16x32_bf16 v[14:17], v[144:147], v[214:217], v[14:17]
	v_mfma_f32_16x16x32_bf16 v[10:13], v[164:167], v[214:217], v[10:13]
	v_mfma_f32_16x16x32_bf16 v[62:65], v[160:163], v[194:197], v[62:65]
	v_mfma_f32_16x16x32_bf16 v[58:61], v[168:171], v[194:197], v[58:61]
	v_mfma_f32_16x16x32_bf16 v[46:49], v[160:163], v[202:205], v[46:49]
	v_mfma_f32_16x16x32_bf16 v[42:45], v[168:171], v[202:205], v[42:45]
	v_mfma_f32_16x16x32_bf16 v[30:33], v[160:163], v[210:213], v[30:33]
	v_mfma_f32_16x16x32_bf16 v[26:29], v[168:171], v[210:213], v[26:29]
	v_mfma_f32_16x16x32_bf16 v[14:17], v[160:163], v[218:221], v[14:17]
	v_mfma_f32_16x16x32_bf16 v[10:13], v[168:171], v[218:221], v[10:13]
	v_mfma_f32_16x16x32_bf16 v[54:57], v[172:175], v[190:193], v[54:57]
	v_mfma_f32_16x16x32_bf16 v[50:53], v[182:185], v[190:193], v[50:53]
	v_mfma_f32_16x16x32_bf16 v[38:41], v[172:175], v[198:201], v[38:41]
	v_mfma_f32_16x16x32_bf16 v[34:37], v[182:185], v[198:201], v[34:37]
	v_mfma_f32_16x16x32_bf16 v[22:25], v[172:175], v[206:209], v[22:25]
	v_mfma_f32_16x16x32_bf16 v[18:21], v[182:185], v[206:209], v[18:21]
	v_mfma_f32_16x16x32_bf16 v[6:9], v[172:175], v[214:217], v[6:9]
	v_mfma_f32_16x16x32_bf16 v[2:5], v[182:185], v[214:217], v[2:5]
	v_mfma_f32_16x16x32_bf16 v[54:57], v[176:179], v[194:197], v[54:57]
	v_mfma_f32_16x16x32_bf16 v[50:53], v[186:189], v[194:197], v[50:53]
	v_mfma_f32_16x16x32_bf16 v[38:41], v[176:179], v[202:205], v[38:41]
	v_mfma_f32_16x16x32_bf16 v[34:37], v[186:189], v[202:205], v[34:37]
	v_mfma_f32_16x16x32_bf16 v[22:25], v[176:179], v[210:213], v[22:25]
	v_mfma_f32_16x16x32_bf16 v[18:21], v[186:189], v[210:213], v[18:21]
	v_mfma_f32_16x16x32_bf16 v[6:9], v[176:179], v[218:221], v[6:9]
	v_mfma_f32_16x16x32_bf16 v[2:5], v[186:189], v[218:221], v[2:5]
	s_barrier
	s_add_u32 s34, s34, 0x100
	s_addc_u32 s35, s35, 0
	s_add_u32 s2, s2, 0x100
	s_addc_u32 s54, s54, 0
	s_cmp_ge_i32 s59, s57
	s_mov_b32 s33, s59
	s_cbranch_scc0 .LBB0_1130

; #define PG8_STAGE(bufoff, gbase, voff) do { _Pragma("unroll") for (int _i = 0; _i < 2; ++_i) \
;         __builtin_amdgcn_global_load_lds((const unsigned*)((const char*)(gbase) + (voff)[_i]), (PG8_LAS unsigned*)(lds + (bufoff) + ldsw + _i * 8192), 16, 0, 0); } while (0)
; #define PG8_LDA(dst, b, h) do { _Pragma("unroll") for (int m = 0; m < 4; ++m) _Pragma("unroll") for (int k = 0; k < 2; ++k) dst[m][k] = *(const PG8_LAS bf16x8*)(lds + PG8_SA(b, h) + aoff + m * 2048 + k * 1024); } while (0)
; #define PG8_LDB(dst, b, h) do { _Pragma("unroll") for (int n = 0; n < 2; ++n) _Pragma("unroll") for (int k = 0; k < 2; ++k) dst[n][k] = *(const PG8_LAS bf16x8*)(lds + PG8_SB(b, h) + boff + n * 2048 + k * 1024); } while (0)
; #define PG8_MMA(ai, bj, At, Bt) do { __builtin_amdgcn_s_setprio(1); _Pragma("unroll") for (int m = 0; m < 4; ++m) _Pragma("unroll") for (int n = 0; n < 2; ++n) _Pragma("unroll") for (int k = 0; k < 2; ++k) \
;         acc[ai][bj][m][n] = __builtin_amdgcn_mfma_f32_16x16x32_bf16(Bt[n][k], At[m][k], acc[ai][bj][m][n], 0, 0, 0); __builtin_amdgcn_s_setprio(0); } while (0)
; #define PG8_WAIT_V(n) asm volatile("s_waitcnt vmcnt(" #n ")" ::: "memory")
; #define PG8_WAIT_L(n) asm volatile("s_waitcnt lgkmcnt(" #n ")" ::: "memory")
; #define PG8_BAR __builtin_amdgcn_s_barrier()
; #define PG8_SCHED __builtin_amdgcn_sched_barrier(0)
; template <class Epi, class Sched, bool ALIGN_EPI = false, bool SP2 = false>
; __device__ __forceinline__ void gemm_phase(PG8_LAS unsigned char* lds, const Gemm g, const Sched& S, const Epi& E) {
;     ...
;             PG8_LDB(B0, 0, 0); PG8_LDB(B1, 0, 1); PG8_SCHED; PG8_LDA(At, 0, 0); PG8_STAGE(PG8_SA(1, 1), a1 + hstep, voffA);
;             PG8_WAIT_V(8); PG8_WAIT_L(0); PG8_BAR; PG8_MMA(0, 0, At, B0); PG8_MMA(0, 1, At, B1); PG8_BAR; PG8_SCHED;
;             PG8_LDA(At, 0, 1); PG8_STAGE(PG8_SB(0, 0), b2, voffB); PG8_STAGE(PG8_SB(0, 1), b2 + hstep, voffB); PG8_STAGE(PG8_SA(0, 0), a2, voffA);
;             PG8_WAIT_V(8); PG8_WAIT_L(0); PG8_BAR; PG8_MMA(1, 0, At, B0); PG8_MMA(1, 1, At, B1); PG8_BAR; PG8_SCHED;
.LBB0_1222:
	s_add_i32 s59, s33, 2
	s_add_u32 s6, s38, 0x80
	s_addc_u32 s7, s39, 0
	s_add_i32 s72, 0, 0x10000
	s_cmp_eq_u32 s54, s33
	s_cselect_b32 s41, s13, s7
	s_cselect_b32 s40, s12, s6
	s_cselect_b32 s7, s37, s81
	s_cselect_b32 s6, s36, s80
	s_add_i32 s33, 0, 0x14000
	v_add_u32_e32 v166, s72, v148
	v_add_u32_e32 v178, s33, v148
	ds_read_b128 v[144:147], v166
	ds_read_b128 v[158:161], v166 offset:1024
	ds_read_b128 v[162:165], v166 offset:2048
	ds_read_b128 v[166:169], v166 offset:3072
	ds_read_b128 v[170:173], v178
	ds_read_b128 v[174:177], v178 offset:1024
	ds_read_b128 v[182:185], v178 offset:2048
	ds_read_b128 v[186:189], v178 offset:3072
	s_add_i32 m0, s45, 0xc000
	ds_read_b128 v[190:193], v151
	ds_read_b128 v[194:197], v151 offset:1024
	ds_read_b128 v[198:201], v151 offset:2048
	ds_read_b128 v[202:205], v151 offset:3072
	ds_read_b128 v[206:209], v151 offset:4096
	ds_read_b128 v[210:213], v151 offset:5120
	ds_read_b128 v[214:217], v151 offset:6144
	ds_read_b128 v[218:221], v151 offset:7168
	global_load_lds_dwordx4 v140, s[38:39]
	s_add_i32 m0, s45, 0xe000
	s_nop 0
	global_load_lds_dwordx4 v142, s[38:39]
	s_waitcnt vmcnt(8)
	s_waitcnt lgkmcnt(0)
	s_barrier
	s_waitcnt lgkmcnt(0)
	v_mfma_f32_16x16x32_bf16 v[126:129], v[144:147], v[190:193], v[126:129]
	v_mfma_f32_16x16x32_bf16 v[122:125], v[162:165], v[190:193], v[122:125]
	v_mfma_f32_16x16x32_bf16 v[110:113], v[144:147], v[198:201], v[110:113]
	v_mfma_f32_16x16x32_bf16 v[106:109], v[162:165], v[198:201], v[106:109]
	v_mfma_f32_16x16x32_bf16 v[94:97], v[144:147], v[206:209], v[94:97]
	v_mfma_f32_16x16x32_bf16 v[90:93], v[162:165], v[206:209], v[90:93]
	v_mfma_f32_16x16x32_bf16 v[78:81], v[144:147], v[214:217], v[78:81]
	v_mfma_f32_16x16x32_bf16 v[74:77], v[162:165], v[214:217], v[74:77]
	v_mfma_f32_16x16x32_bf16 v[126:129], v[158:161], v[194:197], v[126:129]
	v_mfma_f32_16x16x32_bf16 v[122:125], v[166:169], v[194:197], v[122:125]
	v_mfma_f32_16x16x32_bf16 v[110:113], v[158:161], v[202:205], v[110:113]
	v_mfma_f32_16x16x32_bf16 v[106:109], v[166:169], v[202:205], v[106:109]
	v_mfma_f32_16x16x32_bf16 v[94:97], v[158:161], v[210:213], v[94:97]
	v_mfma_f32_16x16x32_bf16 v[90:93], v[166:169], v[210:213], v[90:93]
	v_mfma_f32_16x16x32_bf16 v[78:81], v[158:161], v[218:221], v[78:81]
	v_mfma_f32_16x16x32_bf16 v[74:77], v[166:169], v[218:221], v[74:77]
	v_mfma_f32_16x16x32_bf16 v[118:121], v[170:173], v[190:193], v[118:121]
	v_mfma_f32_16x16x32_bf16 v[114:117], v[182:185], v[190:193], v[114:117]
	v_mfma_f32_16x16x32_bf16 v[102:105], v[170:173], v[198:201], v[102:105]
	v_mfma_f32_16x16x32_bf16 v[98:101], v[182:185], v[198:201], v[98:101]
	v_mfma_f32_16x16x32_bf16 v[86:89], v[170:173], v[206:209], v[86:89]
	v_mfma_f32_16x16x32_bf16 v[82:85], v[182:185], v[206:209], v[82:85]
	v_mfma_f32_16x16x32_bf16 v[70:73], v[170:173], v[214:217], v[70:73]
	v_mfma_f32_16x16x32_bf16 v[66:69], v[182:185], v[214:217], v[66:69]
	v_mfma_f32_16x16x32_bf16 v[118:121], v[174:177], v[194:197], v[118:121]
	v_mfma_f32_16x16x32_bf16 v[114:117], v[186:189], v[194:197], v[114:117]
	v_mfma_f32_16x16x32_bf16 v[102:105], v[174:177], v[202:205], v[102:105]
	v_mfma_f32_16x16x32_bf16 v[98:101], v[186:189], v[202:205], v[98:101]
	v_mfma_f32_16x16x32_bf16 v[86:89], v[174:177], v[210:213], v[86:89]
	v_mfma_f32_16x16x32_bf16 v[82:85], v[186:189], v[210:213], v[82:85]
	v_mfma_f32_16x16x32_bf16 v[70:73], v[174:177], v[218:221], v[70:73]
	v_mfma_f32_16x16x32_bf16 v[66:69], v[186:189], v[218:221], v[66:69]
	s_barrier
	s_add_i32 s72, s72, s44
	s_mov_b32 m0, s72
	ds_read_b128 v[190:193], v151 offset:16384
	ds_read_b128 v[194:197], v151 offset:17408
	ds_read_b128 v[198:201], v151 offset:18432
	ds_read_b128 v[202:205], v151 offset:19456
	ds_read_b128 v[206:209], v151 offset:20480
	ds_read_b128 v[210:213], v151 offset:21504
	ds_read_b128 v[214:217], v151 offset:22528
	ds_read_b128 v[218:221], v151 offset:23552
	global_load_lds_dwordx4 v132, s[6:7]
	s_add_i32 m0, s72, 0x2000
	s_add_u32 s100, s6, 0x80
	s_addc_u32 s101, s7, 0
	global_load_lds_dwordx4 v136, s[6:7]
	s_add_u32 s6, s6, s20
	s_addc_u32 s7, s7, s21
	s_add_i32 s33, s33, s44
	s_mov_b32 m0, s33
	s_nop 0
	global_load_lds_dwordx4 v132, s[6:7]
	s_add_i32 m0, s33, 0x2000
	s_nop 0
	global_load_lds_dwordx4 v136, s[6:7]
	s_mov_b32 m0, s45
	s_nop 0
	global_load_lds_dwordx4 v130, s[40:41]
	s_mov_b32 m0, s46
	s_nop 0
	global_load_lds_dwordx4 v134, s[40:41]
	s_waitcnt vmcnt(8)
	s_waitcnt lgkmcnt(0)
	s_barrier
	s_waitcnt lgkmcnt(0)
	v_mfma_f32_16x16x32_bf16 v[62:65], v[144:147], v[190:193], v[62:65]
	v_mfma_f32_16x16x32_bf16 v[58:61], v[162:165], v[190:193], v[58:61]
	v_mfma_f32_16x16x32_bf16 v[46:49], v[144:147], v[198:201], v[46:49]
	v_mfma_f32_16x16x32_bf16 v[42:45], v[162:165], v[198:201], v[42:45]
	v_mfma_f32_16x16x32_bf16 v[30:33], v[144:147], v[206:209], v[30:33]
	v_mfma_f32_16x16x32_bf16 v[26:29], v[162:165], v[206:209], v[26:29]
	v_mfma_f32_16x16x32_bf16 v[14:17], v[144:147], v[214:217], v[14:17]
	v_mfma_f32_16x16x32_bf16 v[10:13], v[162:165], v[214:217], v[10:13]
	v_mfma_f32_16x16x32_bf16 v[62:65], v[158:161], v[194:197], v[62:65]
	v_mfma_f32_16x16x32_bf16 v[58:61], v[166:169], v[194:197], v[58:61]
	v_mfma_f32_16x16x32_bf16 v[46:49], v[158:161], v[202:205], v[46:49]
	v_mfma_f32_16x16x32_bf16 v[42:45], v[166:169], v[202:205], v[42:45]
	v_mfma_f32_16x16x32_bf16 v[30:33], v[158:161], v[210:213], v[30:33]
	v_mfma_f32_16x16x32_bf16 v[26:29], v[166:169], v[210:213], v[26:29]
	v_mfma_f32_16x16x32_bf16 v[14:17], v[158:161], v[218:221], v[14:17]
	v_mfma_f32_16x16x32_bf16 v[10:13], v[166:169], v[218:221], v[10:13]
	v_mfma_f32_16x16x32_bf16 v[54:57], v[170:173], v[190:193], v[54:57]
	v_mfma_f32_16x16x32_bf16 v[50:53], v[182:185], v[190:193], v[50:53]
	v_mfma_f32_16x16x32_bf16 v[38:41], v[170:173], v[198:201], v[38:41]
	v_mfma_f32_16x16x32_bf16 v[34:37], v[182:185], v[198:201], v[34:37]
	v_mfma_f32_16x16x32_bf16 v[22:25], v[170:173], v[206:209], v[22:25]
	v_mfma_f32_16x16x32_bf16 v[18:21], v[182:185], v[206:209], v[18:21]
	v_mfma_f32_16x16x32_bf16 v[6:9], v[170:173], v[214:217], v[6:9]
	v_mfma_f32_16x16x32_bf16 v[2:5], v[182:185], v[214:217], v[2:5]
	v_mfma_f32_16x16x32_bf16 v[54:57], v[174:177], v[194:197], v[54:57]
	v_mfma_f32_16x16x32_bf16 v[50:53], v[186:189], v[194:197], v[50:53]
	v_mfma_f32_16x16x32_bf16 v[38:41], v[174:177], v[202:205], v[38:41]
	v_mfma_f32_16x16x32_bf16 v[34:37], v[186:189], v[202:205], v[34:37]
	v_mfma_f32_16x16x32_bf16 v[22:25], v[174:177], v[210:213], v[22:25]
	v_mfma_f32_16x16x32_bf16 v[18:21], v[186:189], v[210:213], v[18:21]
	v_mfma_f32_16x16x32_bf16 v[6:9], v[174:177], v[218:221], v[6:9]
	v_mfma_f32_16x16x32_bf16 v[2:5], v[186:189], v[218:221], v[2:5]
	s_barrier
; #define PG8_STAGE(bufoff, gbase, voff) do { _Pragma("unroll") for (int _i = 0; _i < 2; ++_i) \
;         __builtin_amdgcn_global_load_lds((const unsigned*)((const char*)(gbase) + (voff)[_i]), (PG8_LAS unsigned*)(lds + (bufoff) + ldsw + _i * 8192), 16, 0, 0); } while (0)
; #define PG8_LDA(dst, b, h) do { _Pragma("unroll") for (int m = 0; m < 4; ++m) _Pragma("unroll") for (int k = 0; k < 2; ++k) dst[m][k] = *(const PG8_LAS bf16x8*)(lds + PG8_SA(b, h) + aoff + m * 2048 + k * 1024); } while (0)
; #define PG8_LDB(dst, b, h) do { _Pragma("unroll") for (int n = 0; n < 2; ++n) _Pragma("unroll") for (int k = 0; k < 2; ++k) dst[n][k] = *(const PG8_LAS bf16x8*)(lds + PG8_SB(b, h) + boff + n * 2048 + k * 1024); } while (0)
; #define PG8_MMA(ai, bj, At, Bt) do { __builtin_amdgcn_s_setprio(1); _Pragma("unroll") for (int m = 0; m < 4; ++m) _Pragma("unroll") for (int n = 0; n < 2; ++n) _Pragma("unroll") for (int k = 0; k < 2; ++k) \
;         acc[ai][bj][m][n] = __builtin_amdgcn_mfma_f32_16x16x32_bf16(Bt[n][k], At[m][k], acc[ai][bj][m][n], 0, 0, 0); __builtin_amdgcn_s_setprio(0); } while (0)
; #define PG8_WAIT_V(n) asm volatile("s_waitcnt vmcnt(" #n ")" ::: "memory")
; #define PG8_WAIT_L(n) asm volatile("s_waitcnt lgkmcnt(" #n ")" ::: "memory")
; #define PG8_BAR __builtin_amdgcn_s_barrier()
; #define PG8_SCHED __builtin_amdgcn_sched_barrier(0)
; template <class Epi, class Sched, bool ALIGN_EPI = false, bool SP2 = false>
; __device__ __forceinline__ void gemm_phase(PG8_LAS unsigned char* lds, const Gemm g, const Sched& S, const Epi& E) {
;     ...
;         for (int t = 0; t < nt; t += 2) {
;             const bool last = (t == nt - 2);
;             const char* a1 = cA + (size_t)(t + 1) * kstep;
;             const char* a2 = last ? nA : cA + (size_t)(t + 2) * kstep; const char* b2 = last ? nB : cB + (size_t)(t + 2) * kstep;
;     ...
;             PG8_LDB(B0, 1, 0); PG8_LDB(B1, 1, 1); PG8_SCHED; PG8_LDA(At, 1, 0); PG8_STAGE(PG8_SA(0, 1), a2 + hstep, voffA);
;             PG8_WAIT_V(8); PG8_WAIT_L(0); PG8_BAR; PG8_MMA(0, 0, At, B0); PG8_MMA(0, 1, At, B1); PG8_BAR; PG8_SCHED;
;             PG8_LDA(At, 1, 1); PG8_STAGE(PG8_SB(1, 0), b3, voffB); PG8_STAGE(PG8_SB(1, 1), b3 + hstep, voffB); PG8_STAGE(PG8_SA(1, 0), a3, voffA);
;             PG8_WAIT_V(8); PG8_WAIT_L(0); PG8_BAR; PG8_MMA(1, 0, At, B0); PG8_MMA(1, 1, At, B1); PG8_BAR; PG8_SCHED;
	s_add_i32 s33, 0, 0x18000
	s_add_i32 s72, 0, 0x1c000
	v_add_u32_e32 v166, s33, v148
	v_add_u32_e32 v181, s72, v148
	ds_read_b128 v[144:147], v166
	ds_read_b128 v[158:161], v166 offset:1024
	ds_read_b128 v[162:165], v166 offset:2048
	ds_read_b128 v[166:169], v166 offset:3072
	ds_read_b128 v[170:173], v181
	ds_read_b128 v[174:177], v181 offset:1024
	ds_read_b128 v[182:185], v181 offset:2048
	ds_read_b128 v[186:189], v181 offset:3072
	s_add_u32 s6, s40, s20
	s_addc_u32 s7, s41, s21
	s_mov_b32 m0, s47
	ds_read_b128 v[190:193], v151 offset:32768
	ds_read_b128 v[194:197], v151 offset:33792
	ds_read_b128 v[198:201], v151 offset:34816
	ds_read_b128 v[202:205], v151 offset:35840
	ds_read_b128 v[206:209], v151 offset:36864
	ds_read_b128 v[210:213], v151 offset:37888
	ds_read_b128 v[214:217], v151 offset:38912
	ds_read_b128 v[218:221], v151 offset:39936
	global_load_lds_dwordx4 v130, s[6:7]
	s_mov_b32 m0, s48
	s_nop 0
	global_load_lds_dwordx4 v134, s[6:7]
	s_waitcnt vmcnt(8)
	s_waitcnt lgkmcnt(0)
	s_barrier
	s_waitcnt lgkmcnt(0)
	v_mfma_f32_16x16x32_bf16 v[126:129], v[144:147], v[190:193], v[126:129]
	v_mfma_f32_16x16x32_bf16 v[122:125], v[162:165], v[190:193], v[122:125]
	v_mfma_f32_16x16x32_bf16 v[110:113], v[144:147], v[198:201], v[110:113]
	v_mfma_f32_16x16x32_bf16 v[106:109], v[162:165], v[198:201], v[106:109]
	v_mfma_f32_16x16x32_bf16 v[94:97], v[144:147], v[206:209], v[94:97]
	v_mfma_f32_16x16x32_bf16 v[90:93], v[162:165], v[206:209], v[90:93]
	v_mfma_f32_16x16x32_bf16 v[78:81], v[144:147], v[214:217], v[78:81]
	v_mfma_f32_16x16x32_bf16 v[74:77], v[162:165], v[214:217], v[74:77]
	v_mfma_f32_16x16x32_bf16 v[126:129], v[158:161], v[194:197], v[126:129]
	v_mfma_f32_16x16x32_bf16 v[122:125], v[166:169], v[194:197], v[122:125]
	v_mfma_f32_16x16x32_bf16 v[110:113], v[158:161], v[202:205], v[110:113]
	v_mfma_f32_16x16x32_bf16 v[106:109], v[166:169], v[202:205], v[106:109]
	v_mfma_f32_16x16x32_bf16 v[94:97], v[158:161], v[210:213], v[94:97]
	v_mfma_f32_16x16x32_bf16 v[90:93], v[166:169], v[210:213], v[90:93]
	v_mfma_f32_16x16x32_bf16 v[78:81], v[158:161], v[218:221], v[78:81]
	v_mfma_f32_16x16x32_bf16 v[74:77], v[166:169], v[218:221], v[74:77]
	v_mfma_f32_16x16x32_bf16 v[118:121], v[170:173], v[190:193], v[118:121]
	v_mfma_f32_16x16x32_bf16 v[114:117], v[182:185], v[190:193], v[114:117]
	v_mfma_f32_16x16x32_bf16 v[102:105], v[170:173], v[198:201], v[102:105]
	v_mfma_f32_16x16x32_bf16 v[98:101], v[182:185], v[198:201], v[98:101]
	v_mfma_f32_16x16x32_bf16 v[86:89], v[170:173], v[206:209], v[86:89]
	v_mfma_f32_16x16x32_bf16 v[82:85], v[182:185], v[206:209], v[82:85]
	v_mfma_f32_16x16x32_bf16 v[70:73], v[170:173], v[214:217], v[70:73]
	v_mfma_f32_16x16x32_bf16 v[66:69], v[182:185], v[214:217], v[66:69]
	v_mfma_f32_16x16x32_bf16 v[118:121], v[174:177], v[194:197], v[118:121]
	v_mfma_f32_16x16x32_bf16 v[114:117], v[186:189], v[194:197], v[114:117]
	v_mfma_f32_16x16x32_bf16 v[102:105], v[174:177], v[202:205], v[102:105]
	v_mfma_f32_16x16x32_bf16 v[98:101], v[186:189], v[202:205], v[98:101]
	v_mfma_f32_16x16x32_bf16 v[86:89], v[174:177], v[210:213], v[86:89]
	v_mfma_f32_16x16x32_bf16 v[82:85], v[186:189], v[210:213], v[82:85]
	v_mfma_f32_16x16x32_bf16 v[70:73], v[174:177], v[218:221], v[70:73]
	v_mfma_f32_16x16x32_bf16 v[66:69], v[186:189], v[218:221], v[66:69]
	s_barrier
	s_add_i32 s6, s33, s44
	s_mov_b32 m0, s6
	ds_read_b128 v[190:193], v151 offset:49152
	ds_read_b128 v[194:197], v151 offset:50176
	ds_read_b128 v[198:201], v151 offset:51200
	ds_read_b128 v[202:205], v151 offset:52224
	ds_read_b128 v[206:209], v151 offset:53248
	ds_read_b128 v[210:213], v151 offset:54272
	ds_read_b128 v[214:217], v151 offset:55296
	ds_read_b128 v[218:221], v151 offset:56320
	global_load_lds_dwordx4 v132, s[100:101]
	s_add_i32 m0, s6, 0x2000
	s_add_i32 s6, s72, s44
	global_load_lds_dwordx4 v136, s[100:101]
	s_add_u32 s100, s100, s20
	s_addc_u32 s101, s101, s21
	s_mov_b32 m0, s6
	s_nop 0
	global_load_lds_dwordx4 v132, s[100:101]
	s_add_i32 m0, s6, 0x2000
	s_nop 0
	global_load_lds_dwordx4 v136, s[100:101]
	s_add_u32 s100, s40, 0x80
	s_addc_u32 s101, s41, 0
	s_mov_b32 m0, s50
	s_nop 0
	global_load_lds_dwordx4 v130, s[100:101]
	s_mov_b32 m0, s51
	s_nop 0
	global_load_lds_dwordx4 v134, s[100:101]
	s_waitcnt vmcnt(8)
	s_waitcnt lgkmcnt(0)
	s_barrier
	s_waitcnt lgkmcnt(0)
	v_mfma_f32_16x16x32_bf16 v[62:65], v[144:147], v[190:193], v[62:65]
	v_mfma_f32_16x16x32_bf16 v[58:61], v[162:165], v[190:193], v[58:61]
	v_mfma_f32_16x16x32_bf16 v[46:49], v[144:147], v[198:201], v[46:49]
	v_mfma_f32_16x16x32_bf16 v[42:45], v[162:165], v[198:201], v[42:45]
	v_mfma_f32_16x16x32_bf16 v[30:33], v[144:147], v[206:209], v[30:33]
	v_mfma_f32_16x16x32_bf16 v[26:29], v[162:165], v[206:209], v[26:29]
	v_mfma_f32_16x16x32_bf16 v[14:17], v[144:147], v[214:217], v[14:17]
	v_mfma_f32_16x16x32_bf16 v[10:13], v[162:165], v[214:217], v[10:13]
	v_mfma_f32_16x16x32_bf16 v[62:65], v[158:161], v[194:197], v[62:65]
	v_mfma_f32_16x16x32_bf16 v[58:61], v[166:169], v[194:197], v[58:61]
	v_mfma_f32_16x16x32_bf16 v[46:49], v[158:161], v[202:205], v[46:49]
	v_mfma_f32_16x16x32_bf16 v[42:45], v[166:169], v[202:205], v[42:45]
	v_mfma_f32_16x16x32_bf16 v[30:33], v[158:161], v[210:213], v[30:33]
	v_mfma_f32_16x16x32_bf16 v[26:29], v[166:169], v[210:213], v[26:29]
	v_mfma_f32_16x16x32_bf16 v[14:17], v[158:161], v[218:221], v[14:17]
	v_mfma_f32_16x16x32_bf16 v[10:13], v[166:169], v[218:221], v[10:13]
	v_mfma_f32_16x16x32_bf16 v[54:57], v[170:173], v[190:193], v[54:57]
	v_mfma_f32_16x16x32_bf16 v[50:53], v[182:185], v[190:193], v[50:53]
	v_mfma_f32_16x16x32_bf16 v[38:41], v[170:173], v[198:201], v[38:41]
	v_mfma_f32_16x16x32_bf16 v[34:37], v[182:185], v[198:201], v[34:37]
	v_mfma_f32_16x16x32_bf16 v[22:25], v[170:173], v[206:209], v[22:25]
	v_mfma_f32_16x16x32_bf16 v[18:21], v[182:185], v[206:209], v[18:21]
	v_mfma_f32_16x16x32_bf16 v[6:9], v[170:173], v[214:217], v[6:9]
	v_mfma_f32_16x16x32_bf16 v[2:5], v[182:185], v[214:217], v[2:5]
	v_mfma_f32_16x16x32_bf16 v[54:57], v[174:177], v[194:197], v[54:57]
	v_mfma_f32_16x16x32_bf16 v[50:53], v[186:189], v[194:197], v[50:53]
	v_mfma_f32_16x16x32_bf16 v[38:41], v[174:177], v[202:205], v[38:41]
	v_mfma_f32_16x16x32_bf16 v[34:37], v[186:189], v[202:205], v[34:37]
	v_mfma_f32_16x16x32_bf16 v[22:25], v[174:177], v[210:213], v[22:25]
	v_mfma_f32_16x16x32_bf16 v[18:21], v[186:189], v[210:213], v[18:21]
	v_mfma_f32_16x16x32_bf16 v[6:9], v[174:177], v[218:221], v[6:9]
	v_mfma_f32_16x16x32_bf16 v[2:5], v[186:189], v[218:221], v[2:5]
	s_barrier
	s_add_u32 s38, s38, 0x100
	s_addc_u32 s39, s39, 0
	s_add_u32 s80, s80, 0x100
	s_addc_u32 s81, s81, 0
	s_cmp_ge_i32 s59, s49
	s_mov_b32 s33, s59
	s_cbranch_scc0 .LBB0_1222
